# on top of best: accumulator zeroing removed; first-iteration MFMAs take C = 0
# baseline (speedup 1.0000x reference)
; #define PG8_STAGE(bufoff, gbase, voff) do { _Pragma("unroll") for (int _i = 0; _i < 2; ++_i) \
;         __builtin_amdgcn_global_load_lds((const unsigned*)((const char*)(gbase) + (voff)[_i]), (PG8_LAS unsigned*)(lds + (bufoff) + ldsw + _i * 8192), 16, 0, 0); } while (0)
; #define PG8_BAR __builtin_amdgcn_s_barrier()
; template <class Epi, class Sched, bool ALIGN_EPI = false, bool SP2 = false>
; __device__ __forceinline__ void gemm_phase(PG8_LAS unsigned char* lds, const Gemm g, const Sched& S, const Epi& E) {
;     int tid_ = threadIdx.x; asm volatile("" : "+v"(tid_));
;     const int tid = tid_, wid = __builtin_amdgcn_readfirstlane(tid >> 6), lane = tid & 63, wr = wid >> 2, wc = wid & 3, fr = lane & 15, fq = lane >> 4;
;     const int K = g.K, nt = K / BK;
;     unsigned voffA[2], voffB[2];
; #pragma unroll
;     for (int i = 0; i < 2; ++i) { int R, C; stage_rc(tid * 16 + i * 8192, R, C); const int Rb = Epi::PERM ? ((R & ~31) + perm32(R & 31)) : R;
;         voffA[i] = (unsigned)(R * K + C) * 2u; voffB[i] = (unsigned)(Rb * K + C) * 2u; }
;     const size_t kstep = (size_t)(BK * 2);
;     const size_t hstep = (size_t)HALF * K * 2;
;     const size_t tstep = 2 * hstep;
;     const unsigned ldsw = (unsigned)wid * 1024u;
;     const int aoff = lds_byte(wr * 64 + fr, fq * 8), boff = lds_byte(wc * 32 + fr, fq * 8);
;     ...
;     Unit cur, nxt; int ui = 0;
;     if (!S.next(0, cur)) return;
;     typedef unsigned long long u64x2_t __attribute__((ext_vector_type(2)));
;     f32x4 acc[2][2][4][2];
;     int rs_pm = -1, rs_tog = 0;
; #pragma unroll
;     for (int a = 0; a < 2; ++a)
; #pragma unroll
;         for (int b = 0; b < 2; ++b)
; #pragma unroll
;             for (int m = 0; m < 4; ++m)
; #pragma unroll
;                 for (int n = 0; n < 2; ++n) { unsigned long long lo_, hi_; asm volatile("v_mov_b64 %0, 0\n\tv_mov_b64 %1, 0" : "=v"(lo_), "=v"(hi_)); acc[a][b][m][n] = __builtin_bit_cast(f32x4, (u64x2_t){lo_, hi_}); }
;     bf16x8 At[4][2], B0[2][2], B1[2][2];
;     const char* cA = (const char*)g.A + (size_t)cur.pm * tstep; const char* cB = (const char*)g.Bt + (size_t)cur.pn * tstep;
;     S.a_ready(cur);
;     if constexpr (SP2) {
;         PG8_STAGE(PG8_SB(0, 0), cB, voffB); PG8_STAGE(PG8_SB(0, 1), cB + hstep, voffB); PG8_STAGE(PG8_SA(0, 0), cA, voffA); PG8_STAGE(PG8_SA(0, 1), cA + hstep, voffA);
;         if (wr == 1) PG8_BAR;
.LBB0_118:
	s_cmp_gt_i32 s88, 5
	s_mov_b64 s[8:9], -1
	s_cbranch_scc0 .LBB0_208
	v_readlane_b32 s4, v253, 10
	s_waitcnt lgkmcnt(0)
	s_add_u32 s8, s14, 0x20000
	v_mov_b32_e32 v0, v230
	v_readlane_b32 s5, v253, 11
	s_addc_u32 s9, s15, 0
	s_andn2_b64 vcc, exec, s[4:5]
	v_readfirstlane_b32 s10, v0
	s_cbranch_vccnz .LBB0_202
	v_lshlrev_b32_e32 v2, 4, v0
	v_add_u32_e32 v3, 0x2000, v2
	v_ashrrev_i32_e32 v4, 31, v3
	v_lshrrev_b32_e32 v4, 22, v4
	v_add_u32_e32 v4, v3, v4
	v_ashrrev_i32_e32 v146, 10, v4
	v_mul_i32_i24_e32 v4, 0x400, v146
	v_sub_u32_e32 v3, v3, v4
	v_lshrrev_b32_e32 v4, 4, v3
	v_bitop3_b32 v3, v4, v3, 32 bitop3:0x6c
	v_ashrrev_i32_e32 v4, 31, v3
	v_lshrrev_b32_e32 v4, 26, v4
	v_add_u32_e32 v4, v3, v4
	v_lshlrev_b32_e32 v5, 3, v146
	v_ashrrev_i32_e32 v147, 6, v4
	v_and_b32_e32 v5, -16, v5
	v_add_u32_e32 v5, v147, v5
	v_and_b32_e32 v6, 3, v147
	s_mov_b32 s7, 0x1fffe0
	v_lshrrev_b32_e32 v7, 2, v5
	v_lshlrev_b32_e32 v8, 1, v5
	v_and_b32_e32 v4, 0xc0, v4
	v_and_or_b32 v6, v5, s7, v6
	v_and_b32_e32 v7, 4, v7
	v_and_b32_e32 v8, 24, v8
	v_sub_u32_e32 v3, v3, v4
	v_or3_b32 v6, v6, v7, v8
	v_lshlrev_b32_e32 v7, 5, v146
	v_ashrrev_i16_sdwa v3, v244, sext(v3) dst_sel:DWORD dst_unused:UNUSED_PAD src0_sel:DWORD src1_sel:BYTE_0
	v_and_b32_e32 v7, 32, v7
	v_bfe_i32 v148, v3, 0, 16
	v_add_lshl_u32 v3, v7, v148, 1
	v_lshl_add_u32 v130, v6, 11, v3
	v_lshl_add_u32 v132, v5, 11, v3
	v_bfe_i32 v3, v0, 27, 1
	v_lshrrev_b32_e32 v3, 22, v3
	v_add_u32_e32 v3, v2, v3
	v_and_b32_e32 v3, 0xfffffc00, v3
	v_sub_u32_e32 v2, v2, v3
	v_lshrrev_b32_e32 v3, 4, v2
	v_ashrrev_i32_e32 v4, 31, v0
	v_bitop3_b32 v2, v3, v2, 32 bitop3:0x6c
	v_lshrrev_b32_e32 v4, 26, v4
	v_ashrrev_i32_e32 v3, 31, v2
	v_add_u32_e32 v4, v0, v4
	v_lshrrev_b32_e32 v3, 26, v3
	v_ashrrev_i32_e32 v150, 6, v4
	v_add_u32_e32 v3, v2, v3
	v_lshlrev_b32_e32 v4, 3, v150
	s_add_u32 s4, s14, 0x10000000
	v_ashrrev_i32_e32 v149, 6, v3
	v_and_b32_e32 v4, -16, v4
	s_addc_u32 s5, s15, 0
	v_add_u32_e32 v4, v149, v4
	s_add_u32 s58, s14, 0xc00000
	v_and_b32_e32 v5, 3, v149
	v_lshrrev_b32_e32 v6, 2, v4
	v_lshlrev_b32_e32 v7, 1, v4
	v_and_b32_e32 v3, 0xc0, v3
	s_addc_u32 s90, s15, 0
	s_ashr_i32 s6, s10, 6
	v_and_or_b32 v5, v4, s7, v5
	v_and_b32_e32 v6, 4, v6
	v_and_b32_e32 v7, 24, v7
	v_sub_u32_e32 v2, v2, v3
	s_ashr_i32 s11, s10, 8
	s_lshl_b32 s91, s6, 10
	v_or3_b32 v5, v5, v6, v7
	v_lshlrev_b32_e32 v6, 5, v150
	v_ashrrev_i16_sdwa v2, v244, sext(v2) dst_sel:DWORD dst_unused:UNUSED_PAD src0_sel:DWORD src1_sel:BYTE_0
	v_readlane_b32 s20, v254, 17
	v_and_b32_e32 v6, 32, v6
	v_bfe_i32 v151, v2, 0, 16
	v_readlane_b32 s21, v254, 18
	s_add_u32 s44, s58, s20
	v_add_lshl_u32 v2, v6, v151, 1
	s_addc_u32 s45, s90, s21
	s_add_i32 s92, s91, 0
	v_lshl_add_u32 v134, v5, 11, v2
	s_add_i32 m0, s92, 0x10000
	s_load_dwordx4 s[48:51], s[0:1], 0x58
	v_lshl_add_u32 v136, v4, 11, v2
	s_waitcnt vmcnt(0)
	global_load_lds_dwordx4 v134, s[44:45]
	s_add_i32 m0, s92, 0x12000
	s_add_u32 s20, s44, 0x40000
	global_load_lds_dwordx4 v130, s[44:45]
	s_addc_u32 s21, s45, 0
	s_add_i32 m0, s92, 0x14000
	v_mov_b32_e32 v135, v1
	global_load_lds_dwordx4 v134, s[20:21]
	s_add_i32 m0, s92, 0x16000
	v_mov_b32_e32 v131, v1
	global_load_lds_dwordx4 v130, s[20:21]
	v_readlane_b32 s20, v254, 46
	v_readlane_b32 s21, v254, 47
	s_add_u32 s46, s4, s20
	s_addc_u32 s47, s5, s21
	s_add_i32 s93, s92, 0x2000
	s_mov_b32 m0, s92
	s_add_u32 s20, s46, 0x40000
	global_load_lds_dwordx4 v136, s[46:47]
	s_mov_b32 m0, s93
	s_addc_u32 s21, s47, 0
	s_add_i32 s94, s92, 0x4000
	global_load_lds_dwordx4 v132, s[46:47]
	s_mov_b32 m0, s94
	s_add_i32 s95, s92, 0x6000
	global_load_lds_dwordx4 v136, s[20:21]
	s_mov_b32 m0, s95
	v_mov_b32_e32 v137, v1
	global_load_lds_dwordx4 v132, s[20:21]
	v_mov_b32_e32 v133, v1
	s_cmp_eq_u32 s11, 1
	v_lshl_add_u64 v[144:145], s[44:45], 0, v[134:135]
	v_lshl_add_u64 v[142:143], s[44:45], 0, v[130:131]
	v_lshl_add_u64 v[138:139], s[46:47], 0, v[136:137]
	s_cselect_b64 s[20:21], -1, 0
	s_cmp_lg_u32 s11, 1
	v_lshl_add_u64 v[140:141], s[46:47], 0, v[132:133]
	s_cbranch_scc1 .LBB0_122
	s_barrier

; #define PG8_STAGE(bufoff, gbase, voff) do { _Pragma("unroll") for (int _i = 0; _i < 2; ++_i) \
;         __builtin_amdgcn_global_load_lds((const unsigned*)((const char*)(gbase) + (voff)[_i]), (PG8_LAS unsigned*)(lds + (bufoff) + ldsw + _i * 8192), 16, 0, 0); } while (0)
; #define PG8_LDA(dst, b, h) do { _Pragma("unroll") for (int m = 0; m < 4; ++m) _Pragma("unroll") for (int k = 0; k < 2; ++k) dst[m][k] = *(const PG8_LAS bf16x8*)(lds + PG8_SA(b, h) + aoff + m * 2048 + k * 1024); } while (0)
; #define PG8_LDB(dst, b, h) do { _Pragma("unroll") for (int n = 0; n < 2; ++n) _Pragma("unroll") for (int k = 0; k < 2; ++k) dst[n][k] = *(const PG8_LAS bf16x8*)(lds + PG8_SB(b, h) + boff + n * 2048 + k * 1024); } while (0)
; #define PG8_MMA(ai, bj, At, Bt) do { __builtin_amdgcn_s_setprio(1); _Pragma("unroll") for (int m = 0; m < 4; ++m) _Pragma("unroll") for (int n = 0; n < 2; ++n) _Pragma("unroll") for (int k = 0; k < 2; ++k) \
;         acc[ai][bj][m][n] = __builtin_amdgcn_mfma_f32_16x16x32_bf16(Bt[n][k], At[m][k], acc[ai][bj][m][n], 0, 0, 0); __builtin_amdgcn_s_setprio(0); } while (0)
; #define PG8_WAIT_V(n) asm volatile("s_waitcnt vmcnt(" #n ")" ::: "memory")
; #define PG8_WAIT_L(n) asm volatile("s_waitcnt lgkmcnt(" #n ")" ::: "memory")
; #define PG8_BAR __builtin_amdgcn_s_barrier()
; #define PG8_SCHED __builtin_amdgcn_sched_barrier(0)
; template <class Epi, class Sched, bool ALIGN_EPI = false, bool SP2 = false>
; __device__ __forceinline__ void gemm_phase(PG8_LAS unsigned char* lds, const Gemm g, const Sched& S, const Epi& E) {
;     ...
;             const bool last = (t == nt - 2);
;             const char* a1 = cA + (size_t)(t + 1) * kstep;
;             const char* a2 = last ? nA : cA + (size_t)(t + 2) * kstep; const char* b2 = last ? nB : cB + (size_t)(t + 2) * kstep;
;             const char* a3 = a2 + kstep; const char* b3 = b2 + kstep;
;             if (last && has_next) S.a_ready(nxt);
;             if constexpr (SP2) {
;             PG8_LDB(B0, 0, 0); PG8_LDB(B1, 0, 1); PG8_SCHED; PG8_LDA(At, 0, 0); PG8_STAGE(PG8_SA(1, 1), a1 + hstep, voffA);
;             PG8_WAIT_V(8); PG8_WAIT_L(0); PG8_BAR; PG8_MMA(0, 0, At, B0); PG8_MMA(0, 1, At, B1); PG8_BAR; PG8_SCHED;
.LBB0_132:
	s_add_u32 s18, s46, 0xfffc0080
	s_addc_u32 s38, s47, -1
	s_add_i32 s39, 0, 0x10000
	s_cmp_eq_u32 s85, 12
	s_cselect_b32 s81, s33, s38
	s_cselect_b32 s80, s73, s18
	v_add_u32_e32 v0, s39, v176
	s_cselect_b32 s45, s75, s84
	s_cselect_b32 s44, s82, s83
	s_add_i32 s18, 0, 0x14000
	ds_read_b128 v[144:147], v0
	ds_read_b128 v[148:151], v0 offset:1024
	ds_read_b128 v[152:155], v0 offset:2048
	ds_read_b128 v[156:159], v0 offset:3072
	v_add_u32_e32 v0, s18, v176
	ds_read_b128 v[160:163], v0
	ds_read_b128 v[164:167], v0 offset:1024
	ds_read_b128 v[168:171], v0 offset:2048
	ds_read_b128 v[172:175], v0 offset:3072
	v_lshl_add_u64 v[218:219], s[46:47], 0, v[140:141]
	s_add_i32 m0, s92, 0xc000
	ds_read_b128 v[180:183], v178
	ds_read_b128 v[184:187], v178 offset:1024
	ds_read_b128 v[188:191], v178 offset:2048
	ds_read_b128 v[192:195], v178 offset:3072
	ds_read_b128 v[202:205], v178 offset:4096
	ds_read_b128 v[206:209], v178 offset:5120
	ds_read_b128 v[210:213], v178 offset:6144
	ds_read_b128 v[214:217], v178 offset:7168
	global_load_lds_dwordx4 v[218:219], off
	v_lshl_add_u64 v[218:219], s[46:47], 0, v[142:143]
	s_add_i32 m0, s92, 0xe000
	s_nop 0
	global_load_lds_dwordx4 v[218:219], off
	s_waitcnt vmcnt(8)
	s_waitcnt lgkmcnt(0)
	s_barrier
	s_setprio 1
	s_cmp_eq_u32 s85, -2
	s_cbranch_scc1 .Lz132_0_first
	v_mfma_f32_16x16x32_bf16 v[118:121], v[144:147], v[180:183], v[118:121]
	v_mfma_f32_16x16x32_bf16 v[118:121], v[148:151], v[184:187], v[118:121]
	v_mfma_f32_16x16x32_bf16 v[102:105], v[144:147], v[188:191], v[102:105]
	v_mfma_f32_16x16x32_bf16 v[102:105], v[148:151], v[192:195], v[102:105]
	v_mfma_f32_16x16x32_bf16 v[86:89], v[144:147], v[202:205], v[86:89]
	v_mfma_f32_16x16x32_bf16 v[86:89], v[148:151], v[206:209], v[86:89]
	v_mfma_f32_16x16x32_bf16 v[70:73], v[144:147], v[210:213], v[70:73]
	v_mfma_f32_16x16x32_bf16 v[70:73], v[148:151], v[214:217], v[70:73]
	v_mfma_f32_16x16x32_bf16 v[114:117], v[152:155], v[180:183], v[114:117]
	v_mfma_f32_16x16x32_bf16 v[114:117], v[156:159], v[184:187], v[114:117]
	v_mfma_f32_16x16x32_bf16 v[98:101], v[152:155], v[188:191], v[98:101]
	v_mfma_f32_16x16x32_bf16 v[98:101], v[156:159], v[192:195], v[98:101]
	v_mfma_f32_16x16x32_bf16 v[82:85], v[152:155], v[202:205], v[82:85]
	v_mfma_f32_16x16x32_bf16 v[82:85], v[156:159], v[206:209], v[82:85]
	v_mfma_f32_16x16x32_bf16 v[66:69], v[152:155], v[210:213], v[66:69]
	v_mfma_f32_16x16x32_bf16 v[66:69], v[156:159], v[214:217], v[66:69]
	v_mfma_f32_16x16x32_bf16 v[126:129], v[160:163], v[180:183], v[126:129]
	v_mfma_f32_16x16x32_bf16 v[126:129], v[164:167], v[184:187], v[126:129]
	v_mfma_f32_16x16x32_bf16 v[110:113], v[160:163], v[188:191], v[110:113]
	v_mfma_f32_16x16x32_bf16 v[110:113], v[164:167], v[192:195], v[110:113]
	v_mfma_f32_16x16x32_bf16 v[94:97], v[160:163], v[202:205], v[94:97]
	v_mfma_f32_16x16x32_bf16 v[94:97], v[164:167], v[206:209], v[94:97]
	v_mfma_f32_16x16x32_bf16 v[78:81], v[160:163], v[210:213], v[78:81]
	v_mfma_f32_16x16x32_bf16 v[78:81], v[164:167], v[214:217], v[78:81]
	v_mfma_f32_16x16x32_bf16 v[122:125], v[168:171], v[180:183], v[122:125]
	v_mfma_f32_16x16x32_bf16 v[122:125], v[172:175], v[184:187], v[122:125]
	v_mfma_f32_16x16x32_bf16 v[106:109], v[168:171], v[188:191], v[106:109]
	v_mfma_f32_16x16x32_bf16 v[106:109], v[172:175], v[192:195], v[106:109]
	v_mfma_f32_16x16x32_bf16 v[90:93], v[168:171], v[202:205], v[90:93]
	v_mfma_f32_16x16x32_bf16 v[90:93], v[172:175], v[206:209], v[90:93]
	v_mfma_f32_16x16x32_bf16 v[74:77], v[168:171], v[210:213], v[74:77]
	v_mfma_f32_16x16x32_bf16 v[74:77], v[172:175], v[214:217], v[74:77]
	s_branch .Lz132_0_join
.Lz132_0_first:
	v_mfma_f32_16x16x32_bf16 v[118:121], v[144:147], v[180:183], 0
	v_mfma_f32_16x16x32_bf16 v[118:121], v[148:151], v[184:187], v[118:121]
	v_mfma_f32_16x16x32_bf16 v[102:105], v[144:147], v[188:191], 0
	v_mfma_f32_16x16x32_bf16 v[102:105], v[148:151], v[192:195], v[102:105]
	v_mfma_f32_16x16x32_bf16 v[86:89], v[144:147], v[202:205], 0
	v_mfma_f32_16x16x32_bf16 v[86:89], v[148:151], v[206:209], v[86:89]
	v_mfma_f32_16x16x32_bf16 v[70:73], v[144:147], v[210:213], 0
	v_mfma_f32_16x16x32_bf16 v[70:73], v[148:151], v[214:217], v[70:73]
	v_mfma_f32_16x16x32_bf16 v[114:117], v[152:155], v[180:183], 0
	v_mfma_f32_16x16x32_bf16 v[114:117], v[156:159], v[184:187], v[114:117]
	v_mfma_f32_16x16x32_bf16 v[98:101], v[152:155], v[188:191], 0
	v_mfma_f32_16x16x32_bf16 v[98:101], v[156:159], v[192:195], v[98:101]
	v_mfma_f32_16x16x32_bf16 v[82:85], v[152:155], v[202:205], 0
	v_mfma_f32_16x16x32_bf16 v[82:85], v[156:159], v[206:209], v[82:85]
	v_mfma_f32_16x16x32_bf16 v[66:69], v[152:155], v[210:213], 0
	v_mfma_f32_16x16x32_bf16 v[66:69], v[156:159], v[214:217], v[66:69]
	v_mfma_f32_16x16x32_bf16 v[126:129], v[160:163], v[180:183], 0
	v_mfma_f32_16x16x32_bf16 v[126:129], v[164:167], v[184:187], v[126:129]
	v_mfma_f32_16x16x32_bf16 v[110:113], v[160:163], v[188:191], 0
	v_mfma_f32_16x16x32_bf16 v[110:113], v[164:167], v[192:195], v[110:113]
	v_mfma_f32_16x16x32_bf16 v[94:97], v[160:163], v[202:205], 0
	v_mfma_f32_16x16x32_bf16 v[94:97], v[164:167], v[206:209], v[94:97]
	v_mfma_f32_16x16x32_bf16 v[78:81], v[160:163], v[210:213], 0
	v_mfma_f32_16x16x32_bf16 v[78:81], v[164:167], v[214:217], v[78:81]
	v_mfma_f32_16x16x32_bf16 v[122:125], v[168:171], v[180:183], 0
	v_mfma_f32_16x16x32_bf16 v[122:125], v[172:175], v[184:187], v[122:125]
	v_mfma_f32_16x16x32_bf16 v[106:109], v[168:171], v[188:191], 0
	v_mfma_f32_16x16x32_bf16 v[106:109], v[172:175], v[192:195], v[106:109]
	v_mfma_f32_16x16x32_bf16 v[90:93], v[168:171], v[202:205], 0
	v_mfma_f32_16x16x32_bf16 v[90:93], v[172:175], v[206:209], v[90:93]
	v_mfma_f32_16x16x32_bf16 v[74:77], v[168:171], v[210:213], 0
	v_mfma_f32_16x16x32_bf16 v[74:77], v[172:175], v[214:217], v[74:77]
; #define PG8_STAGE(bufoff, gbase, voff) do { _Pragma("unroll") for (int _i = 0; _i < 2; ++_i) \
;         __builtin_amdgcn_global_load_lds((const unsigned*)((const char*)(gbase) + (voff)[_i]), (PG8_LAS unsigned*)(lds + (bufoff) + ldsw + _i * 8192), 16, 0, 0); } while (0)
; #define PG8_LDA(dst, b, h) do { _Pragma("unroll") for (int m = 0; m < 4; ++m) _Pragma("unroll") for (int k = 0; k < 2; ++k) dst[m][k] = *(const PG8_LAS bf16x8*)(lds + PG8_SA(b, h) + aoff + m * 2048 + k * 1024); } while (0)
; #define PG8_MMA(ai, bj, At, Bt) do { __builtin_amdgcn_s_setprio(1); _Pragma("unroll") for (int m = 0; m < 4; ++m) _Pragma("unroll") for (int n = 0; n < 2; ++n) _Pragma("unroll") for (int k = 0; k < 2; ++k) \
;         acc[ai][bj][m][n] = __builtin_amdgcn_mfma_f32_16x16x32_bf16(Bt[n][k], At[m][k], acc[ai][bj][m][n], 0, 0, 0); __builtin_amdgcn_s_setprio(0); } while (0)
; #define PG8_WAIT_V(n) asm volatile("s_waitcnt vmcnt(" #n ")" ::: "memory")
; #define PG8_WAIT_L(n) asm volatile("s_waitcnt lgkmcnt(" #n ")" ::: "memory")
; #define PG8_BAR __builtin_amdgcn_s_barrier()
; #define PG8_SCHED __builtin_amdgcn_sched_barrier(0)
; template <class Epi, class Sched, bool ALIGN_EPI = false, bool SP2 = false>
; __device__ __forceinline__ void gemm_phase(PG8_LAS unsigned char* lds, const Gemm g, const Sched& S, const Epi& E) {
;     ...
;             PG8_LDA(At, 0, 1); PG8_STAGE(PG8_SB(0, 0), b2, voffB); PG8_STAGE(PG8_SB(0, 1), b2 + hstep, voffB); PG8_STAGE(PG8_SA(0, 0), a2, voffA);
;             PG8_WAIT_V(8); PG8_WAIT_L(0); PG8_BAR; PG8_MMA(1, 0, At, B0); PG8_MMA(1, 1, At, B1); PG8_BAR; PG8_SCHED;
.Lz132_0_join:
	s_setprio 0
	s_barrier
	s_add_i32 s38, s39, s91
	v_lshl_add_u64 v[218:219], s[44:45], 0, v[134:135]
	s_mov_b32 m0, s38
	ds_read_b128 v[180:183], v178 offset:16384
	ds_read_b128 v[184:187], v178 offset:17408
	ds_read_b128 v[188:191], v178 offset:18432
	ds_read_b128 v[192:195], v178 offset:19456
	ds_read_b128 v[202:205], v178 offset:20480
	ds_read_b128 v[206:209], v178 offset:21504
	ds_read_b128 v[210:213], v178 offset:22528
	ds_read_b128 v[214:217], v178 offset:23552
	global_load_lds_dwordx4 v[218:219], off
	s_add_i32 m0, s38, 0x2000
	s_add_u32 s38, s44, 0x40000
	v_lshl_add_u64 v[220:221], s[44:45], 0, v[130:131]
	s_addc_u32 s39, s45, 0
	s_add_i32 s18, s18, s91
	global_load_lds_dwordx4 v[220:221], off
	v_lshl_add_u64 v[222:223], s[38:39], 0, v[134:135]
	s_mov_b32 m0, s18
	v_lshl_add_u64 v[224:225], s[80:81], 0, v[132:133]
	global_load_lds_dwordx4 v[222:223], off
	v_lshl_add_u64 v[222:223], s[38:39], 0, v[130:131]
	s_add_i32 m0, s18, 0x2000
	s_nop 0
	global_load_lds_dwordx4 v[222:223], off
	v_lshl_add_u64 v[222:223], s[80:81], 0, v[136:137]
	s_mov_b32 m0, s92
	s_nop 0
	global_load_lds_dwordx4 v[222:223], off
	s_mov_b32 m0, s93
	s_nop 0
	global_load_lds_dwordx4 v[224:225], off
	s_waitcnt vmcnt(8)
	s_waitcnt lgkmcnt(0)
	s_barrier
	s_setprio 1
	s_cmp_eq_u32 s85, -2
	s_cbranch_scc1 .Lz132_1_first
	v_mfma_f32_16x16x32_bf16 v[54:57], v[144:147], v[180:183], v[54:57]
	v_mfma_f32_16x16x32_bf16 v[54:57], v[148:151], v[184:187], v[54:57]
	v_mfma_f32_16x16x32_bf16 v[38:41], v[144:147], v[188:191], v[38:41]
	v_mfma_f32_16x16x32_bf16 v[38:41], v[148:151], v[192:195], v[38:41]
	v_mfma_f32_16x16x32_bf16 v[22:25], v[144:147], v[202:205], v[22:25]
	v_mfma_f32_16x16x32_bf16 v[22:25], v[148:151], v[206:209], v[22:25]
	v_mfma_f32_16x16x32_bf16 v[6:9], v[144:147], v[210:213], v[6:9]
	v_mfma_f32_16x16x32_bf16 v[6:9], v[148:151], v[214:217], v[6:9]
	v_mfma_f32_16x16x32_bf16 v[50:53], v[152:155], v[180:183], v[50:53]
	v_mfma_f32_16x16x32_bf16 v[50:53], v[156:159], v[184:187], v[50:53]
	v_mfma_f32_16x16x32_bf16 v[34:37], v[152:155], v[188:191], v[34:37]
	v_mfma_f32_16x16x32_bf16 v[34:37], v[156:159], v[192:195], v[34:37]
	v_mfma_f32_16x16x32_bf16 v[18:21], v[152:155], v[202:205], v[18:21]
	v_mfma_f32_16x16x32_bf16 v[18:21], v[156:159], v[206:209], v[18:21]
	v_mfma_f32_16x16x32_bf16 v[2:5], v[152:155], v[210:213], v[2:5]
	v_mfma_f32_16x16x32_bf16 v[2:5], v[156:159], v[214:217], v[2:5]
	v_mfma_f32_16x16x32_bf16 v[62:65], v[160:163], v[180:183], v[62:65]
	v_mfma_f32_16x16x32_bf16 v[62:65], v[164:167], v[184:187], v[62:65]
	v_mfma_f32_16x16x32_bf16 v[46:49], v[160:163], v[188:191], v[46:49]
	v_mfma_f32_16x16x32_bf16 v[46:49], v[164:167], v[192:195], v[46:49]
	v_mfma_f32_16x16x32_bf16 v[30:33], v[160:163], v[202:205], v[30:33]
	v_mfma_f32_16x16x32_bf16 v[30:33], v[164:167], v[206:209], v[30:33]
	v_mfma_f32_16x16x32_bf16 v[10:13], v[160:163], v[210:213], v[10:13]
	v_mfma_f32_16x16x32_bf16 v[10:13], v[164:167], v[214:217], v[10:13]
	v_mfma_f32_16x16x32_bf16 v[58:61], v[168:171], v[180:183], v[58:61]
	v_mfma_f32_16x16x32_bf16 v[58:61], v[172:175], v[184:187], v[58:61]
	v_mfma_f32_16x16x32_bf16 v[42:45], v[168:171], v[188:191], v[42:45]
	v_mfma_f32_16x16x32_bf16 v[42:45], v[172:175], v[192:195], v[42:45]
	v_mfma_f32_16x16x32_bf16 v[26:29], v[168:171], v[202:205], v[26:29]
	v_mfma_f32_16x16x32_bf16 v[26:29], v[172:175], v[206:209], v[26:29]
	v_mfma_f32_16x16x32_bf16 v[14:17], v[168:171], v[210:213], v[14:17]
	v_mfma_f32_16x16x32_bf16 v[14:17], v[172:175], v[214:217], v[14:17]
	s_branch .Lz132_1_join
.Lz132_1_first:
	v_mfma_f32_16x16x32_bf16 v[54:57], v[144:147], v[180:183], 0
	v_mfma_f32_16x16x32_bf16 v[54:57], v[148:151], v[184:187], v[54:57]
	v_mfma_f32_16x16x32_bf16 v[38:41], v[144:147], v[188:191], 0
	v_mfma_f32_16x16x32_bf16 v[38:41], v[148:151], v[192:195], v[38:41]
	v_mfma_f32_16x16x32_bf16 v[22:25], v[144:147], v[202:205], 0
	v_mfma_f32_16x16x32_bf16 v[22:25], v[148:151], v[206:209], v[22:25]
	v_mfma_f32_16x16x32_bf16 v[6:9], v[144:147], v[210:213], 0
	v_mfma_f32_16x16x32_bf16 v[6:9], v[148:151], v[214:217], v[6:9]
	v_mfma_f32_16x16x32_bf16 v[50:53], v[152:155], v[180:183], 0
	v_mfma_f32_16x16x32_bf16 v[50:53], v[156:159], v[184:187], v[50:53]
	v_mfma_f32_16x16x32_bf16 v[34:37], v[152:155], v[188:191], 0
	v_mfma_f32_16x16x32_bf16 v[34:37], v[156:159], v[192:195], v[34:37]
	v_mfma_f32_16x16x32_bf16 v[18:21], v[152:155], v[202:205], 0
	v_mfma_f32_16x16x32_bf16 v[18:21], v[156:159], v[206:209], v[18:21]
	v_mfma_f32_16x16x32_bf16 v[2:5], v[152:155], v[210:213], 0
	v_mfma_f32_16x16x32_bf16 v[2:5], v[156:159], v[214:217], v[2:5]
	v_mfma_f32_16x16x32_bf16 v[62:65], v[160:163], v[180:183], 0
	v_mfma_f32_16x16x32_bf16 v[62:65], v[164:167], v[184:187], v[62:65]
	v_mfma_f32_16x16x32_bf16 v[46:49], v[160:163], v[188:191], 0
	v_mfma_f32_16x16x32_bf16 v[46:49], v[164:167], v[192:195], v[46:49]
	v_mfma_f32_16x16x32_bf16 v[30:33], v[160:163], v[202:205], 0
	v_mfma_f32_16x16x32_bf16 v[30:33], v[164:167], v[206:209], v[30:33]
	v_mfma_f32_16x16x32_bf16 v[10:13], v[160:163], v[210:213], 0
	v_mfma_f32_16x16x32_bf16 v[10:13], v[164:167], v[214:217], v[10:13]
	v_mfma_f32_16x16x32_bf16 v[58:61], v[168:171], v[180:183], 0
	v_mfma_f32_16x16x32_bf16 v[58:61], v[172:175], v[184:187], v[58:61]
	v_mfma_f32_16x16x32_bf16 v[42:45], v[168:171], v[188:191], 0
	v_mfma_f32_16x16x32_bf16 v[42:45], v[172:175], v[192:195], v[42:45]
	v_mfma_f32_16x16x32_bf16 v[26:29], v[168:171], v[202:205], 0
	v_mfma_f32_16x16x32_bf16 v[26:29], v[172:175], v[206:209], v[26:29]
	v_mfma_f32_16x16x32_bf16 v[14:17], v[168:171], v[210:213], 0
	v_mfma_f32_16x16x32_bf16 v[14:17], v[172:175], v[214:217], v[14:17]
; #define PG8_STAGE(bufoff, gbase, voff) do { _Pragma("unroll") for (int _i = 0; _i < 2; ++_i) \
;         __builtin_amdgcn_global_load_lds((const unsigned*)((const char*)(gbase) + (voff)[_i]), (PG8_LAS unsigned*)(lds + (bufoff) + ldsw + _i * 8192), 16, 0, 0); } while (0)
; #define PG8_LDA(dst, b, h) do { _Pragma("unroll") for (int m = 0; m < 4; ++m) _Pragma("unroll") for (int k = 0; k < 2; ++k) dst[m][k] = *(const PG8_LAS bf16x8*)(lds + PG8_SA(b, h) + aoff + m * 2048 + k * 1024); } while (0)
; #define PG8_LDB(dst, b, h) do { _Pragma("unroll") for (int n = 0; n < 2; ++n) _Pragma("unroll") for (int k = 0; k < 2; ++k) dst[n][k] = *(const PG8_LAS bf16x8*)(lds + PG8_SB(b, h) + boff + n * 2048 + k * 1024); } while (0)
; #define PG8_MMA(ai, bj, At, Bt) do { __builtin_amdgcn_s_setprio(1); _Pragma("unroll") for (int m = 0; m < 4; ++m) _Pragma("unroll") for (int n = 0; n < 2; ++n) _Pragma("unroll") for (int k = 0; k < 2; ++k) \
;         acc[ai][bj][m][n] = __builtin_amdgcn_mfma_f32_16x16x32_bf16(Bt[n][k], At[m][k], acc[ai][bj][m][n], 0, 0, 0); __builtin_amdgcn_s_setprio(0); } while (0)
; #define PG8_WAIT_V(n) asm volatile("s_waitcnt vmcnt(" #n ")" ::: "memory")
; #define PG8_WAIT_L(n) asm volatile("s_waitcnt lgkmcnt(" #n ")" ::: "memory")
; #define PG8_BAR __builtin_amdgcn_s_barrier()
; #define PG8_SCHED __builtin_amdgcn_sched_barrier(0)
; template <class Epi, class Sched, bool ALIGN_EPI = false, bool SP2 = false>
; __device__ __forceinline__ void gemm_phase(PG8_LAS unsigned char* lds, const Gemm g, const Sched& S, const Epi& E) {
;     ...
;             PG8_WAIT_V(8); PG8_WAIT_L(0); PG8_BAR; PG8_MMA(1, 0, At, B0); PG8_MMA(1, 1, At, B1); PG8_BAR; PG8_SCHED;
;             PG8_LDB(B0, 1, 0); PG8_LDB(B1, 1, 1); PG8_SCHED; PG8_LDA(At, 1, 0); PG8_STAGE(PG8_SA(0, 1), a2 + hstep, voffA);
;             PG8_WAIT_V(8); PG8_WAIT_L(0); PG8_BAR; PG8_MMA(0, 0, At, B0); PG8_MMA(0, 1, At, B1); PG8_BAR; PG8_SCHED;
.Lz132_1_join:
	s_setprio 0
	s_barrier
	s_add_i32 s18, 0, 0x18000
	v_add_u32_e32 v0, s18, v176
	s_add_i32 vcc_lo, 0, 0x1c000
	ds_read_b128 v[144:147], v0
	ds_read_b128 v[148:151], v0 offset:1024
	ds_read_b128 v[152:155], v0 offset:2048
	ds_read_b128 v[156:159], v0 offset:3072
	v_add_u32_e32 v0, vcc_lo, v176
	ds_read_b128 v[160:163], v0
	ds_read_b128 v[164:167], v0 offset:1024
	ds_read_b128 v[168:171], v0 offset:2048
	ds_read_b128 v[172:175], v0 offset:3072
	s_add_u32 s38, s80, 0x40000
	s_addc_u32 s39, s81, 0
	s_mov_b32 m0, s94
	v_lshl_add_u64 v[226:227], s[38:39], 0, v[136:137]
	ds_read_b128 v[180:183], v178 offset:32768
	ds_read_b128 v[184:187], v178 offset:33792
	ds_read_b128 v[188:191], v178 offset:34816
	ds_read_b128 v[192:195], v178 offset:35840
	ds_read_b128 v[202:205], v178 offset:36864
	ds_read_b128 v[206:209], v178 offset:37888
	ds_read_b128 v[210:213], v178 offset:38912
	ds_read_b128 v[214:217], v178 offset:39936
	global_load_lds_dwordx4 v[226:227], off
	v_lshl_add_u64 v[226:227], s[38:39], 0, v[132:133]
	s_mov_b32 m0, s95
	s_nop 0
	global_load_lds_dwordx4 v[226:227], off
	s_waitcnt vmcnt(8)
	s_waitcnt lgkmcnt(0)
	s_barrier
	s_setprio 1
	v_mfma_f32_16x16x32_bf16 v[118:121], v[144:147], v[180:183], v[118:121]
	v_mfma_f32_16x16x32_bf16 v[118:121], v[148:151], v[184:187], v[118:121]
	v_mfma_f32_16x16x32_bf16 v[102:105], v[144:147], v[188:191], v[102:105]
	v_mfma_f32_16x16x32_bf16 v[102:105], v[148:151], v[192:195], v[102:105]
	v_mfma_f32_16x16x32_bf16 v[86:89], v[144:147], v[202:205], v[86:89]
	v_mfma_f32_16x16x32_bf16 v[86:89], v[148:151], v[206:209], v[86:89]
	v_mfma_f32_16x16x32_bf16 v[70:73], v[144:147], v[210:213], v[70:73]
	v_mfma_f32_16x16x32_bf16 v[70:73], v[148:151], v[214:217], v[70:73]
	v_mfma_f32_16x16x32_bf16 v[114:117], v[152:155], v[180:183], v[114:117]
	v_mfma_f32_16x16x32_bf16 v[114:117], v[156:159], v[184:187], v[114:117]
	v_mfma_f32_16x16x32_bf16 v[98:101], v[152:155], v[188:191], v[98:101]
	v_mfma_f32_16x16x32_bf16 v[98:101], v[156:159], v[192:195], v[98:101]
	v_mfma_f32_16x16x32_bf16 v[82:85], v[152:155], v[202:205], v[82:85]
	v_mfma_f32_16x16x32_bf16 v[82:85], v[156:159], v[206:209], v[82:85]
	v_mfma_f32_16x16x32_bf16 v[66:69], v[152:155], v[210:213], v[66:69]
	v_mfma_f32_16x16x32_bf16 v[66:69], v[156:159], v[214:217], v[66:69]
	v_mfma_f32_16x16x32_bf16 v[126:129], v[160:163], v[180:183], v[126:129]
	v_mfma_f32_16x16x32_bf16 v[126:129], v[164:167], v[184:187], v[126:129]
	v_mfma_f32_16x16x32_bf16 v[110:113], v[160:163], v[188:191], v[110:113]
	v_mfma_f32_16x16x32_bf16 v[110:113], v[164:167], v[192:195], v[110:113]
	v_mfma_f32_16x16x32_bf16 v[94:97], v[160:163], v[202:205], v[94:97]
	v_mfma_f32_16x16x32_bf16 v[94:97], v[164:167], v[206:209], v[94:97]
	v_mfma_f32_16x16x32_bf16 v[78:81], v[160:163], v[210:213], v[78:81]
	v_mfma_f32_16x16x32_bf16 v[78:81], v[164:167], v[214:217], v[78:81]
	v_mfma_f32_16x16x32_bf16 v[122:125], v[168:171], v[180:183], v[122:125]
	v_mfma_f32_16x16x32_bf16 v[122:125], v[172:175], v[184:187], v[122:125]
	v_mfma_f32_16x16x32_bf16 v[106:109], v[168:171], v[188:191], v[106:109]
	v_mfma_f32_16x16x32_bf16 v[106:109], v[172:175], v[192:195], v[106:109]
	v_mfma_f32_16x16x32_bf16 v[90:93], v[168:171], v[202:205], v[90:93]
	v_mfma_f32_16x16x32_bf16 v[90:93], v[172:175], v[206:209], v[90:93]
	v_mfma_f32_16x16x32_bf16 v[74:77], v[168:171], v[210:213], v[74:77]
	v_mfma_f32_16x16x32_bf16 v[74:77], v[172:175], v[214:217], v[74:77]
	s_setprio 0
	s_barrier
; #define PG8_STAGE(bufoff, gbase, voff) do { _Pragma("unroll") for (int _i = 0; _i < 2; ++_i) \
;         __builtin_amdgcn_global_load_lds((const unsigned*)((const char*)(gbase) + (voff)[_i]), (PG8_LAS unsigned*)(lds + (bufoff) + ldsw + _i * 8192), 16, 0, 0); } while (0)
; #define PG8_LDA(dst, b, h) do { _Pragma("unroll") for (int m = 0; m < 4; ++m) _Pragma("unroll") for (int k = 0; k < 2; ++k) dst[m][k] = *(const PG8_LAS bf16x8*)(lds + PG8_SA(b, h) + aoff + m * 2048 + k * 1024); } while (0)
; #define PG8_WAIT_V(n) asm volatile("s_waitcnt vmcnt(" #n ")" ::: "memory")
; template <class Epi, class Sched, bool ALIGN_EPI = false, bool SP2 = false>
; __device__ __forceinline__ void gemm_phase(PG8_LAS unsigned char* lds, const Gemm g, const Sched& S, const Epi& E) {
;     ...
;             PG8_LDA(At, 1, 1); PG8_STAGE(PG8_SB(1, 0), b3, voffB); PG8_STAGE(PG8_SB(1, 1), b3 + hstep, voffB); PG8_STAGE(PG8_SA(1, 0), a3, voffA);
;             PG8_WAIT_V(8); PG8_WAIT_L(0); PG8_BAR; PG8_MMA(1, 0, At, B0); PG8_MMA(1, 1, At, B1); PG8_BAR; PG8_SCHED;
;             } else {
;             PG8_LDB(B0, 0, 0); PG8_SCHED; PG8_LDA(At, 0, 0); PG8_STAGE(PG8_SA(1, 1), a1 + hstep, voffA);
;             PG8_WAIT_L(8); PG8_BAR; PG8_WAIT_L(0); PG8_MMA(0, 0, At, B0); PG8_BAR; PG8_SCHED;
;             PG8_LDB(B1, 0, 1); PG8_STAGE(PG8_SB(0, 0), b2, voffB);
;             PG8_BAR; PG8_WAIT_L(0); PG8_MMA(0, 1, At, B1); PG8_BAR;
;             PG8_LDA(At, 0, 1); PG8_STAGE(PG8_SA(0, 0), a2, voffA);
;             PG8_BAR; PG8_WAIT_L(0); PG8_MMA(1, 0, At, B0); PG8_BAR; PG8_SCHED;
;             PG8_STAGE(PG8_SB(0, 1), b2 + hstep, voffB);
;             PG8_WAIT_V(6); PG8_BAR; PG8_MMA(1, 1, At, B1); PG8_BAR;
;             PG8_LDB(B0, 1, 0); PG8_SCHED; PG8_LDA(At, 1, 0); PG8_STAGE(PG8_SA(0, 1), a2 + hstep, voffA);
;             PG8_WAIT_L(8); PG8_BAR; PG8_WAIT_L(0); PG8_MMA(0, 0, At, B0); PG8_BAR; PG8_SCHED;
;             PG8_LDB(B1, 1, 1); PG8_STAGE(PG8_SB(1, 0), b3, voffB);
;             PG8_BAR; PG8_WAIT_L(0); PG8_MMA(0, 1, At, B1); PG8_BAR;
;             PG8_LDA(At, 1, 1); PG8_STAGE(PG8_SA(1, 0), a3, voffA);
;             PG8_BAR; PG8_WAIT_L(0); PG8_MMA(1, 0, At, B0); PG8_BAR; PG8_SCHED;
;             PG8_STAGE(PG8_SB(1, 1), b3 + hstep, voffB);
;             PG8_WAIT_V(6); PG8_BAR; PG8_MMA(1, 1, At, B1); PG8_BAR;
;             }
;         }
;         if constexpr (ALIGN_EPI) { if (wr == 0) PG8_BAR; }
	s_add_i32 s18, s18, s91
	v_lshl_add_u64 v[218:219], v[218:219], 0, s[30:31]
	s_mov_b32 m0, s18
	ds_read_b128 v[180:183], v178 offset:49152
	ds_read_b128 v[184:187], v178 offset:50176
	ds_read_b128 v[188:191], v178 offset:51200
	ds_read_b128 v[192:195], v178 offset:52224
	ds_read_b128 v[202:205], v178 offset:53248
	ds_read_b128 v[206:209], v178 offset:54272
	ds_read_b128 v[210:213], v178 offset:55296
	ds_read_b128 v[214:217], v178 offset:56320
	global_load_lds_dwordx4 v[218:219], off
	s_add_i32 m0, s18, 0x2000
	s_add_u32 s38, s44, 0x40080
	v_lshl_add_u64 v[218:219], v[220:221], 0, s[30:31]
	s_addc_u32 s39, s45, 0
	s_add_i32 s18, vcc_lo, s91
	global_load_lds_dwordx4 v[218:219], off
	v_lshl_add_u64 v[218:219], s[38:39], 0, v[134:135]
	s_mov_b32 m0, s18
	s_nop 0
	global_load_lds_dwordx4 v[218:219], off
	v_lshl_add_u64 v[218:219], s[38:39], 0, v[130:131]
	s_add_i32 m0, s18, 0x2000
	s_nop 0
	global_load_lds_dwordx4 v[218:219], off
	v_lshl_add_u64 v[218:219], v[222:223], 0, s[30:31]
	s_mov_b32 m0, s7
	s_nop 0
	global_load_lds_dwordx4 v[218:219], off
	v_lshl_add_u64 v[218:219], v[224:225], 0, s[30:31]
	s_mov_b32 m0, s96
	s_nop 0
	global_load_lds_dwordx4 v[218:219], off
	s_waitcnt vmcnt(8)
	s_waitcnt lgkmcnt(0)
	s_barrier
	s_setprio 1
	v_mfma_f32_16x16x32_bf16 v[54:57], v[144:147], v[180:183], v[54:57]
	v_mfma_f32_16x16x32_bf16 v[54:57], v[148:151], v[184:187], v[54:57]
	v_mfma_f32_16x16x32_bf16 v[38:41], v[144:147], v[188:191], v[38:41]
	v_mfma_f32_16x16x32_bf16 v[38:41], v[148:151], v[192:195], v[38:41]
	v_mfma_f32_16x16x32_bf16 v[22:25], v[144:147], v[202:205], v[22:25]
	v_mfma_f32_16x16x32_bf16 v[22:25], v[148:151], v[206:209], v[22:25]
	v_mfma_f32_16x16x32_bf16 v[6:9], v[144:147], v[210:213], v[6:9]
	v_mfma_f32_16x16x32_bf16 v[6:9], v[148:151], v[214:217], v[6:9]
	v_mfma_f32_16x16x32_bf16 v[50:53], v[152:155], v[180:183], v[50:53]
	v_mfma_f32_16x16x32_bf16 v[50:53], v[156:159], v[184:187], v[50:53]
	v_mfma_f32_16x16x32_bf16 v[34:37], v[152:155], v[188:191], v[34:37]
	v_mfma_f32_16x16x32_bf16 v[34:37], v[156:159], v[192:195], v[34:37]
	v_mfma_f32_16x16x32_bf16 v[18:21], v[152:155], v[202:205], v[18:21]
	v_mfma_f32_16x16x32_bf16 v[18:21], v[156:159], v[206:209], v[18:21]
	v_mfma_f32_16x16x32_bf16 v[2:5], v[152:155], v[210:213], v[2:5]
	v_mfma_f32_16x16x32_bf16 v[2:5], v[156:159], v[214:217], v[2:5]
	v_mfma_f32_16x16x32_bf16 v[62:65], v[160:163], v[180:183], v[62:65]
	v_mfma_f32_16x16x32_bf16 v[62:65], v[164:167], v[184:187], v[62:65]
	v_mfma_f32_16x16x32_bf16 v[46:49], v[160:163], v[188:191], v[46:49]
	v_mfma_f32_16x16x32_bf16 v[46:49], v[164:167], v[192:195], v[46:49]
	v_mfma_f32_16x16x32_bf16 v[30:33], v[160:163], v[202:205], v[30:33]
	v_mfma_f32_16x16x32_bf16 v[30:33], v[164:167], v[206:209], v[30:33]
	v_mfma_f32_16x16x32_bf16 v[10:13], v[160:163], v[210:213], v[10:13]
	v_mfma_f32_16x16x32_bf16 v[10:13], v[164:167], v[214:217], v[10:13]
	v_mfma_f32_16x16x32_bf16 v[58:61], v[168:171], v[180:183], v[58:61]
	v_mfma_f32_16x16x32_bf16 v[58:61], v[172:175], v[184:187], v[58:61]
	v_mfma_f32_16x16x32_bf16 v[42:45], v[168:171], v[188:191], v[42:45]
	v_mfma_f32_16x16x32_bf16 v[42:45], v[172:175], v[192:195], v[42:45]
	v_mfma_f32_16x16x32_bf16 v[26:29], v[168:171], v[202:205], v[26:29]
	v_mfma_f32_16x16x32_bf16 v[26:29], v[172:175], v[206:209], v[26:29]
	v_mfma_f32_16x16x32_bf16 v[14:17], v[168:171], v[210:213], v[14:17]
	v_mfma_f32_16x16x32_bf16 v[14:17], v[172:175], v[214:217], v[14:17]
	s_setprio 0
	s_barrier
	s_add_i32 s85, s85, 2
	s_add_u32 s46, s46, 0x100
	s_addc_u32 s47, s47, 0
	s_add_u32 s83, s83, 0x100
	s_addc_u32 s84, s84, 0
	s_cmp_gt_u32 s85, 13
	s_cbranch_scc0 .LBB0_132
	s_and_b64 vcc, exec, s[10:11]
	s_cbranch_vccz .LBB0_135
	s_barrier

; __device__ __forceinline__ unsigned cvt_pk_bf16(float lo, float hi) { unsigned r; asm volatile("v_cvt_pk_bf16_f32 %0, %1, %2" : "=v"(r) : "v"(lo), "v"(hi)); return r; }
;     __device__ __forceinline__ void operator()(const f32x4 (&acc)[2][2][4][2], const Unit& u, int wr, int wc, int fr, int fq, PG8_LAS unsigned char* lds, int& rs_pm, int& rs_tog) const {
;     ...
;                 for (int bj = 0; bj < 2; ++bj) { u32x4 w; w.x = cvt_pk_bf16(x[bj][0][0], x[bj][0][1]); w.y = cvt_pk_bf16(x[bj][0][2], x[bj][0][3]); w.z = cvt_pk_bf16(x[bj][1][0], x[bj][1][1]); w.w = cvt_pk_bf16(x[bj][1][2], x[bj][1][3]);
;                     *(u32x4*)(base + (size_t)row * 1024 + head * 64 + 32 * bj + dcol) = w; }
; template <class Epi, class Sched, bool ALIGN_EPI = false, bool SP2 = false>
; __device__ __forceinline__ void gemm_phase(PG8_LAS unsigned char* lds, const Gemm g, const Sched& S, const Epi& E) {
;     ...
;         if (!has_next) break;
; #pragma unroll
;         for (int a = 0; a < 2; ++a)
; #pragma unroll
;             for (int b = 0; b < 2; ++b)
; #pragma unroll
;                 for (int m = 0; m < 4; ++m)
; #pragma unroll
;                     for (int n = 0; n < 2; ++n) { unsigned long long lo_, hi_; asm volatile("v_mov_b64 %0, 0\n\tv_mov_b64 %1, 0" : "=v"(lo_), "=v"(hi_)); acc[a][b][m][n] = __builtin_bit_cast(f32x4, (u64x2_t){lo_, hi_}); }
;         cur = nxt; cA = nA; cB = nB; ++ui;
.LBB0_198:
	v_lshlrev_b64 v[2:3], 11, v[116:117]
	v_lshl_add_u64 v[6:7], v[114:115], 0, v[2:3]
	s_mov_b64 s[38:39], 0x58000
	s_mov_b32 s18, 0x58000
	v_lshl_add_u64 v[8:9], v[6:7], 0, s[38:39]
	v_add_co_u32_e32 v6, vcc, s18, v6
	v_cvt_pk_bf16_f32 v2, v16, v17
	v_cvt_pk_bf16_f32 v3, v14, v15
	v_cvt_pk_bf16_f32 v4, v24, v25
	v_cvt_pk_bf16_f32 v5, v22, v23
	s_nop 1
	v_addc_co_u32_e32 v7, vcc, 0, v7, vcc
	global_store_dwordx4 v[6:7], v[2:5], off
	s_andn2_b64 vcc, exec, s[42:43]
	s_mov_b64 s[42:43], -1
	v_cvt_pk_bf16_f32 v2, v28, v29
	v_cvt_pk_bf16_f32 v3, v26, v27
	v_cvt_pk_bf16_f32 v4, v32, v33
	v_cvt_pk_bf16_f32 v5, v30, v31
	global_store_dwordx4 v[8:9], v[2:5], off offset:64
	s_cbranch_vccnz .LBB0_124
	s_andn2_b64 vcc, exec, s[20:21]
	s_cbranch_vccnz .LBB0_123
	s_barrier
	s_branch .LBB0_123

; #define PG8_STAGE(bufoff, gbase, voff) do { _Pragma("unroll") for (int _i = 0; _i < 2; ++_i) \
;         __builtin_amdgcn_global_load_lds((const unsigned*)((const char*)(gbase) + (voff)[_i]), (PG8_LAS unsigned*)(lds + (bufoff) + ldsw + _i * 8192), 16, 0, 0); } while (0)
; #define PG8_BAR __builtin_amdgcn_s_barrier()
; template <class Epi, class Sched, bool ALIGN_EPI = false, bool SP2 = false>
; __device__ __forceinline__ void gemm_phase(PG8_LAS unsigned char* lds, const Gemm g, const Sched& S, const Epi& E) {
;     int tid_ = threadIdx.x; asm volatile("" : "+v"(tid_));
;     const int tid = tid_, wid = __builtin_amdgcn_readfirstlane(tid >> 6), lane = tid & 63, wr = wid >> 2, wc = wid & 3, fr = lane & 15, fq = lane >> 4;
;     const int K = g.K, nt = K / BK;
;     unsigned voffA[2], voffB[2];
; #pragma unroll
;     for (int i = 0; i < 2; ++i) { int R, C; stage_rc(tid * 16 + i * 8192, R, C); const int Rb = Epi::PERM ? ((R & ~31) + perm32(R & 31)) : R;
;         voffA[i] = (unsigned)(R * K + C) * 2u; voffB[i] = (unsigned)(Rb * K + C) * 2u; }
;     const size_t kstep = (size_t)(BK * 2);
;     const size_t hstep = (size_t)HALF * K * 2;
;     const size_t tstep = 2 * hstep;
;     const unsigned ldsw = (unsigned)wid * 1024u;
;     const int aoff = lds_byte(wr * 64 + fr, fq * 8), boff = lds_byte(wc * 32 + fr, fq * 8);
;     ...
;     Unit cur, nxt; int ui = 0;
;     if (!S.next(0, cur)) return;
;     typedef unsigned long long u64x2_t __attribute__((ext_vector_type(2)));
;     f32x4 acc[2][2][4][2];
;     int rs_pm = -1, rs_tog = 0;
; #pragma unroll
;     for (int a = 0; a < 2; ++a)
; #pragma unroll
;         for (int b = 0; b < 2; ++b)
; #pragma unroll
;             for (int m = 0; m < 4; ++m)
; #pragma unroll
;                 for (int n = 0; n < 2; ++n) { unsigned long long lo_, hi_; asm volatile("v_mov_b64 %0, 0\n\tv_mov_b64 %1, 0" : "=v"(lo_), "=v"(hi_)); acc[a][b][m][n] = __builtin_bit_cast(f32x4, (u64x2_t){lo_, hi_}); }
;     bf16x8 At[4][2], B0[2][2], B1[2][2];
;     const char* cA = (const char*)g.A + (size_t)cur.pm * tstep; const char* cB = (const char*)g.Bt + (size_t)cur.pn * tstep;
;     S.a_ready(cur);
;     if constexpr (SP2) {
;         PG8_STAGE(PG8_SB(0, 0), cB, voffB); PG8_STAGE(PG8_SB(0, 1), cB + hstep, voffB); PG8_STAGE(PG8_SA(0, 0), cA, voffA); PG8_STAGE(PG8_SA(0, 1), cA + hstep, voffA);
;         if (wr == 1) PG8_BAR;
.LBB0_210:
	s_and_b64 vcc, exec, s[4:5]
	s_cbranch_vccz .LBB0_232
	v_readlane_b32 s4, v253, 12
	v_mov_b32_e32 v144, v230
	v_readlane_b32 s5, v253, 13
	s_andn2_b64 vcc, exec, s[4:5]
	v_readfirstlane_b32 s42, v144
	s_cbranch_vccnz .LBB0_231
	v_lshlrev_b32_e32 v0, 4, v144
	v_add_u32_e32 v2, 0x2000, v0
	v_ashrrev_i32_e32 v3, 31, v2
	v_lshrrev_b32_e32 v3, 22, v3
	v_add_u32_e32 v3, v2, v3
	v_ashrrev_i32_e32 v145, 10, v3
	v_mul_i32_i24_e32 v3, 0x400, v145
	v_sub_u32_e32 v2, v2, v3
	v_lshrrev_b32_e32 v3, 4, v2
	v_bitop3_b32 v2, v3, v2, 32 bitop3:0x6c
	v_ashrrev_i32_e32 v3, 31, v2
	v_lshrrev_b32_e32 v3, 26, v3
	v_add_u32_e32 v3, v2, v3
	v_lshlrev_b32_e32 v4, 3, v145
	v_ashrrev_i32_e32 v146, 6, v3
	v_and_b32_e32 v4, -16, v4
	v_add_u32_e32 v4, v146, v4
	v_and_b32_e32 v5, 3, v146
	s_mov_b32 s8, 0x1fffe0
	v_lshrrev_b32_e32 v6, 2, v4
	v_lshlrev_b32_e32 v7, 1, v4
	v_and_b32_e32 v3, 0xc0, v3
	v_and_or_b32 v5, v4, s8, v5
	v_and_b32_e32 v6, 4, v6
	v_and_b32_e32 v7, 24, v7
	v_sub_u32_e32 v2, v2, v3
	v_or3_b32 v5, v5, v6, v7
	v_lshlrev_b32_e32 v6, 5, v145
	v_ashrrev_i16_sdwa v2, v244, sext(v2) dst_sel:DWORD dst_unused:UNUSED_PAD src0_sel:DWORD src1_sel:BYTE_0
	v_and_b32_e32 v6, 32, v6
	v_bfe_i32 v147, v2, 0, 16
	v_add_lshl_u32 v2, v6, v147, 1
	v_lshl_add_u32 v130, v5, 11, v2
	v_lshl_add_u32 v132, v4, 11, v2
	v_bfe_i32 v2, v144, 27, 1
	v_lshrrev_b32_e32 v2, 22, v2
	v_add_u32_e32 v2, v0, v2
	v_and_b32_e32 v2, 0xfffffc00, v2
	v_sub_u32_e32 v0, v0, v2
	s_waitcnt lgkmcnt(0)
	s_add_u32 s4, s14, 0x10000000
	v_lshrrev_b32_e32 v2, 4, v0
	v_ashrrev_i32_e32 v3, 31, v144
	s_addc_u32 s5, s15, 0
	v_bitop3_b32 v0, v2, v0, 32 bitop3:0x6c
	v_lshrrev_b32_e32 v3, 26, v3
	s_cmp_eq_u32 s88, 4
	v_ashrrev_i32_e32 v2, 31, v0
	v_add_u32_e32 v3, v144, v3
	s_cselect_b64 s[20:21], -1, 0
	v_lshrrev_b32_e32 v2, 26, v2
	v_ashrrev_i32_e32 v149, 6, v3
	s_and_b64 s[6:7], s[20:21], exec
	v_add_u32_e32 v2, v0, v2
	v_lshlrev_b32_e32 v3, 3, v149
	s_mov_b32 s6, 0x1500000
	v_ashrrev_i32_e32 v148, 6, v2
	v_and_b32_e32 v3, -16, v3
	s_cselect_b32 s6, s6, 0x2000000
	v_add_u32_e32 v3, v148, v3
	s_add_u32 s6, s14, s6
	v_and_b32_e32 v4, 3, v148
	v_lshrrev_b32_e32 v5, 2, v3
	v_lshlrev_b32_e32 v6, 1, v3
	v_and_b32_e32 v2, 0xc0, v2
	s_addc_u32 s7, s15, 0
	s_ashr_i32 s44, s42, 6
	v_and_or_b32 v4, v3, s8, v4
	v_and_b32_e32 v5, 4, v5
	v_and_b32_e32 v6, 24, v6
	v_sub_u32_e32 v0, v0, v2
	s_ashr_i32 s43, s42, 8
	s_lshl_b32 s27, s44, 10
	v_or3_b32 v4, v4, v5, v6
	v_lshlrev_b32_e32 v5, 5, v149
	v_ashrrev_i16_sdwa v0, v244, sext(v0) dst_sel:DWORD dst_unused:UNUSED_PAD src0_sel:DWORD src1_sel:BYTE_0
	v_readlane_b32 s8, v254, 14
	v_and_b32_e32 v5, 32, v5
	v_bfe_i32 v150, v0, 0, 16
	v_readlane_b32 s9, v254, 15
	s_add_u32 s56, s6, s8
	v_add_lshl_u32 v2, v5, v150, 1
	s_addc_u32 s57, s7, s9
	s_add_i32 s29, s27, 0
	v_lshl_add_u32 v0, v4, 11, v2
	s_add_i32 m0, s29, 0x10000
	v_lshl_add_u32 v134, v3, 11, v2
	s_waitcnt vmcnt(0)
	global_load_lds_dwordx4 v0, s[56:57]
	s_add_i32 m0, s29, 0x12000
	s_add_u32 s8, s56, 0x40000
	global_load_lds_dwordx4 v130, s[56:57]
	s_addc_u32 s9, s57, 0
	s_add_i32 m0, s29, 0x14000
	v_mov_b32_e32 v131, v1
	global_load_lds_dwordx4 v0, s[8:9]
	s_add_i32 m0, s29, 0x16000
	v_mov_b32_e32 v135, v1
	global_load_lds_dwordx4 v130, s[8:9]
	v_readlane_b32 s8, v254, 42
	v_readlane_b32 s9, v254, 43
	s_add_u32 s60, s4, s8
	s_addc_u32 s61, s5, s9
	s_add_i32 s33, s29, 0x2000
	s_mov_b32 m0, s29
	s_add_u32 s8, s60, 0x40000
	global_load_lds_dwordx4 v134, s[60:61]
	s_mov_b32 m0, s33
	s_addc_u32 s9, s61, 0
	s_add_i32 s58, s29, 0x4000
	global_load_lds_dwordx4 v132, s[60:61]
	s_mov_b32 m0, s58
	s_add_i32 s69, s29, 0x6000
	global_load_lds_dwordx4 v134, s[8:9]
	s_mov_b32 m0, s69
	v_mov_b32_e32 v133, v1
	global_load_lds_dwordx4 v132, s[8:9]
	s_cmp_eq_u32 s43, 1
	v_lshl_add_u64 v[142:143], s[56:57], 0, v[0:1]
	v_lshl_add_u64 v[140:141], s[56:57], 0, v[130:131]
	v_lshl_add_u64 v[136:137], s[60:61], 0, v[134:135]
	s_cselect_b64 s[8:9], -1, 0
	s_cmp_lg_u32 s43, 1
	v_lshl_add_u64 v[138:139], s[60:61], 0, v[132:133]
	s_cbranch_scc1 .LBB0_214
	s_barrier

; #define PG8_STAGE(bufoff, gbase, voff) do { _Pragma("unroll") for (int _i = 0; _i < 2; ++_i) \
;         __builtin_amdgcn_global_load_lds((const unsigned*)((const char*)(gbase) + (voff)[_i]), (PG8_LAS unsigned*)(lds + (bufoff) + ldsw + _i * 8192), 16, 0, 0); } while (0)
; #define PG8_LDA(dst, b, h) do { _Pragma("unroll") for (int m = 0; m < 4; ++m) _Pragma("unroll") for (int k = 0; k < 2; ++k) dst[m][k] = *(const PG8_LAS bf16x8*)(lds + PG8_SA(b, h) + aoff + m * 2048 + k * 1024); } while (0)
; #define PG8_LDB(dst, b, h) do { _Pragma("unroll") for (int n = 0; n < 2; ++n) _Pragma("unroll") for (int k = 0; k < 2; ++k) dst[n][k] = *(const PG8_LAS bf16x8*)(lds + PG8_SB(b, h) + boff + n * 2048 + k * 1024); } while (0)
; #define PG8_MMA(ai, bj, At, Bt) do { __builtin_amdgcn_s_setprio(1); _Pragma("unroll") for (int m = 0; m < 4; ++m) _Pragma("unroll") for (int n = 0; n < 2; ++n) _Pragma("unroll") for (int k = 0; k < 2; ++k) \
;         acc[ai][bj][m][n] = __builtin_amdgcn_mfma_f32_16x16x32_bf16(Bt[n][k], At[m][k], acc[ai][bj][m][n], 0, 0, 0); __builtin_amdgcn_s_setprio(0); } while (0)
; #define PG8_WAIT_V(n) asm volatile("s_waitcnt vmcnt(" #n ")" ::: "memory")
; #define PG8_WAIT_L(n) asm volatile("s_waitcnt lgkmcnt(" #n ")" ::: "memory")
; #define PG8_BAR __builtin_amdgcn_s_barrier()
; #define PG8_SCHED __builtin_amdgcn_sched_barrier(0)
; template <class Epi, class Sched, bool ALIGN_EPI = false, bool SP2 = false>
; __device__ __forceinline__ void gemm_phase(PG8_LAS unsigned char* lds, const Gemm g, const Sched& S, const Epi& E) {
;     ...
;             const bool last = (t == nt - 2);
;             const char* a1 = cA + (size_t)(t + 1) * kstep;
;             const char* a2 = last ? nA : cA + (size_t)(t + 2) * kstep; const char* b2 = last ? nB : cB + (size_t)(t + 2) * kstep;
;             const char* a3 = a2 + kstep; const char* b3 = b2 + kstep;
;             if (last && has_next) S.a_ready(nxt);
;             if constexpr (SP2) {
;             PG8_LDB(B0, 0, 0); PG8_LDB(B1, 0, 1); PG8_SCHED; PG8_LDA(At, 0, 0); PG8_STAGE(PG8_SA(1, 1), a1 + hstep, voffA);
;             PG8_WAIT_V(8); PG8_WAIT_L(0); PG8_BAR; PG8_MMA(0, 0, At, B0); PG8_MMA(0, 1, At, B1); PG8_BAR; PG8_SCHED;
.LBB0_220:
	s_add_u32 s18, s60, 0xfffc0080
	s_addc_u32 s38, s61, -1
	s_add_i32 s39, 0, 0x10000
	s_cmp_eq_u32 s82, 12
	s_cselect_b32 s65, s47, s38
	s_cselect_b32 s64, s78, s18
	v_add_u32_e32 v145, s39, v141
	s_cselect_b32 s57, s49, s81
	s_cselect_b32 s56, s79, s80
	s_add_i32 s18, 0, 0x14000
	ds_read_b128 v[146:149], v145
	ds_read_b128 v[150:153], v145 offset:1024
	ds_read_b128 v[154:157], v145 offset:2048
	ds_read_b128 v[158:161], v145 offset:3072
	v_add_u32_e32 v145, s18, v141
	ds_read_b128 v[162:165], v145
	ds_read_b128 v[166:169], v145 offset:1024
	ds_read_b128 v[170:173], v145 offset:2048
	ds_read_b128 v[174:177], v145 offset:3072
	v_lshl_add_u64 v[194:195], s[60:61], 0, v[136:137]
	s_add_i32 m0, s29, 0xc000
	ds_read_b128 v[178:181], v144
	ds_read_b128 v[182:185], v144 offset:1024
	ds_read_b128 v[186:189], v144 offset:2048
	ds_read_b128 v[190:193], v144 offset:3072
	ds_read_b128 v[202:205], v144 offset:4096
	ds_read_b128 v[206:209], v144 offset:5120
	ds_read_b128 v[210:213], v144 offset:6144
	ds_read_b128 v[214:217], v144 offset:7168
	global_load_lds_dwordx4 v[194:195], off
	v_lshl_add_u64 v[194:195], s[60:61], 0, v[138:139]
	s_add_i32 m0, s29, 0xe000
	s_nop 0
	global_load_lds_dwordx4 v[194:195], off
	s_waitcnt vmcnt(8)
	s_waitcnt lgkmcnt(0)
	s_barrier
	s_setprio 1
	s_cmp_eq_u32 s82, -2
	s_cbranch_scc1 .Lz220_0_first
	v_mfma_f32_16x16x32_bf16 v[114:117], v[146:149], v[178:181], v[114:117]
	v_mfma_f32_16x16x32_bf16 v[114:117], v[150:153], v[182:185], v[114:117]
	v_mfma_f32_16x16x32_bf16 v[98:101], v[146:149], v[186:189], v[98:101]
	v_mfma_f32_16x16x32_bf16 v[98:101], v[150:153], v[190:193], v[98:101]
	v_mfma_f32_16x16x32_bf16 v[82:85], v[146:149], v[202:205], v[82:85]
	v_mfma_f32_16x16x32_bf16 v[82:85], v[150:153], v[206:209], v[82:85]
	v_mfma_f32_16x16x32_bf16 v[66:69], v[146:149], v[210:213], v[66:69]
	v_mfma_f32_16x16x32_bf16 v[66:69], v[150:153], v[214:217], v[66:69]
	v_mfma_f32_16x16x32_bf16 v[118:121], v[154:157], v[178:181], v[118:121]
	v_mfma_f32_16x16x32_bf16 v[118:121], v[158:161], v[182:185], v[118:121]
	v_mfma_f32_16x16x32_bf16 v[102:105], v[154:157], v[186:189], v[102:105]
	v_mfma_f32_16x16x32_bf16 v[102:105], v[158:161], v[190:193], v[102:105]
	v_mfma_f32_16x16x32_bf16 v[86:89], v[154:157], v[202:205], v[86:89]
	v_mfma_f32_16x16x32_bf16 v[86:89], v[158:161], v[206:209], v[86:89]
	v_mfma_f32_16x16x32_bf16 v[70:73], v[154:157], v[210:213], v[70:73]
	v_mfma_f32_16x16x32_bf16 v[70:73], v[158:161], v[214:217], v[70:73]
	v_mfma_f32_16x16x32_bf16 v[122:125], v[162:165], v[178:181], v[122:125]
	v_mfma_f32_16x16x32_bf16 v[122:125], v[166:169], v[182:185], v[122:125]
	v_mfma_f32_16x16x32_bf16 v[106:109], v[162:165], v[186:189], v[106:109]
	v_mfma_f32_16x16x32_bf16 v[106:109], v[166:169], v[190:193], v[106:109]
	v_mfma_f32_16x16x32_bf16 v[90:93], v[162:165], v[202:205], v[90:93]
	v_mfma_f32_16x16x32_bf16 v[90:93], v[166:169], v[206:209], v[90:93]
	v_mfma_f32_16x16x32_bf16 v[74:77], v[162:165], v[210:213], v[74:77]
	v_mfma_f32_16x16x32_bf16 v[74:77], v[166:169], v[214:217], v[74:77]
	v_mfma_f32_16x16x32_bf16 v[126:129], v[170:173], v[178:181], v[126:129]
	v_mfma_f32_16x16x32_bf16 v[126:129], v[174:177], v[182:185], v[126:129]
	v_mfma_f32_16x16x32_bf16 v[110:113], v[170:173], v[186:189], v[110:113]
	v_mfma_f32_16x16x32_bf16 v[110:113], v[174:177], v[190:193], v[110:113]
	v_mfma_f32_16x16x32_bf16 v[94:97], v[170:173], v[202:205], v[94:97]
	v_mfma_f32_16x16x32_bf16 v[94:97], v[174:177], v[206:209], v[94:97]
	v_mfma_f32_16x16x32_bf16 v[78:81], v[170:173], v[210:213], v[78:81]
	v_mfma_f32_16x16x32_bf16 v[78:81], v[174:177], v[214:217], v[78:81]
	s_branch .Lz220_0_join
.Lz220_0_first:
	v_mfma_f32_16x16x32_bf16 v[114:117], v[146:149], v[178:181], 0
	v_mfma_f32_16x16x32_bf16 v[114:117], v[150:153], v[182:185], v[114:117]
	v_mfma_f32_16x16x32_bf16 v[98:101], v[146:149], v[186:189], 0
	v_mfma_f32_16x16x32_bf16 v[98:101], v[150:153], v[190:193], v[98:101]
	v_mfma_f32_16x16x32_bf16 v[82:85], v[146:149], v[202:205], 0
	v_mfma_f32_16x16x32_bf16 v[82:85], v[150:153], v[206:209], v[82:85]
	v_mfma_f32_16x16x32_bf16 v[66:69], v[146:149], v[210:213], 0
	v_mfma_f32_16x16x32_bf16 v[66:69], v[150:153], v[214:217], v[66:69]
	v_mfma_f32_16x16x32_bf16 v[118:121], v[154:157], v[178:181], 0
	v_mfma_f32_16x16x32_bf16 v[118:121], v[158:161], v[182:185], v[118:121]
	v_mfma_f32_16x16x32_bf16 v[102:105], v[154:157], v[186:189], 0
	v_mfma_f32_16x16x32_bf16 v[102:105], v[158:161], v[190:193], v[102:105]
	v_mfma_f32_16x16x32_bf16 v[86:89], v[154:157], v[202:205], 0
	v_mfma_f32_16x16x32_bf16 v[86:89], v[158:161], v[206:209], v[86:89]
	v_mfma_f32_16x16x32_bf16 v[70:73], v[154:157], v[210:213], 0
	v_mfma_f32_16x16x32_bf16 v[70:73], v[158:161], v[214:217], v[70:73]
	v_mfma_f32_16x16x32_bf16 v[122:125], v[162:165], v[178:181], 0
	v_mfma_f32_16x16x32_bf16 v[122:125], v[166:169], v[182:185], v[122:125]
	v_mfma_f32_16x16x32_bf16 v[106:109], v[162:165], v[186:189], 0
	v_mfma_f32_16x16x32_bf16 v[106:109], v[166:169], v[190:193], v[106:109]
	v_mfma_f32_16x16x32_bf16 v[90:93], v[162:165], v[202:205], 0
	v_mfma_f32_16x16x32_bf16 v[90:93], v[166:169], v[206:209], v[90:93]
	v_mfma_f32_16x16x32_bf16 v[74:77], v[162:165], v[210:213], 0
	v_mfma_f32_16x16x32_bf16 v[74:77], v[166:169], v[214:217], v[74:77]
	v_mfma_f32_16x16x32_bf16 v[126:129], v[170:173], v[178:181], 0
	v_mfma_f32_16x16x32_bf16 v[126:129], v[174:177], v[182:185], v[126:129]
	v_mfma_f32_16x16x32_bf16 v[110:113], v[170:173], v[186:189], 0
	v_mfma_f32_16x16x32_bf16 v[110:113], v[174:177], v[190:193], v[110:113]
	v_mfma_f32_16x16x32_bf16 v[94:97], v[170:173], v[202:205], 0
	v_mfma_f32_16x16x32_bf16 v[94:97], v[174:177], v[206:209], v[94:97]
	v_mfma_f32_16x16x32_bf16 v[78:81], v[170:173], v[210:213], 0
	v_mfma_f32_16x16x32_bf16 v[78:81], v[174:177], v[214:217], v[78:81]
; #define PG8_STAGE(bufoff, gbase, voff) do { _Pragma("unroll") for (int _i = 0; _i < 2; ++_i) \
;         __builtin_amdgcn_global_load_lds((const unsigned*)((const char*)(gbase) + (voff)[_i]), (PG8_LAS unsigned*)(lds + (bufoff) + ldsw + _i * 8192), 16, 0, 0); } while (0)
; #define PG8_LDA(dst, b, h) do { _Pragma("unroll") for (int m = 0; m < 4; ++m) _Pragma("unroll") for (int k = 0; k < 2; ++k) dst[m][k] = *(const PG8_LAS bf16x8*)(lds + PG8_SA(b, h) + aoff + m * 2048 + k * 1024); } while (0)
; #define PG8_MMA(ai, bj, At, Bt) do { __builtin_amdgcn_s_setprio(1); _Pragma("unroll") for (int m = 0; m < 4; ++m) _Pragma("unroll") for (int n = 0; n < 2; ++n) _Pragma("unroll") for (int k = 0; k < 2; ++k) \
;         acc[ai][bj][m][n] = __builtin_amdgcn_mfma_f32_16x16x32_bf16(Bt[n][k], At[m][k], acc[ai][bj][m][n], 0, 0, 0); __builtin_amdgcn_s_setprio(0); } while (0)
; #define PG8_WAIT_V(n) asm volatile("s_waitcnt vmcnt(" #n ")" ::: "memory")
; #define PG8_WAIT_L(n) asm volatile("s_waitcnt lgkmcnt(" #n ")" ::: "memory")
; #define PG8_BAR __builtin_amdgcn_s_barrier()
; #define PG8_SCHED __builtin_amdgcn_sched_barrier(0)
; template <class Epi, class Sched, bool ALIGN_EPI = false, bool SP2 = false>
; __device__ __forceinline__ void gemm_phase(PG8_LAS unsigned char* lds, const Gemm g, const Sched& S, const Epi& E) {
;     ...
;             PG8_LDA(At, 0, 1); PG8_STAGE(PG8_SB(0, 0), b2, voffB); PG8_STAGE(PG8_SB(0, 1), b2 + hstep, voffB); PG8_STAGE(PG8_SA(0, 0), a2, voffA);
;             PG8_WAIT_V(8); PG8_WAIT_L(0); PG8_BAR; PG8_MMA(1, 0, At, B0); PG8_MMA(1, 1, At, B1); PG8_BAR; PG8_SCHED;
.Lz220_0_join:
	s_setprio 0
	s_barrier
	s_add_i32 s38, s39, s27
	v_lshl_add_u64 v[194:195], s[56:57], 0, v[0:1]
	s_mov_b32 m0, s38
	ds_read_b128 v[178:181], v144 offset:16384
	ds_read_b128 v[182:185], v144 offset:17408
	ds_read_b128 v[186:189], v144 offset:18432
	ds_read_b128 v[190:193], v144 offset:19456
	ds_read_b128 v[202:205], v144 offset:20480
	ds_read_b128 v[206:209], v144 offset:21504
	ds_read_b128 v[210:213], v144 offset:22528
	ds_read_b128 v[214:217], v144 offset:23552
	global_load_lds_dwordx4 v[194:195], off
	s_add_i32 m0, s38, 0x2000
	s_add_u32 s38, s56, 0x40000
	v_lshl_add_u64 v[218:219], s[56:57], 0, v[130:131]
	s_addc_u32 s39, s57, 0
	s_add_i32 s18, s18, s27
	global_load_lds_dwordx4 v[218:219], off
	v_lshl_add_u64 v[220:221], s[38:39], 0, v[0:1]
	s_mov_b32 m0, s18
	v_lshl_add_u64 v[222:223], s[64:65], 0, v[132:133]
	global_load_lds_dwordx4 v[220:221], off
	v_lshl_add_u64 v[220:221], s[38:39], 0, v[130:131]
	s_add_i32 m0, s18, 0x2000
	s_nop 0
	global_load_lds_dwordx4 v[220:221], off
	v_lshl_add_u64 v[220:221], s[64:65], 0, v[134:135]
	s_mov_b32 m0, s29
	s_nop 0
	global_load_lds_dwordx4 v[220:221], off
	s_mov_b32 m0, s33
	s_nop 0
	global_load_lds_dwordx4 v[222:223], off
	s_waitcnt vmcnt(8)
	s_waitcnt lgkmcnt(0)
	s_barrier
	s_setprio 1
	s_cmp_eq_u32 s82, -2
	s_cbranch_scc1 .Lz220_1_first
	v_mfma_f32_16x16x32_bf16 v[50:53], v[146:149], v[178:181], v[50:53]
	v_mfma_f32_16x16x32_bf16 v[50:53], v[150:153], v[182:185], v[50:53]
	v_mfma_f32_16x16x32_bf16 v[34:37], v[146:149], v[186:189], v[34:37]
	v_mfma_f32_16x16x32_bf16 v[34:37], v[150:153], v[190:193], v[34:37]
	v_mfma_f32_16x16x32_bf16 v[18:21], v[146:149], v[202:205], v[18:21]
	v_mfma_f32_16x16x32_bf16 v[18:21], v[150:153], v[206:209], v[18:21]
	v_mfma_f32_16x16x32_bf16 v[2:5], v[146:149], v[210:213], v[2:5]
	v_mfma_f32_16x16x32_bf16 v[2:5], v[150:153], v[214:217], v[2:5]
	v_mfma_f32_16x16x32_bf16 v[54:57], v[154:157], v[178:181], v[54:57]
	v_mfma_f32_16x16x32_bf16 v[54:57], v[158:161], v[182:185], v[54:57]
	v_mfma_f32_16x16x32_bf16 v[38:41], v[154:157], v[186:189], v[38:41]
	v_mfma_f32_16x16x32_bf16 v[38:41], v[158:161], v[190:193], v[38:41]
	v_mfma_f32_16x16x32_bf16 v[22:25], v[154:157], v[202:205], v[22:25]
	v_mfma_f32_16x16x32_bf16 v[22:25], v[158:161], v[206:209], v[22:25]
	v_mfma_f32_16x16x32_bf16 v[6:9], v[154:157], v[210:213], v[6:9]
	v_mfma_f32_16x16x32_bf16 v[6:9], v[158:161], v[214:217], v[6:9]
	v_mfma_f32_16x16x32_bf16 v[58:61], v[162:165], v[178:181], v[58:61]
	v_mfma_f32_16x16x32_bf16 v[58:61], v[166:169], v[182:185], v[58:61]
	v_mfma_f32_16x16x32_bf16 v[42:45], v[162:165], v[186:189], v[42:45]
	v_mfma_f32_16x16x32_bf16 v[42:45], v[166:169], v[190:193], v[42:45]
	v_mfma_f32_16x16x32_bf16 v[26:29], v[162:165], v[202:205], v[26:29]
	v_mfma_f32_16x16x32_bf16 v[26:29], v[166:169], v[206:209], v[26:29]
	v_mfma_f32_16x16x32_bf16 v[10:13], v[162:165], v[210:213], v[10:13]
	v_mfma_f32_16x16x32_bf16 v[10:13], v[166:169], v[214:217], v[10:13]
	v_mfma_f32_16x16x32_bf16 v[62:65], v[170:173], v[178:181], v[62:65]
	v_mfma_f32_16x16x32_bf16 v[62:65], v[174:177], v[182:185], v[62:65]
	v_mfma_f32_16x16x32_bf16 v[46:49], v[170:173], v[186:189], v[46:49]
	v_mfma_f32_16x16x32_bf16 v[46:49], v[174:177], v[190:193], v[46:49]
	v_mfma_f32_16x16x32_bf16 v[30:33], v[170:173], v[202:205], v[30:33]
	v_mfma_f32_16x16x32_bf16 v[30:33], v[174:177], v[206:209], v[30:33]
	v_mfma_f32_16x16x32_bf16 v[14:17], v[170:173], v[210:213], v[14:17]
	v_mfma_f32_16x16x32_bf16 v[14:17], v[174:177], v[214:217], v[14:17]
	s_branch .Lz220_1_join
.Lz220_1_first:
	v_mfma_f32_16x16x32_bf16 v[50:53], v[146:149], v[178:181], 0
	v_mfma_f32_16x16x32_bf16 v[50:53], v[150:153], v[182:185], v[50:53]
	v_mfma_f32_16x16x32_bf16 v[34:37], v[146:149], v[186:189], 0
	v_mfma_f32_16x16x32_bf16 v[34:37], v[150:153], v[190:193], v[34:37]
	v_mfma_f32_16x16x32_bf16 v[18:21], v[146:149], v[202:205], 0
	v_mfma_f32_16x16x32_bf16 v[18:21], v[150:153], v[206:209], v[18:21]
	v_mfma_f32_16x16x32_bf16 v[2:5], v[146:149], v[210:213], 0
	v_mfma_f32_16x16x32_bf16 v[2:5], v[150:153], v[214:217], v[2:5]
	v_mfma_f32_16x16x32_bf16 v[54:57], v[154:157], v[178:181], 0
	v_mfma_f32_16x16x32_bf16 v[54:57], v[158:161], v[182:185], v[54:57]
	v_mfma_f32_16x16x32_bf16 v[38:41], v[154:157], v[186:189], 0
	v_mfma_f32_16x16x32_bf16 v[38:41], v[158:161], v[190:193], v[38:41]
	v_mfma_f32_16x16x32_bf16 v[22:25], v[154:157], v[202:205], 0
	v_mfma_f32_16x16x32_bf16 v[22:25], v[158:161], v[206:209], v[22:25]
	v_mfma_f32_16x16x32_bf16 v[6:9], v[154:157], v[210:213], 0
	v_mfma_f32_16x16x32_bf16 v[6:9], v[158:161], v[214:217], v[6:9]
	v_mfma_f32_16x16x32_bf16 v[58:61], v[162:165], v[178:181], 0
	v_mfma_f32_16x16x32_bf16 v[58:61], v[166:169], v[182:185], v[58:61]
	v_mfma_f32_16x16x32_bf16 v[42:45], v[162:165], v[186:189], 0
	v_mfma_f32_16x16x32_bf16 v[42:45], v[166:169], v[190:193], v[42:45]
	v_mfma_f32_16x16x32_bf16 v[26:29], v[162:165], v[202:205], 0
	v_mfma_f32_16x16x32_bf16 v[26:29], v[166:169], v[206:209], v[26:29]
	v_mfma_f32_16x16x32_bf16 v[10:13], v[162:165], v[210:213], 0
	v_mfma_f32_16x16x32_bf16 v[10:13], v[166:169], v[214:217], v[10:13]
	v_mfma_f32_16x16x32_bf16 v[62:65], v[170:173], v[178:181], 0
	v_mfma_f32_16x16x32_bf16 v[62:65], v[174:177], v[182:185], v[62:65]
	v_mfma_f32_16x16x32_bf16 v[46:49], v[170:173], v[186:189], 0
	v_mfma_f32_16x16x32_bf16 v[46:49], v[174:177], v[190:193], v[46:49]
	v_mfma_f32_16x16x32_bf16 v[30:33], v[170:173], v[202:205], 0
	v_mfma_f32_16x16x32_bf16 v[30:33], v[174:177], v[206:209], v[30:33]
	v_mfma_f32_16x16x32_bf16 v[14:17], v[170:173], v[210:213], 0
	v_mfma_f32_16x16x32_bf16 v[14:17], v[174:177], v[214:217], v[14:17]
; #define PG8_STAGE(bufoff, gbase, voff) do { _Pragma("unroll") for (int _i = 0; _i < 2; ++_i) \
;         __builtin_amdgcn_global_load_lds((const unsigned*)((const char*)(gbase) + (voff)[_i]), (PG8_LAS unsigned*)(lds + (bufoff) + ldsw + _i * 8192), 16, 0, 0); } while (0)
; #define PG8_LDA(dst, b, h) do { _Pragma("unroll") for (int m = 0; m < 4; ++m) _Pragma("unroll") for (int k = 0; k < 2; ++k) dst[m][k] = *(const PG8_LAS bf16x8*)(lds + PG8_SA(b, h) + aoff + m * 2048 + k * 1024); } while (0)
; #define PG8_LDB(dst, b, h) do { _Pragma("unroll") for (int n = 0; n < 2; ++n) _Pragma("unroll") for (int k = 0; k < 2; ++k) dst[n][k] = *(const PG8_LAS bf16x8*)(lds + PG8_SB(b, h) + boff + n * 2048 + k * 1024); } while (0)
; #define PG8_MMA(ai, bj, At, Bt) do { __builtin_amdgcn_s_setprio(1); _Pragma("unroll") for (int m = 0; m < 4; ++m) _Pragma("unroll") for (int n = 0; n < 2; ++n) _Pragma("unroll") for (int k = 0; k < 2; ++k) \
;         acc[ai][bj][m][n] = __builtin_amdgcn_mfma_f32_16x16x32_bf16(Bt[n][k], At[m][k], acc[ai][bj][m][n], 0, 0, 0); __builtin_amdgcn_s_setprio(0); } while (0)
; #define PG8_WAIT_V(n) asm volatile("s_waitcnt vmcnt(" #n ")" ::: "memory")
; #define PG8_WAIT_L(n) asm volatile("s_waitcnt lgkmcnt(" #n ")" ::: "memory")
; #define PG8_BAR __builtin_amdgcn_s_barrier()
; #define PG8_SCHED __builtin_amdgcn_sched_barrier(0)
; template <class Epi, class Sched, bool ALIGN_EPI = false, bool SP2 = false>
; __device__ __forceinline__ void gemm_phase(PG8_LAS unsigned char* lds, const Gemm g, const Sched& S, const Epi& E) {
;     ...
;             PG8_WAIT_V(8); PG8_WAIT_L(0); PG8_BAR; PG8_MMA(1, 0, At, B0); PG8_MMA(1, 1, At, B1); PG8_BAR; PG8_SCHED;
;             PG8_LDB(B0, 1, 0); PG8_LDB(B1, 1, 1); PG8_SCHED; PG8_LDA(At, 1, 0); PG8_STAGE(PG8_SA(0, 1), a2 + hstep, voffA);
;             PG8_WAIT_V(8); PG8_WAIT_L(0); PG8_BAR; PG8_MMA(0, 0, At, B0); PG8_MMA(0, 1, At, B1); PG8_BAR; PG8_SCHED;
.Lz220_1_join:
	s_setprio 0
	s_barrier
	s_add_i32 s18, 0, 0x18000
	v_add_u32_e32 v145, s18, v141
	s_add_i32 s83, 0, 0x1c000
	ds_read_b128 v[146:149], v145
	ds_read_b128 v[150:153], v145 offset:1024
	ds_read_b128 v[154:157], v145 offset:2048
	ds_read_b128 v[158:161], v145 offset:3072
	v_add_u32_e32 v145, s83, v141
	ds_read_b128 v[162:165], v145
	ds_read_b128 v[166:169], v145 offset:1024
	ds_read_b128 v[170:173], v145 offset:2048
	ds_read_b128 v[174:177], v145 offset:3072
	s_add_u32 s38, s64, 0x40000
	s_addc_u32 s39, s65, 0
	s_mov_b32 m0, s58
	v_lshl_add_u64 v[224:225], s[38:39], 0, v[134:135]
	ds_read_b128 v[178:181], v144 offset:32768
	ds_read_b128 v[182:185], v144 offset:33792
	ds_read_b128 v[186:189], v144 offset:34816
	ds_read_b128 v[190:193], v144 offset:35840
	ds_read_b128 v[202:205], v144 offset:36864
	ds_read_b128 v[206:209], v144 offset:37888
	ds_read_b128 v[210:213], v144 offset:38912
	ds_read_b128 v[214:217], v144 offset:39936
	global_load_lds_dwordx4 v[224:225], off
	v_lshl_add_u64 v[224:225], s[38:39], 0, v[132:133]
	s_mov_b32 m0, s69
	s_nop 0
	global_load_lds_dwordx4 v[224:225], off
	s_waitcnt vmcnt(8)
	s_waitcnt lgkmcnt(0)
	s_barrier
	s_setprio 1
	v_mfma_f32_16x16x32_bf16 v[114:117], v[146:149], v[178:181], v[114:117]
	v_mfma_f32_16x16x32_bf16 v[114:117], v[150:153], v[182:185], v[114:117]
	v_mfma_f32_16x16x32_bf16 v[98:101], v[146:149], v[186:189], v[98:101]
	v_mfma_f32_16x16x32_bf16 v[98:101], v[150:153], v[190:193], v[98:101]
	v_mfma_f32_16x16x32_bf16 v[82:85], v[146:149], v[202:205], v[82:85]
	v_mfma_f32_16x16x32_bf16 v[82:85], v[150:153], v[206:209], v[82:85]
	v_mfma_f32_16x16x32_bf16 v[66:69], v[146:149], v[210:213], v[66:69]
	v_mfma_f32_16x16x32_bf16 v[66:69], v[150:153], v[214:217], v[66:69]
	v_mfma_f32_16x16x32_bf16 v[118:121], v[154:157], v[178:181], v[118:121]
	v_mfma_f32_16x16x32_bf16 v[118:121], v[158:161], v[182:185], v[118:121]
	v_mfma_f32_16x16x32_bf16 v[102:105], v[154:157], v[186:189], v[102:105]
	v_mfma_f32_16x16x32_bf16 v[102:105], v[158:161], v[190:193], v[102:105]
	v_mfma_f32_16x16x32_bf16 v[86:89], v[154:157], v[202:205], v[86:89]
	v_mfma_f32_16x16x32_bf16 v[86:89], v[158:161], v[206:209], v[86:89]
	v_mfma_f32_16x16x32_bf16 v[70:73], v[154:157], v[210:213], v[70:73]
	v_mfma_f32_16x16x32_bf16 v[70:73], v[158:161], v[214:217], v[70:73]
	v_mfma_f32_16x16x32_bf16 v[122:125], v[162:165], v[178:181], v[122:125]
	v_mfma_f32_16x16x32_bf16 v[122:125], v[166:169], v[182:185], v[122:125]
	v_mfma_f32_16x16x32_bf16 v[106:109], v[162:165], v[186:189], v[106:109]
	v_mfma_f32_16x16x32_bf16 v[106:109], v[166:169], v[190:193], v[106:109]
	v_mfma_f32_16x16x32_bf16 v[90:93], v[162:165], v[202:205], v[90:93]
	v_mfma_f32_16x16x32_bf16 v[90:93], v[166:169], v[206:209], v[90:93]
	v_mfma_f32_16x16x32_bf16 v[74:77], v[162:165], v[210:213], v[74:77]
	v_mfma_f32_16x16x32_bf16 v[74:77], v[166:169], v[214:217], v[74:77]
	v_mfma_f32_16x16x32_bf16 v[126:129], v[170:173], v[178:181], v[126:129]
	v_mfma_f32_16x16x32_bf16 v[126:129], v[174:177], v[182:185], v[126:129]
	v_mfma_f32_16x16x32_bf16 v[110:113], v[170:173], v[186:189], v[110:113]
	v_mfma_f32_16x16x32_bf16 v[110:113], v[174:177], v[190:193], v[110:113]
	v_mfma_f32_16x16x32_bf16 v[94:97], v[170:173], v[202:205], v[94:97]
	v_mfma_f32_16x16x32_bf16 v[94:97], v[174:177], v[206:209], v[94:97]
	v_mfma_f32_16x16x32_bf16 v[78:81], v[170:173], v[210:213], v[78:81]
	v_mfma_f32_16x16x32_bf16 v[78:81], v[174:177], v[214:217], v[78:81]
	s_setprio 0
	s_barrier
; #define PG8_STAGE(bufoff, gbase, voff) do { _Pragma("unroll") for (int _i = 0; _i < 2; ++_i) \
;         __builtin_amdgcn_global_load_lds((const unsigned*)((const char*)(gbase) + (voff)[_i]), (PG8_LAS unsigned*)(lds + (bufoff) + ldsw + _i * 8192), 16, 0, 0); } while (0)
; #define PG8_LDA(dst, b, h) do { _Pragma("unroll") for (int m = 0; m < 4; ++m) _Pragma("unroll") for (int k = 0; k < 2; ++k) dst[m][k] = *(const PG8_LAS bf16x8*)(lds + PG8_SA(b, h) + aoff + m * 2048 + k * 1024); } while (0)
; #define PG8_WAIT_V(n) asm volatile("s_waitcnt vmcnt(" #n ")" ::: "memory")
; template <class Epi, class Sched, bool ALIGN_EPI = false, bool SP2 = false>
; __device__ __forceinline__ void gemm_phase(PG8_LAS unsigned char* lds, const Gemm g, const Sched& S, const Epi& E) {
;     ...
;             PG8_LDA(At, 1, 1); PG8_STAGE(PG8_SB(1, 0), b3, voffB); PG8_STAGE(PG8_SB(1, 1), b3 + hstep, voffB); PG8_STAGE(PG8_SA(1, 0), a3, voffA);
;             PG8_WAIT_V(8); PG8_WAIT_L(0); PG8_BAR; PG8_MMA(1, 0, At, B0); PG8_MMA(1, 1, At, B1); PG8_BAR; PG8_SCHED;
;             } else {
;             PG8_LDB(B0, 0, 0); PG8_SCHED; PG8_LDA(At, 0, 0); PG8_STAGE(PG8_SA(1, 1), a1 + hstep, voffA);
;             PG8_WAIT_L(8); PG8_BAR; PG8_WAIT_L(0); PG8_MMA(0, 0, At, B0); PG8_BAR; PG8_SCHED;
;             PG8_LDB(B1, 0, 1); PG8_STAGE(PG8_SB(0, 0), b2, voffB);
;             PG8_BAR; PG8_WAIT_L(0); PG8_MMA(0, 1, At, B1); PG8_BAR;
;             PG8_LDA(At, 0, 1); PG8_STAGE(PG8_SA(0, 0), a2, voffA);
;             PG8_BAR; PG8_WAIT_L(0); PG8_MMA(1, 0, At, B0); PG8_BAR; PG8_SCHED;
;             PG8_STAGE(PG8_SB(0, 1), b2 + hstep, voffB);
;             PG8_WAIT_V(6); PG8_BAR; PG8_MMA(1, 1, At, B1); PG8_BAR;
;             PG8_LDB(B0, 1, 0); PG8_SCHED; PG8_LDA(At, 1, 0); PG8_STAGE(PG8_SA(0, 1), a2 + hstep, voffA);
;             PG8_WAIT_L(8); PG8_BAR; PG8_WAIT_L(0); PG8_MMA(0, 0, At, B0); PG8_BAR; PG8_SCHED;
;             PG8_LDB(B1, 1, 1); PG8_STAGE(PG8_SB(1, 0), b3, voffB);
;             PG8_BAR; PG8_WAIT_L(0); PG8_MMA(0, 1, At, B1); PG8_BAR;
;             PG8_LDA(At, 1, 1); PG8_STAGE(PG8_SA(1, 0), a3, voffA);
;             PG8_BAR; PG8_WAIT_L(0); PG8_MMA(1, 0, At, B0); PG8_BAR; PG8_SCHED;
;             PG8_STAGE(PG8_SB(1, 1), b3 + hstep, voffB);
;             PG8_WAIT_V(6); PG8_BAR; PG8_MMA(1, 1, At, B1); PG8_BAR;
;             }
;         }
;         if constexpr (ALIGN_EPI) { if (wr == 0) PG8_BAR; }
	s_add_i32 s18, s18, s27
	v_lshl_add_u64 v[194:195], v[194:195], 0, s[30:31]
	s_mov_b32 m0, s18
	ds_read_b128 v[178:181], v144 offset:49152
	ds_read_b128 v[182:185], v144 offset:50176
	ds_read_b128 v[186:189], v144 offset:51200
	ds_read_b128 v[190:193], v144 offset:52224
	ds_read_b128 v[202:205], v144 offset:53248
	ds_read_b128 v[206:209], v144 offset:54272
	ds_read_b128 v[210:213], v144 offset:55296
	ds_read_b128 v[214:217], v144 offset:56320
	global_load_lds_dwordx4 v[194:195], off
	s_add_i32 m0, s18, 0x2000
	s_add_u32 s38, s56, 0x40080
	v_lshl_add_u64 v[194:195], v[218:219], 0, s[30:31]
	s_addc_u32 s39, s57, 0
	s_add_i32 s18, s83, s27
	global_load_lds_dwordx4 v[194:195], off
	v_lshl_add_u64 v[194:195], s[38:39], 0, v[0:1]
	s_mov_b32 m0, s18
	s_nop 0
	global_load_lds_dwordx4 v[194:195], off
	v_lshl_add_u64 v[194:195], s[38:39], 0, v[130:131]
	s_add_i32 m0, s18, 0x2000
	s_nop 0
	global_load_lds_dwordx4 v[194:195], off
	v_lshl_add_u64 v[194:195], v[220:221], 0, s[30:31]
	s_mov_b32 m0, s71
	s_nop 0
	global_load_lds_dwordx4 v[194:195], off
	v_lshl_add_u64 v[194:195], v[222:223], 0, s[30:31]
	s_mov_b32 m0, s72
	s_nop 0
	global_load_lds_dwordx4 v[194:195], off
	s_waitcnt vmcnt(8)
	s_waitcnt lgkmcnt(0)
	s_barrier
	s_setprio 1
	v_mfma_f32_16x16x32_bf16 v[50:53], v[146:149], v[178:181], v[50:53]
	v_mfma_f32_16x16x32_bf16 v[50:53], v[150:153], v[182:185], v[50:53]
	v_mfma_f32_16x16x32_bf16 v[34:37], v[146:149], v[186:189], v[34:37]
	v_mfma_f32_16x16x32_bf16 v[34:37], v[150:153], v[190:193], v[34:37]
	v_mfma_f32_16x16x32_bf16 v[18:21], v[146:149], v[202:205], v[18:21]
	v_mfma_f32_16x16x32_bf16 v[18:21], v[150:153], v[206:209], v[18:21]
	v_mfma_f32_16x16x32_bf16 v[2:5], v[146:149], v[210:213], v[2:5]
	v_mfma_f32_16x16x32_bf16 v[2:5], v[150:153], v[214:217], v[2:5]
	v_mfma_f32_16x16x32_bf16 v[54:57], v[154:157], v[178:181], v[54:57]
	v_mfma_f32_16x16x32_bf16 v[54:57], v[158:161], v[182:185], v[54:57]
	v_mfma_f32_16x16x32_bf16 v[38:41], v[154:157], v[186:189], v[38:41]
	v_mfma_f32_16x16x32_bf16 v[38:41], v[158:161], v[190:193], v[38:41]
	v_mfma_f32_16x16x32_bf16 v[22:25], v[154:157], v[202:205], v[22:25]
	v_mfma_f32_16x16x32_bf16 v[22:25], v[158:161], v[206:209], v[22:25]
	v_mfma_f32_16x16x32_bf16 v[6:9], v[154:157], v[210:213], v[6:9]
	v_mfma_f32_16x16x32_bf16 v[6:9], v[158:161], v[214:217], v[6:9]
	v_mfma_f32_16x16x32_bf16 v[58:61], v[162:165], v[178:181], v[58:61]
	v_mfma_f32_16x16x32_bf16 v[58:61], v[166:169], v[182:185], v[58:61]
	v_mfma_f32_16x16x32_bf16 v[42:45], v[162:165], v[186:189], v[42:45]
	v_mfma_f32_16x16x32_bf16 v[42:45], v[166:169], v[190:193], v[42:45]
	v_mfma_f32_16x16x32_bf16 v[26:29], v[162:165], v[202:205], v[26:29]
	v_mfma_f32_16x16x32_bf16 v[26:29], v[166:169], v[206:209], v[26:29]
	v_mfma_f32_16x16x32_bf16 v[10:13], v[162:165], v[210:213], v[10:13]
	v_mfma_f32_16x16x32_bf16 v[10:13], v[166:169], v[214:217], v[10:13]
	v_mfma_f32_16x16x32_bf16 v[62:65], v[170:173], v[178:181], v[62:65]
	v_mfma_f32_16x16x32_bf16 v[62:65], v[174:177], v[182:185], v[62:65]
	v_mfma_f32_16x16x32_bf16 v[46:49], v[170:173], v[186:189], v[46:49]
	v_mfma_f32_16x16x32_bf16 v[46:49], v[174:177], v[190:193], v[46:49]
	v_mfma_f32_16x16x32_bf16 v[30:33], v[170:173], v[202:205], v[30:33]
	v_mfma_f32_16x16x32_bf16 v[30:33], v[174:177], v[206:209], v[30:33]
	v_mfma_f32_16x16x32_bf16 v[14:17], v[170:173], v[210:213], v[14:17]
	v_mfma_f32_16x16x32_bf16 v[14:17], v[174:177], v[214:217], v[14:17]
	s_setprio 0
	s_barrier
	s_add_i32 s82, s82, 2
	s_add_u32 s60, s60, 0x100
	s_addc_u32 s61, s61, 0
	s_add_u32 s80, s80, 0x100
	s_addc_u32 s81, s81, 0
	s_cmp_gt_u32 s82, 13
	s_cbranch_scc0 .LBB0_220
	s_and_b64 vcc, exec, s[44:45]
	s_cbranch_vccz .LBB0_223
	s_barrier

; #define PG8_LAS __attribute__((address_space(3)))
; __device__ __forceinline__ unsigned cvt_pk_bf16(float lo, float hi) { unsigned r; asm volatile("v_cvt_pk_bf16_f32 %0, %1, %2" : "=v"(r) : "v"(lo), "v"(hi)); return r; }
;     __device__ __forceinline__ void operator()(const f32x4 (&acc)[2][2][4][2], const Unit& u, int wr, int wc, int fr, int fq, PG8_LAS unsigned char* lds, int& rs_pm, int& rs_tog) const {
;     ...
;         const PG8_LAS float* rt_ = row_scale_table(ssq, u.pm, lds, rs_pm, rs_tog) + wr * 64 + fr;
; #pragma unroll
;         for (int ai = 0; ai < 2; ++ai)
; #pragma unroll
;             for (int m = 0; m < 4; ++m) {
;                 const int row = row0 + ai * HALF + m * 16;
;                 const float rr = rt_[ai * HALF + m * 16], k1 = -kLog2e * rr, rr2 = rr * rr;
;                 const f32x4 a0 = acc[ai][0][m][0], a1 = acc[ai][0][m][1];
;                 f32x4 e0 = a0 * k1, e1 = a1 * k1;
;                 f32x4 g0 = (a0 * acc[ai][1][m][0]) * rr2, g1 = (a1 * acc[ai][1][m][1]) * rr2;
; #pragma unroll
;                 for (int i = 0; i < 4; ++i) { e0[i] = __builtin_amdgcn_exp2f(e0[i]); e1[i] = __builtin_amdgcn_exp2f(e1[i]); }
;                 e0 = e0 + 1.0f; e1 = e1 + 1.0f;
; #pragma unroll
;                 for (int i = 0; i < 4; ++i) { e0[i] = __builtin_amdgcn_rcpf(e0[i]); e1[i] = __builtin_amdgcn_rcpf(e1[i]); }
;                 g0 = g0 * e0; g1 = g1 * e1;
;                 const float b[8] = {g0[0], g0[1], g0[2], g0[3], g1[0], g1[1], g1[2], g1[3]};
;                 u32x4 w; w.x = cvt_pk_bf16(b[0], b[1]); w.y = cvt_pk_bf16(b[2], b[3]); w.z = cvt_pk_bf16(b[4], b[5]); w.w = cvt_pk_bf16(b[6], b[7]);
;                 *(u32x4*)(act + (size_t)row * ldc + col0) = w;
.LBB0_227:
	v_lshl_add_u32 v146, s73, 10, v142
	ds_read_b32 v147, v146
	v_lshl_or_b32 v148, s76, 7, v143
	v_add_u32_e32 v145, s47, v140
	v_ashrrev_i32_e32 v149, 31, v148
	s_andn2_b64 vcc, exec, s[42:43]
	s_waitcnt lgkmcnt(0)
	v_mul_f32_e32 v150, 0xbfb8aa3b, v147
	v_pk_mul_f32 v[154:155], v[116:117], v[150:151] op_sel_hi:[1,0]
	v_pk_mul_f32 v[156:157], v[114:115], v[150:151] op_sel_hi:[1,0]
	v_pk_mul_f32 v[158:159], v[120:121], v[150:151] op_sel_hi:[1,0]
	v_pk_mul_f32 v[150:151], v[118:119], v[150:151] op_sel_hi:[1,0]
	v_pk_mul_f32 v[120:121], v[120:121], v[128:129]
	v_pk_mul_f32 v[118:119], v[118:119], v[126:127]
	v_exp_f32_e32 v126, v156
	v_exp_f32_e32 v128, v150
	v_exp_f32_e32 v127, v157
	v_exp_f32_e32 v129, v151
	v_exp_f32_e32 v150, v154
	v_exp_f32_e32 v154, v158
	v_exp_f32_e32 v151, v155
	v_exp_f32_e32 v155, v159
	v_pk_mul_f32 v[116:117], v[116:117], v[124:125]
	v_pk_mul_f32 v[114:115], v[114:115], v[122:123]
	v_pk_add_f32 v[122:123], v[150:151], 1.0 op_sel_hi:[1,0]
	v_pk_add_f32 v[124:125], v[126:127], 1.0 op_sel_hi:[1,0]
	v_pk_add_f32 v[126:127], v[154:155], 1.0 op_sel_hi:[1,0]
	v_pk_add_f32 v[128:129], v[128:129], 1.0 op_sel_hi:[1,0]
	v_rcp_f32_e32 v122, v122
	v_rcp_f32_e32 v128, v128
	v_rcp_f32_e32 v129, v129
	v_rcp_f32_e32 v126, v126
	v_rcp_f32_e32 v123, v123
	v_rcp_f32_e32 v127, v127
	v_rcp_f32_e32 v124, v124
	v_rcp_f32_e32 v125, v125
	v_mul_f32_e32 v152, v147, v147
	v_pk_mul_f32 v[116:117], v[116:117], v[152:153] op_sel_hi:[1,0]
	v_pk_mul_f32 v[120:121], v[120:121], v[152:153] op_sel_hi:[1,0]
	v_pk_mul_f32 v[118:119], v[118:119], v[152:153] op_sel_hi:[1,0]
	v_pk_mul_f32 v[114:115], v[114:115], v[152:153] op_sel_hi:[1,0]
	v_pk_mul_f32 v[116:117], v[116:117], v[122:123]
	v_pk_mul_f32 v[122:123], v[120:121], v[126:127]
	v_pk_mul_f32 v[120:121], v[118:119], v[128:129]
	v_pk_mul_f32 v[114:115], v[114:115], v[124:125]
	s_mov_b64 s[42:43], -1
	v_cvt_pk_bf16_f32 v118, v114, v115
	v_cvt_pk_bf16_f32 v119, v116, v117
	v_cvt_pk_bf16_f32 v120, v120, v121
	v_cvt_pk_bf16_f32 v121, v122, v123
	ds_read_b32 v124, v146 offset:64
	v_mov_b64_e32 v[114:115], s[10:11]
	v_mad_i64_i32 v[122:123], s[38:39], v145, s86, v[114:115]
	v_lshlrev_b64 v[116:117], 1, v[148:149]
	v_lshl_add_u64 v[122:123], v[122:123], 0, v[116:117]
	global_store_dwordx4 v[122:123], v[118:121], off
	s_waitcnt lgkmcnt(0)
	s_nop 0
	v_mul_f32_e32 v118, 0xbfb8aa3b, v124
	v_mul_f32_e32 v120, v124, v124
	v_pk_mul_f32 v[122:123], v[100:101], v[118:119] op_sel_hi:[1,0]
	v_pk_mul_f32 v[124:125], v[98:99], v[118:119] op_sel_hi:[1,0]
	v_pk_mul_f32 v[126:127], v[104:105], v[118:119] op_sel_hi:[1,0]
	v_pk_mul_f32 v[118:119], v[102:103], v[118:119] op_sel_hi:[1,0]
	v_pk_mul_f32 v[104:105], v[104:105], v[112:113]
	v_pk_mul_f32 v[102:103], v[102:103], v[110:111]
	v_exp_f32_e32 v110, v124
	v_exp_f32_e32 v112, v118
	v_exp_f32_e32 v111, v125
	v_exp_f32_e32 v113, v119
	v_exp_f32_e32 v118, v122
	v_exp_f32_e32 v122, v126
	v_exp_f32_e32 v119, v123
	v_exp_f32_e32 v123, v127
	v_pk_mul_f32 v[100:101], v[100:101], v[108:109]
	v_pk_mul_f32 v[98:99], v[98:99], v[106:107]
	v_pk_add_f32 v[106:107], v[118:119], 1.0 op_sel_hi:[1,0]
	v_pk_add_f32 v[108:109], v[110:111], 1.0 op_sel_hi:[1,0]
	v_pk_add_f32 v[110:111], v[122:123], 1.0 op_sel_hi:[1,0]
	v_pk_add_f32 v[112:113], v[112:113], 1.0 op_sel_hi:[1,0]
	v_rcp_f32_e32 v108, v108
	v_rcp_f32_e32 v109, v109
	v_rcp_f32_e32 v106, v106
	v_rcp_f32_e32 v110, v110
	v_rcp_f32_e32 v107, v107
	v_rcp_f32_e32 v111, v111
	v_rcp_f32_e32 v112, v112
	v_rcp_f32_e32 v113, v113
	v_pk_mul_f32 v[100:101], v[100:101], v[120:121] op_sel_hi:[1,0]
	v_pk_mul_f32 v[98:99], v[98:99], v[120:121] op_sel_hi:[1,0]
	v_pk_mul_f32 v[104:105], v[104:105], v[120:121] op_sel_hi:[1,0]
	v_pk_mul_f32 v[102:103], v[102:103], v[120:121] op_sel_hi:[1,0]
	v_pk_mul_f32 v[100:101], v[100:101], v[106:107]
	v_pk_mul_f32 v[98:99], v[98:99], v[108:109]
	v_pk_mul_f32 v[104:105], v[104:105], v[110:111]
	v_pk_mul_f32 v[102:103], v[102:103], v[112:113]
	v_cvt_pk_bf16_f32 v98, v98, v99
	v_cvt_pk_bf16_f32 v99, v100, v101
	v_or_b32_e32 v118, 16, v145
	v_cvt_pk_bf16_f32 v100, v102, v103
	v_cvt_pk_bf16_f32 v101, v104, v105
	ds_read_b32 v104, v146 offset:128
	v_mad_i64_i32 v[102:103], s[38:39], v118, s86, v[114:115]
	v_lshl_add_u64 v[102:103], v[102:103], 0, v[116:117]
	global_store_dwordx4 v[102:103], v[98:101], off
	s_waitcnt lgkmcnt(0)
	s_nop 0
	v_mul_f32_e32 v98, 0xbfb8aa3b, v104
	v_mul_f32_e32 v100, v104, v104
	v_pk_mul_f32 v[102:103], v[84:85], v[98:99] op_sel_hi:[1,0]
	v_pk_mul_f32 v[104:105], v[82:83], v[98:99] op_sel_hi:[1,0]
	v_pk_mul_f32 v[106:107], v[88:89], v[98:99] op_sel_hi:[1,0]
	v_pk_mul_f32 v[98:99], v[86:87], v[98:99] op_sel_hi:[1,0]
	v_pk_mul_f32 v[88:89], v[88:89], v[96:97]
	v_pk_mul_f32 v[86:87], v[86:87], v[94:95]
	v_exp_f32_e32 v94, v104
	v_exp_f32_e32 v96, v98
	v_exp_f32_e32 v95, v105
	v_exp_f32_e32 v97, v99
	v_exp_f32_e32 v98, v102
	v_exp_f32_e32 v102, v106
	v_exp_f32_e32 v99, v103
	v_exp_f32_e32 v103, v107
	v_pk_mul_f32 v[84:85], v[84:85], v[92:93]
	v_pk_mul_f32 v[82:83], v[82:83], v[90:91]
	v_pk_add_f32 v[90:91], v[98:99], 1.0 op_sel_hi:[1,0]
	v_pk_add_f32 v[92:93], v[94:95], 1.0 op_sel_hi:[1,0]
	v_pk_add_f32 v[94:95], v[102:103], 1.0 op_sel_hi:[1,0]
	v_pk_add_f32 v[96:97], v[96:97], 1.0 op_sel_hi:[1,0]
	v_rcp_f32_e32 v92, v92
	v_rcp_f32_e32 v93, v93
	v_rcp_f32_e32 v90, v90
	v_rcp_f32_e32 v94, v94
	v_rcp_f32_e32 v91, v91
	v_rcp_f32_e32 v95, v95
	v_rcp_f32_e32 v96, v96
	v_rcp_f32_e32 v97, v97
	v_pk_mul_f32 v[84:85], v[84:85], v[100:101] op_sel_hi:[1,0]
	v_pk_mul_f32 v[82:83], v[82:83], v[100:101] op_sel_hi:[1,0]
	v_pk_mul_f32 v[88:89], v[88:89], v[100:101] op_sel_hi:[1,0]
	v_pk_mul_f32 v[86:87], v[86:87], v[100:101] op_sel_hi:[1,0]
	v_pk_mul_f32 v[84:85], v[84:85], v[90:91]
	v_pk_mul_f32 v[82:83], v[82:83], v[92:93]
	v_pk_mul_f32 v[88:89], v[88:89], v[94:95]
	v_pk_mul_f32 v[86:87], v[86:87], v[96:97]
	v_cvt_pk_bf16_f32 v82, v82, v83
	v_cvt_pk_bf16_f32 v83, v84, v85
	v_or_b32_e32 v98, 32, v145
	v_cvt_pk_bf16_f32 v84, v86, v87
	v_cvt_pk_bf16_f32 v85, v88, v89
	ds_read_b32 v88, v146 offset:192
	v_mad_i64_i32 v[86:87], s[38:39], v98, s86, v[114:115]
	v_lshl_add_u64 v[86:87], v[86:87], 0, v[116:117]
	global_store_dwordx4 v[86:87], v[82:85], off
	s_waitcnt lgkmcnt(0)
; __device__ __forceinline__ unsigned cvt_pk_bf16(float lo, float hi) { unsigned r; asm volatile("v_cvt_pk_bf16_f32 %0, %1, %2" : "=v"(r) : "v"(lo), "v"(hi)); return r; }
;     __device__ __forceinline__ void operator()(const f32x4 (&acc)[2][2][4][2], const Unit& u, int wr, int wc, int fr, int fq, PG8_LAS unsigned char* lds, int& rs_pm, int& rs_tog) const {
;     ...
;             for (int m = 0; m < 4; ++m) {
;                 const int row = row0 + ai * HALF + m * 16;
;                 const float rr = rt_[ai * HALF + m * 16], k1 = -kLog2e * rr, rr2 = rr * rr;
;                 const f32x4 a0 = acc[ai][0][m][0], a1 = acc[ai][0][m][1];
;                 f32x4 e0 = a0 * k1, e1 = a1 * k1;
;                 f32x4 g0 = (a0 * acc[ai][1][m][0]) * rr2, g1 = (a1 * acc[ai][1][m][1]) * rr2;
; #pragma unroll
;                 for (int i = 0; i < 4; ++i) { e0[i] = __builtin_amdgcn_exp2f(e0[i]); e1[i] = __builtin_amdgcn_exp2f(e1[i]); }
;                 e0 = e0 + 1.0f; e1 = e1 + 1.0f;
; #pragma unroll
;                 for (int i = 0; i < 4; ++i) { e0[i] = __builtin_amdgcn_rcpf(e0[i]); e1[i] = __builtin_amdgcn_rcpf(e1[i]); }
;                 g0 = g0 * e0; g1 = g1 * e1;
;                 const float b[8] = {g0[0], g0[1], g0[2], g0[3], g1[0], g1[1], g1[2], g1[3]};
;                 u32x4 w; w.x = cvt_pk_bf16(b[0], b[1]); w.y = cvt_pk_bf16(b[2], b[3]); w.z = cvt_pk_bf16(b[4], b[5]); w.w = cvt_pk_bf16(b[6], b[7]);
;                 *(u32x4*)(act + (size_t)row * ldc + col0) = w;
	s_nop 0
	v_mul_f32_e32 v82, 0xbfb8aa3b, v88
	v_mul_f32_e32 v84, v88, v88
	v_pk_mul_f32 v[86:87], v[68:69], v[82:83] op_sel_hi:[1,0]
	v_pk_mul_f32 v[88:89], v[66:67], v[82:83] op_sel_hi:[1,0]
	v_pk_mul_f32 v[90:91], v[72:73], v[82:83] op_sel_hi:[1,0]
	v_pk_mul_f32 v[82:83], v[70:71], v[82:83] op_sel_hi:[1,0]
	v_pk_mul_f32 v[72:73], v[72:73], v[80:81]
	v_pk_mul_f32 v[70:71], v[70:71], v[78:79]
	v_exp_f32_e32 v78, v88
	v_exp_f32_e32 v80, v82
	v_exp_f32_e32 v79, v89
	v_exp_f32_e32 v81, v83
	v_exp_f32_e32 v82, v86
	v_exp_f32_e32 v86, v90
	v_exp_f32_e32 v83, v87
	v_exp_f32_e32 v87, v91
	v_pk_mul_f32 v[68:69], v[68:69], v[76:77]
	v_pk_mul_f32 v[66:67], v[66:67], v[74:75]
	v_pk_add_f32 v[74:75], v[82:83], 1.0 op_sel_hi:[1,0]
	v_pk_add_f32 v[76:77], v[78:79], 1.0 op_sel_hi:[1,0]
	v_pk_add_f32 v[78:79], v[86:87], 1.0 op_sel_hi:[1,0]
	v_pk_add_f32 v[80:81], v[80:81], 1.0 op_sel_hi:[1,0]
	v_rcp_f32_e32 v76, v76
	v_rcp_f32_e32 v77, v77
	v_rcp_f32_e32 v74, v74
	v_rcp_f32_e32 v78, v78
	v_rcp_f32_e32 v75, v75
	v_rcp_f32_e32 v79, v79
	v_rcp_f32_e32 v80, v80
	v_rcp_f32_e32 v81, v81
	v_pk_mul_f32 v[68:69], v[68:69], v[84:85] op_sel_hi:[1,0]
	v_pk_mul_f32 v[66:67], v[66:67], v[84:85] op_sel_hi:[1,0]
	v_pk_mul_f32 v[72:73], v[72:73], v[84:85] op_sel_hi:[1,0]
	v_pk_mul_f32 v[70:71], v[70:71], v[84:85] op_sel_hi:[1,0]
	v_pk_mul_f32 v[68:69], v[68:69], v[74:75]
	v_pk_mul_f32 v[66:67], v[66:67], v[76:77]
	v_pk_mul_f32 v[72:73], v[72:73], v[78:79]
	v_pk_mul_f32 v[70:71], v[70:71], v[80:81]
	v_cvt_pk_bf16_f32 v66, v66, v67
	v_cvt_pk_bf16_f32 v67, v68, v69
	v_or_b32_e32 v82, 48, v145
	v_cvt_pk_bf16_f32 v68, v70, v71
	v_cvt_pk_bf16_f32 v69, v72, v73
	ds_read_b32 v72, v146 offset:512
	v_mad_i64_i32 v[70:71], s[38:39], v82, s86, v[114:115]
	v_lshl_add_u64 v[70:71], v[70:71], 0, v[116:117]
	global_store_dwordx4 v[70:71], v[66:69], off
	s_waitcnt lgkmcnt(0)
	s_nop 0
	v_mul_f32_e32 v66, 0xbfb8aa3b, v72
	v_mul_f32_e32 v68, v72, v72
	v_pk_mul_f32 v[70:71], v[52:53], v[66:67] op_sel_hi:[1,0]
	v_pk_mul_f32 v[72:73], v[50:51], v[66:67] op_sel_hi:[1,0]
	v_pk_mul_f32 v[74:75], v[56:57], v[66:67] op_sel_hi:[1,0]
	v_pk_mul_f32 v[66:67], v[54:55], v[66:67] op_sel_hi:[1,0]
	v_pk_mul_f32 v[56:57], v[56:57], v[64:65]
	v_pk_mul_f32 v[54:55], v[54:55], v[62:63]
	v_exp_f32_e32 v62, v72
	v_exp_f32_e32 v64, v66
	v_exp_f32_e32 v63, v73
	v_exp_f32_e32 v65, v67
	v_exp_f32_e32 v66, v70
	v_exp_f32_e32 v70, v74
	v_exp_f32_e32 v67, v71
	v_exp_f32_e32 v71, v75
	v_pk_mul_f32 v[52:53], v[52:53], v[60:61]
	v_pk_mul_f32 v[50:51], v[50:51], v[58:59]
	v_pk_add_f32 v[58:59], v[66:67], 1.0 op_sel_hi:[1,0]
	v_pk_add_f32 v[60:61], v[62:63], 1.0 op_sel_hi:[1,0]
	v_pk_add_f32 v[62:63], v[70:71], 1.0 op_sel_hi:[1,0]
	v_pk_add_f32 v[64:65], v[64:65], 1.0 op_sel_hi:[1,0]
	v_rcp_f32_e32 v60, v60
	v_rcp_f32_e32 v61, v61
	v_rcp_f32_e32 v58, v58
	v_rcp_f32_e32 v62, v62
	v_rcp_f32_e32 v59, v59
	v_rcp_f32_e32 v63, v63
	v_rcp_f32_e32 v64, v64
	v_rcp_f32_e32 v65, v65
	v_add_u32_e32 v69, 0x80, v145
	v_pk_mul_f32 v[52:53], v[52:53], v[68:69] op_sel_hi:[1,0]
	v_pk_mul_f32 v[50:51], v[50:51], v[68:69] op_sel_hi:[1,0]
	v_pk_mul_f32 v[56:57], v[56:57], v[68:69] op_sel_hi:[1,0]
	v_pk_mul_f32 v[54:55], v[54:55], v[68:69] op_sel_hi:[1,0]
	v_pk_mul_f32 v[52:53], v[52:53], v[58:59]
	v_pk_mul_f32 v[50:51], v[50:51], v[60:61]
	v_pk_mul_f32 v[56:57], v[56:57], v[62:63]
	v_pk_mul_f32 v[54:55], v[54:55], v[64:65]
	v_cvt_pk_bf16_f32 v50, v50, v51
	v_cvt_pk_bf16_f32 v51, v52, v53
	s_nop 0
	v_cvt_pk_bf16_f32 v52, v54, v55
	v_cvt_pk_bf16_f32 v53, v56, v57
	ds_read_b32 v56, v146 offset:576
	v_mad_i64_i32 v[54:55], s[38:39], v69, s86, v[114:115]
	v_lshl_add_u64 v[54:55], v[54:55], 0, v[116:117]
	global_store_dwordx4 v[54:55], v[50:53], off
	s_waitcnt lgkmcnt(0)
; __device__ __forceinline__ unsigned cvt_pk_bf16(float lo, float hi) { unsigned r; asm volatile("v_cvt_pk_bf16_f32 %0, %1, %2" : "=v"(r) : "v"(lo), "v"(hi)); return r; }
;     __device__ __forceinline__ void operator()(const f32x4 (&acc)[2][2][4][2], const Unit& u, int wr, int wc, int fr, int fq, PG8_LAS unsigned char* lds, int& rs_pm, int& rs_tog) const {
;     ...
;             for (int m = 0; m < 4; ++m) {
;                 const int row = row0 + ai * HALF + m * 16;
;                 const float rr = rt_[ai * HALF + m * 16], k1 = -kLog2e * rr, rr2 = rr * rr;
;                 const f32x4 a0 = acc[ai][0][m][0], a1 = acc[ai][0][m][1];
;                 f32x4 e0 = a0 * k1, e1 = a1 * k1;
;                 f32x4 g0 = (a0 * acc[ai][1][m][0]) * rr2, g1 = (a1 * acc[ai][1][m][1]) * rr2;
; #pragma unroll
;                 for (int i = 0; i < 4; ++i) { e0[i] = __builtin_amdgcn_exp2f(e0[i]); e1[i] = __builtin_amdgcn_exp2f(e1[i]); }
;                 e0 = e0 + 1.0f; e1 = e1 + 1.0f;
; #pragma unroll
;                 for (int i = 0; i < 4; ++i) { e0[i] = __builtin_amdgcn_rcpf(e0[i]); e1[i] = __builtin_amdgcn_rcpf(e1[i]); }
;                 g0 = g0 * e0; g1 = g1 * e1;
;                 const float b[8] = {g0[0], g0[1], g0[2], g0[3], g1[0], g1[1], g1[2], g1[3]};
;                 u32x4 w; w.x = cvt_pk_bf16(b[0], b[1]); w.y = cvt_pk_bf16(b[2], b[3]); w.z = cvt_pk_bf16(b[4], b[5]); w.w = cvt_pk_bf16(b[6], b[7]);
;                 *(u32x4*)(act + (size_t)row * ldc + col0) = w;
; template <class Epi, class Sched, bool ALIGN_EPI = false, bool SP2 = false>
; __device__ __forceinline__ void gemm_phase(PG8_LAS unsigned char* lds, const Gemm g, const Sched& S, const Epi& E) {
;     ...
;         if (!has_next) break;
; #pragma unroll
;         for (int a = 0; a < 2; ++a)
; #pragma unroll
;             for (int b = 0; b < 2; ++b)
; #pragma unroll
;                 for (int m = 0; m < 4; ++m)
; #pragma unroll
;                     for (int n = 0; n < 2; ++n) { unsigned long long lo_, hi_; asm volatile("v_mov_b64 %0, 0\n\tv_mov_b64 %1, 0" : "=v"(lo_), "=v"(hi_)); acc[a][b][m][n] = __builtin_bit_cast(f32x4, (u64x2_t){lo_, hi_}); }
;         cur = nxt; cA = nA; cB = nB; ++ui;
	s_nop 0
	v_mul_f32_e32 v50, 0xbfb8aa3b, v56
	v_mul_f32_e32 v52, v56, v56
	v_pk_mul_f32 v[54:55], v[36:37], v[50:51] op_sel_hi:[1,0]
	v_pk_mul_f32 v[56:57], v[34:35], v[50:51] op_sel_hi:[1,0]
	v_pk_mul_f32 v[58:59], v[40:41], v[50:51] op_sel_hi:[1,0]
	v_pk_mul_f32 v[50:51], v[38:39], v[50:51] op_sel_hi:[1,0]
	v_pk_mul_f32 v[40:41], v[40:41], v[48:49]
	v_pk_mul_f32 v[38:39], v[38:39], v[46:47]
	v_exp_f32_e32 v46, v56
	v_exp_f32_e32 v48, v50
	v_exp_f32_e32 v47, v57
	v_exp_f32_e32 v49, v51
	v_exp_f32_e32 v50, v54
	v_exp_f32_e32 v54, v58
	v_exp_f32_e32 v51, v55
	v_exp_f32_e32 v55, v59
	v_pk_mul_f32 v[36:37], v[36:37], v[44:45]
	v_pk_mul_f32 v[34:35], v[34:35], v[42:43]
	v_pk_add_f32 v[42:43], v[50:51], 1.0 op_sel_hi:[1,0]
	v_pk_add_f32 v[44:45], v[46:47], 1.0 op_sel_hi:[1,0]
	v_pk_add_f32 v[46:47], v[54:55], 1.0 op_sel_hi:[1,0]
	v_pk_add_f32 v[48:49], v[48:49], 1.0 op_sel_hi:[1,0]
	v_rcp_f32_e32 v44, v44
	v_rcp_f32_e32 v45, v45
	v_rcp_f32_e32 v42, v42
	v_rcp_f32_e32 v46, v46
	v_rcp_f32_e32 v43, v43
	v_rcp_f32_e32 v47, v47
	v_rcp_f32_e32 v48, v48
	v_rcp_f32_e32 v49, v49
	v_pk_mul_f32 v[36:37], v[36:37], v[52:53] op_sel_hi:[1,0]
	v_pk_mul_f32 v[34:35], v[34:35], v[52:53] op_sel_hi:[1,0]
	v_pk_mul_f32 v[40:41], v[40:41], v[52:53] op_sel_hi:[1,0]
	v_pk_mul_f32 v[38:39], v[38:39], v[52:53] op_sel_hi:[1,0]
	v_pk_mul_f32 v[36:37], v[36:37], v[42:43]
	v_pk_mul_f32 v[34:35], v[34:35], v[44:45]
	v_pk_mul_f32 v[40:41], v[40:41], v[46:47]
	v_pk_mul_f32 v[38:39], v[38:39], v[48:49]
	v_cvt_pk_bf16_f32 v34, v34, v35
	v_cvt_pk_bf16_f32 v35, v36, v37
	v_add_u32_e32 v50, 0x90, v145
	v_cvt_pk_bf16_f32 v36, v38, v39
	v_cvt_pk_bf16_f32 v37, v40, v41
	ds_read_b32 v40, v146 offset:640
	v_mad_i64_i32 v[38:39], s[38:39], v50, s86, v[114:115]
	v_lshl_add_u64 v[38:39], v[38:39], 0, v[116:117]
	global_store_dwordx4 v[38:39], v[34:37], off
	s_waitcnt lgkmcnt(0)
	s_nop 0
	v_mul_f32_e32 v34, 0xbfb8aa3b, v40
	v_mul_f32_e32 v36, v40, v40
	v_pk_mul_f32 v[38:39], v[20:21], v[34:35] op_sel_hi:[1,0]
	v_pk_mul_f32 v[40:41], v[18:19], v[34:35] op_sel_hi:[1,0]
	v_pk_mul_f32 v[42:43], v[24:25], v[34:35] op_sel_hi:[1,0]
	v_pk_mul_f32 v[34:35], v[22:23], v[34:35] op_sel_hi:[1,0]
	v_pk_mul_f32 v[24:25], v[24:25], v[32:33]
	v_pk_mul_f32 v[22:23], v[22:23], v[30:31]
	v_exp_f32_e32 v30, v40
	v_exp_f32_e32 v32, v34
	v_exp_f32_e32 v31, v41
	v_exp_f32_e32 v33, v35
	v_exp_f32_e32 v34, v38
	v_exp_f32_e32 v38, v42
	v_exp_f32_e32 v35, v39
	v_exp_f32_e32 v39, v43
	v_pk_mul_f32 v[20:21], v[20:21], v[28:29]
	v_pk_mul_f32 v[18:19], v[18:19], v[26:27]
	v_pk_add_f32 v[26:27], v[34:35], 1.0 op_sel_hi:[1,0]
	v_pk_add_f32 v[28:29], v[30:31], 1.0 op_sel_hi:[1,0]
	v_pk_add_f32 v[30:31], v[38:39], 1.0 op_sel_hi:[1,0]
	v_pk_add_f32 v[32:33], v[32:33], 1.0 op_sel_hi:[1,0]
	v_rcp_f32_e32 v28, v28
	v_rcp_f32_e32 v29, v29
	v_rcp_f32_e32 v26, v26
	v_rcp_f32_e32 v30, v30
	v_rcp_f32_e32 v27, v27
	v_rcp_f32_e32 v31, v31
	v_rcp_f32_e32 v32, v32
	v_rcp_f32_e32 v33, v33
	v_pk_mul_f32 v[20:21], v[20:21], v[36:37] op_sel_hi:[1,0]
	v_pk_mul_f32 v[18:19], v[18:19], v[36:37] op_sel_hi:[1,0]
	v_pk_mul_f32 v[24:25], v[24:25], v[36:37] op_sel_hi:[1,0]
	v_pk_mul_f32 v[22:23], v[22:23], v[36:37] op_sel_hi:[1,0]
	v_pk_mul_f32 v[20:21], v[20:21], v[26:27]
	v_pk_mul_f32 v[18:19], v[18:19], v[28:29]
	v_pk_mul_f32 v[24:25], v[24:25], v[30:31]
	v_pk_mul_f32 v[22:23], v[22:23], v[32:33]
	v_cvt_pk_bf16_f32 v18, v18, v19
	v_cvt_pk_bf16_f32 v19, v20, v21
	v_add_u32_e32 v34, 0xa0, v145
	v_cvt_pk_bf16_f32 v20, v22, v23
	v_cvt_pk_bf16_f32 v21, v24, v25
	ds_read_b32 v24, v146 offset:704
	v_mad_i64_i32 v[22:23], s[38:39], v34, s86, v[114:115]
	v_lshl_add_u64 v[22:23], v[22:23], 0, v[116:117]
	global_store_dwordx4 v[22:23], v[18:21], off
	s_waitcnt lgkmcnt(0)
	s_nop 0
	v_mul_f32_e32 v18, 0xbfb8aa3b, v24
	v_mul_f32_e32 v20, v24, v24
	v_pk_mul_f32 v[22:23], v[4:5], v[18:19] op_sel_hi:[1,0]
	v_pk_mul_f32 v[24:25], v[2:3], v[18:19] op_sel_hi:[1,0]
	v_pk_mul_f32 v[26:27], v[8:9], v[18:19] op_sel_hi:[1,0]
	v_pk_mul_f32 v[18:19], v[6:7], v[18:19] op_sel_hi:[1,0]
	v_pk_mul_f32 v[8:9], v[8:9], v[16:17]
	v_pk_mul_f32 v[6:7], v[6:7], v[14:15]
	v_exp_f32_e32 v14, v24
	v_exp_f32_e32 v16, v18
	v_exp_f32_e32 v15, v25
	v_exp_f32_e32 v17, v19
	v_exp_f32_e32 v18, v22
	v_exp_f32_e32 v19, v23
	v_exp_f32_e32 v22, v26
	v_exp_f32_e32 v23, v27
	v_pk_mul_f32 v[4:5], v[4:5], v[12:13]
	v_pk_mul_f32 v[2:3], v[2:3], v[10:11]
	v_pk_add_f32 v[10:11], v[18:19], 1.0 op_sel_hi:[1,0]
	v_pk_add_f32 v[12:13], v[14:15], 1.0 op_sel_hi:[1,0]
	v_pk_add_f32 v[16:17], v[16:17], 1.0 op_sel_hi:[1,0]
	v_rcp_f32_e32 v12, v12
	v_rcp_f32_e32 v16, v16
	v_rcp_f32_e32 v13, v13
	v_rcp_f32_e32 v17, v17
	v_rcp_f32_e32 v10, v10
	v_rcp_f32_e32 v11, v11
	v_pk_add_f32 v[14:15], v[22:23], 1.0 op_sel_hi:[1,0]
	v_pk_mul_f32 v[4:5], v[4:5], v[20:21] op_sel_hi:[1,0]
	v_rcp_f32_e32 v14, v14
	v_rcp_f32_e32 v15, v15
	v_pk_mul_f32 v[2:3], v[2:3], v[20:21] op_sel_hi:[1,0]
	v_pk_mul_f32 v[6:7], v[6:7], v[20:21] op_sel_hi:[1,0]
	v_add_u32_e32 v18, 0xb0, v145
	v_pk_mul_f32 v[4:5], v[4:5], v[10:11]
	v_pk_mul_f32 v[2:3], v[2:3], v[12:13]
	v_pk_mul_f32 v[6:7], v[6:7], v[16:17]
	v_pk_mul_f32 v[8:9], v[8:9], v[20:21] op_sel_hi:[1,0]
	v_cvt_pk_bf16_f32 v2, v2, v3
	v_cvt_pk_bf16_f32 v3, v4, v5
	v_cvt_pk_bf16_f32 v4, v6, v7
	v_mad_i64_i32 v[6:7], s[38:39], v18, s86, v[114:115]
	v_pk_mul_f32 v[8:9], v[8:9], v[14:15]
	v_lshl_add_u64 v[6:7], v[6:7], 0, v[116:117]
	v_cvt_pk_bf16_f32 v5, v8, v9
	global_store_dwordx4 v[6:7], v[2:5], off
	s_cbranch_vccnz .LBB0_216
	s_andn2_b64 vcc, exec, s[8:9]
	s_cbranch_vccnz .LBB0_215
	s_barrier
	s_branch .LBB0_215

; #define PG8_STAGE(bufoff, gbase, voff) do { _Pragma("unroll") for (int _i = 0; _i < 2; ++_i) \
;         __builtin_amdgcn_global_load_lds((const unsigned*)((const char*)(gbase) + (voff)[_i]), (PG8_LAS unsigned*)(lds + (bufoff) + ldsw + _i * 8192), 16, 0, 0); } while (0)
; #define PG8_WAIT_V(n) asm volatile("s_waitcnt vmcnt(" #n ")" ::: "memory")
; #define PG8_BAR __builtin_amdgcn_s_barrier()
; template <class Epi, class Sched, bool ALIGN_EPI = false, bool SP2 = false>
; __device__ __forceinline__ void gemm_phase(PG8_LAS unsigned char* lds, const Gemm g, const Sched& S, const Epi& E) {
;     ...
;     const int tid = tid_, wid = __builtin_amdgcn_readfirstlane(tid >> 6), lane = tid & 63, wr = wid >> 2, wc = wid & 3, fr = lane & 15, fq = lane >> 4;
;     const int K = g.K, nt = K / BK;
;     unsigned voffA[2], voffB[2];
; #pragma unroll
;     for (int i = 0; i < 2; ++i) { int R, C; stage_rc(tid * 16 + i * 8192, R, C); const int Rb = Epi::PERM ? ((R & ~31) + perm32(R & 31)) : R;
;         voffA[i] = (unsigned)(R * K + C) * 2u; voffB[i] = (unsigned)(Rb * K + C) * 2u; }
;     const size_t kstep = (size_t)(BK * 2);
;     const size_t hstep = (size_t)HALF * K * 2;
;     const size_t tstep = 2 * hstep;
;     const unsigned ldsw = (unsigned)wid * 1024u;
;     const int aoff = lds_byte(wr * 64 + fr, fq * 8), boff = lds_byte(wc * 32 + fr, fq * 8);
;     ...
;     const char* cA = (const char*)g.A + (size_t)cur.pm * tstep; const char* cB = (const char*)g.Bt + (size_t)cur.pn * tstep;
;     S.a_ready(cur);
;     if constexpr (SP2) {
;         PG8_STAGE(PG8_SB(0, 0), cB, voffB); PG8_STAGE(PG8_SB(0, 1), cB + hstep, voffB); PG8_STAGE(PG8_SA(0, 0), cA, voffA); PG8_STAGE(PG8_SA(0, 1), cA + hstep, voffA);
;         if (wr == 1) PG8_BAR;
;         PG8_WAIT_V(2); PG8_BAR;
;         PG8_STAGE(PG8_SB(1, 0), cB + kstep, voffB); PG8_STAGE(PG8_SA(1, 0), cA + kstep, voffA); PG8_STAGE(PG8_SB(1, 1), cB + hstep + kstep, voffB);
;         PG8_WAIT_V(6); PG8_BAR;
.LBB0_254:
	s_andn2_b64 vcc, exec, s[46:47]
	s_cbranch_vccnz .LBB0_385
	v_bfe_i32 v3, v142, 27, 1
	v_lshlrev_b32_e32 v2, 4, v142
	v_lshrrev_b32_e32 v3, 22, v3
	v_add_u32_e32 v3, v2, v3
	s_cmp_eq_u32 s88, 8
	v_and_b32_e32 v3, 0xfffffc00, v3
	s_cselect_b64 s[6:7], -1, 0
	v_sub_u32_e32 v3, v2, v3
	s_and_b64 s[46:47], s[6:7], exec
	s_brev_b32 s5, 24
	s_mov_b32 s38, 0xa00000
	v_ashrrev_i32_e32 v0, 31, v142
	v_lshrrev_b32_e32 v4, 4, v3
	s_cselect_b32 s5, s5, 0x4000000
	s_cselect_b32 s38, s38, 0x3100000
	s_and_b64 s[46:47], s[44:45], exec
	v_lshrrev_b32_e32 v0, 26, v0
	v_bitop3_b32 v3, v4, v3, 32 bitop3:0x6c
	s_cselect_b32 s38, 0x2b00000, s38
	s_cmp_eq_u32 s88, 3
	v_add_u32_e32 v0, v142, v0
	v_ashrrev_i32_e32 v5, 31, v3
	s_cselect_b64 s[70:71], -1, 0
	v_ashrrev_i32_e32 v0, 6, v0
	v_lshrrev_b32_e32 v5, 26, v5
	s_and_b64 s[46:47], s[70:71], exec
	v_lshlrev_b32_e32 v4, 3, v0
	v_add_u32_e32 v5, v3, v5
	s_cselect_b32 s39, 0x14000000, s5
	s_cselect_b32 s38, 0x800000, s38
	s_or_b64 s[6:7], s[70:71], s[6:7]
	v_and_b32_e32 v4, -16, v4
	v_ashrrev_i32_e32 v6, 6, v5
	v_lshlrev_b32_e32 v0, 5, v0
	s_and_b64 s[6:7], s[6:7], exec
	s_movk_i32 s5, 0x400
	v_add_u32_e32 v4, v6, v4
	v_and_b32_e32 v143, 32, v0
	v_and_b32_e32 v0, 0xc0, v5
	s_cselect_b32 s73, s5, 0xb00
	v_sub_u32_e32 v0, v3, v0
	v_lshlrev_b32_e32 v3, 1, v4
	v_lshrrev_b32_e32 v5, 2, v4
	v_and_b32_e32 v6, 3, v6
	s_mov_b32 s5, 0xffffe0
	v_ashrrev_i16_sdwa v0, v244, sext(v0) dst_sel:DWORD dst_unused:UNUSED_PAD src0_sel:DWORD src1_sel:BYTE_0
	v_and_b32_e32 v3, 24, v3
	v_and_b32_e32 v5, 4, v5
	v_and_or_b32 v6, v4, s5, v6
	v_bfe_i32 v144, v0, 0, 16
	v_or3_b32 v3, v6, v5, v3
	v_add_u32_e32 v0, v143, v144
	v_mul_lo_u32 v145, v4, s73
	v_mul_u32_u24_e32 v3, s73, v3
	v_add_u32_e32 v2, 0x2000, v2
	v_add_lshl_u32 v194, v0, v145, 1
	v_add_lshl_u32 v0, v3, v0, 1
	v_ashrrev_i32_e32 v3, 31, v2
	v_lshrrev_b32_e32 v3, 22, v3
	v_add_u32_e32 v3, v2, v3
	v_ashrrev_i32_e32 v3, 10, v3
	v_mul_i32_i24_e32 v4, 0x400, v3
	v_sub_u32_e32 v2, v2, v4
	v_lshrrev_b32_e32 v4, 4, v2
	v_bitop3_b32 v2, v4, v2, 32 bitop3:0x6c
	v_ashrrev_i32_e32 v5, 31, v2
	v_lshrrev_b32_e32 v5, 26, v5
	v_lshlrev_b32_e32 v4, 3, v3
	v_add_u32_e32 v5, v2, v5
	v_and_b32_e32 v4, -16, v4
	v_ashrrev_i32_e32 v6, 6, v5
	v_add_u32_e32 v4, v6, v4
	v_and_b32_e32 v6, 3, v6
	s_ashr_i32 s74, s27, 6
	s_ashr_i32 s72, s27, 8
	v_and_or_b32 v6, v4, s5, v6
	s_lshl_b32 s58, s73, 8
	s_lshl_b32 s5, s73, 9
	s_lshl_b32 s6, s74, 10
	s_add_u32 s7, s14, s39
	v_lshlrev_b32_e32 v3, 5, v3
	s_addc_u32 s69, s15, 0
	v_and_b32_e32 v146, 32, v3
	v_and_b32_e32 v3, 0xc0, v5
	s_add_u32 s90, s14, s38
	v_sub_u32_e32 v2, v2, v3
	v_lshlrev_b32_e32 v3, 1, v4
	v_lshrrev_b32_e32 v5, 2, v4
	s_addc_u32 s91, s15, 0
	s_mul_i32 s46, s5, s29
	v_ashrrev_i16_sdwa v2, v244, sext(v2) dst_sel:DWORD dst_unused:UNUSED_PAD src0_sel:DWORD src1_sel:BYTE_0
	v_and_b32_e32 v3, 24, v3
	v_and_b32_e32 v5, 4, v5
	s_mul_hi_i32 s47, s5, s29
	s_add_u32 s46, s90, s46
	v_bfe_i32 v147, v2, 0, 16
	v_or3_b32 v3, v6, v5, v3
	s_addc_u32 s47, s91, s47
	s_add_i32 s92, s6, 0
	v_add_u32_e32 v2, v146, v147
	v_mul_lo_u32 v148, v4, s73
	v_mul_u32_u24_e32 v3, s73, v3
	s_add_i32 m0, s92, 0x10000
	v_add_lshl_u32 v202, v2, v148, 1
	v_add_lshl_u32 v204, v3, v2, 1
	s_waitcnt vmcnt(0)
	global_load_lds_dwordx4 v0, s[46:47]
	s_add_i32 m0, s92, 0x12000
	s_add_u32 s48, s46, s58
	global_load_lds_dwordx4 v204, s[46:47]
	s_addc_u32 s49, s47, 0
	s_add_i32 m0, s92, 0x14000
	s_mul_i32 s39, s5, s33
	v_mov_b32_e32 v205, v1
	global_load_lds_dwordx4 v0, s[48:49]
	s_add_i32 m0, s92, 0x16000
	s_mul_hi_i32 s38, s5, s33
	v_lshl_add_u64 v[118:119], s[48:49], 0, v[0:1]
	v_lshl_add_u64 v[120:121], s[48:49], 0, v[204:205]
	global_load_lds_dwordx4 v204, s[48:49]
	s_add_u32 s48, s7, s39
	s_addc_u32 s49, s69, s38
	s_add_i32 s93, s92, 0x2000
	s_mov_b32 m0, s92
	s_add_u32 s60, s48, s58
	global_load_lds_dwordx4 v194, s[48:49]
	s_mov_b32 m0, s93
	s_addc_u32 s61, s49, 0
	s_add_i32 s94, s92, 0x4000
	global_load_lds_dwordx4 v202, s[48:49]
	s_mov_b32 m0, s94
	s_add_i32 s95, s92, 0x6000
	global_load_lds_dwordx4 v194, s[60:61]
	s_mov_b32 m0, s95
	v_mov_b32_e32 v195, v1
	global_load_lds_dwordx4 v202, s[60:61]
	v_mov_b32_e32 v203, v1
	s_cmp_eq_u32 s72, 1
	v_mov_b32_e32 v241, v240
	v_mov_b32_e32 v240, v239
	v_mov_b32_e32 v239, v238
	v_mov_b32_e32 v238, v233
	v_mov_b32_e32 v233, v245
	v_mov_b32_e32 v252, 1
	v_lshl_add_u64 v[110:111], s[46:47], 0, v[0:1]
	v_lshl_add_u64 v[112:113], s[46:47], 0, v[204:205]
	v_lshl_add_u64 v[138:139], s[48:49], 0, v[194:195]
	v_lshl_add_u64 v[140:141], s[48:49], 0, v[202:203]
	s_cselect_b64 s[60:61], -1, 0
	s_cmp_lg_u32 s72, 1
	s_cbranch_scc1 .LBB0_257
	s_barrier

; #define PG8_STAGE(bufoff, gbase, voff) do { _Pragma("unroll") for (int _i = 0; _i < 2; ++_i) \
;         __builtin_amdgcn_global_load_lds((const unsigned*)((const char*)(gbase) + (voff)[_i]), (PG8_LAS unsigned*)(lds + (bufoff) + ldsw + _i * 8192), 16, 0, 0); } while (0)
; #define PG8_LDA(dst, b, h) do { _Pragma("unroll") for (int m = 0; m < 4; ++m) _Pragma("unroll") for (int k = 0; k < 2; ++k) dst[m][k] = *(const PG8_LAS bf16x8*)(lds + PG8_SA(b, h) + aoff + m * 2048 + k * 1024); } while (0)
; #define PG8_LDB(dst, b, h) do { _Pragma("unroll") for (int n = 0; n < 2; ++n) _Pragma("unroll") for (int k = 0; k < 2; ++k) dst[n][k] = *(const PG8_LAS bf16x8*)(lds + PG8_SB(b, h) + boff + n * 2048 + k * 1024); } while (0)
; #define PG8_MMA(ai, bj, At, Bt) do { __builtin_amdgcn_s_setprio(1); _Pragma("unroll") for (int m = 0; m < 4; ++m) _Pragma("unroll") for (int n = 0; n < 2; ++n) _Pragma("unroll") for (int k = 0; k < 2; ++k) \
;         acc[ai][bj][m][n] = __builtin_amdgcn_mfma_f32_16x16x32_bf16(Bt[n][k], At[m][k], acc[ai][bj][m][n], 0, 0, 0); __builtin_amdgcn_s_setprio(0); } while (0)
; #define PG8_WAIT_V(n) asm volatile("s_waitcnt vmcnt(" #n ")" ::: "memory")
; #define PG8_WAIT_L(n) asm volatile("s_waitcnt lgkmcnt(" #n ")" ::: "memory")
; #define PG8_BAR __builtin_amdgcn_s_barrier()
; #define PG8_SCHED __builtin_amdgcn_sched_barrier(0)
; template <class Epi, class Sched, bool ALIGN_EPI = false, bool SP2 = false>
; __device__ __forceinline__ void gemm_phase(PG8_LAS unsigned char* lds, const Gemm g, const Sched& S, const Epi& E) {
;     ...
;             PG8_LDB(B0, 0, 0); PG8_LDB(B1, 0, 1); PG8_SCHED; PG8_LDA(At, 0, 0); PG8_STAGE(PG8_SA(1, 1), a1 + hstep, voffA);
;             PG8_WAIT_V(8); PG8_WAIT_L(0); PG8_BAR; PG8_MMA(0, 0, At, B0); PG8_MMA(0, 1, At, B1); PG8_BAR; PG8_SCHED;
.LBB0_274:
	s_add_i32 vcc_lo, s46, 2
	s_add_u32 s38, s48, 0x80
	s_addc_u32 s39, s49, 0
	s_add_i32 vcc_hi, 0, 0x10000
	s_cmp_eq_u32 s99, s46
	s_cselect_b32 s47, s81, s39
	s_cselect_b32 s46, s80, s38
	s_cselect_b32 s39, s83, s51
	s_cselect_b32 s38, s82, s50
	s_add_i32 s18, 0, 0x14000
	v_add_u32_e32 v142, vcc_hi, v245
	v_add_u32_e32 v158, s18, v245
	ds_read_b128 v[110:113], v142
	ds_read_b128 v[118:121], v142 offset:1024
	ds_read_b128 v[138:141], v142 offset:2048
	ds_read_b128 v[142:145], v142 offset:3072
	ds_read_b128 v[146:149], v158
	ds_read_b128 v[150:153], v158 offset:1024
	ds_read_b128 v[154:157], v158 offset:2048
	ds_read_b128 v[158:161], v158 offset:3072
	v_lshl_add_u64 v[210:211], s[48:49], 0, v[206:207]
	s_add_i32 m0, s92, 0xc000
	ds_read_b128 v[162:165], v247
	ds_read_b128 v[166:169], v247 offset:1024
	ds_read_b128 v[170:173], v247 offset:2048
	ds_read_b128 v[174:177], v247 offset:3072
	ds_read_b128 v[178:181], v247 offset:4096
	ds_read_b128 v[182:185], v247 offset:5120
	ds_read_b128 v[186:189], v247 offset:6144
	ds_read_b128 v[190:193], v247 offset:7168
	global_load_lds_dwordx4 v[210:211], off
	v_lshl_add_u64 v[210:211], s[48:49], 0, v[208:209]
	s_add_i32 m0, s92, 0xe000
	s_nop 0
	global_load_lds_dwordx4 v[210:211], off
	s_waitcnt vmcnt(8)
	s_waitcnt lgkmcnt(0)
	s_barrier
	s_setprio 1
	s_cmp_eq_u32 vcc_lo, 2
	s_cbranch_scc1 .Lz274_0_first
	v_mfma_f32_16x16x32_bf16 v[130:133], v[110:113], v[162:165], v[130:133]
	v_mfma_f32_16x16x32_bf16 v[130:133], v[118:121], v[166:169], v[130:133]
	v_mfma_f32_16x16x32_bf16 v[114:117], v[110:113], v[170:173], v[114:117]
	v_mfma_f32_16x16x32_bf16 v[114:117], v[118:121], v[174:177], v[114:117]
	v_mfma_f32_16x16x32_bf16 v[94:97], v[110:113], v[178:181], v[94:97]
	v_mfma_f32_16x16x32_bf16 v[94:97], v[118:121], v[182:185], v[94:97]
	v_mfma_f32_16x16x32_bf16 v[78:81], v[110:113], v[186:189], v[78:81]
	v_mfma_f32_16x16x32_bf16 v[78:81], v[118:121], v[190:193], v[78:81]
	v_mfma_f32_16x16x32_bf16 v[134:137], v[138:141], v[162:165], v[134:137]
	v_mfma_f32_16x16x32_bf16 v[134:137], v[142:145], v[166:169], v[134:137]
	v_mfma_f32_16x16x32_bf16 v[106:109], v[138:141], v[170:173], v[106:109]
	v_mfma_f32_16x16x32_bf16 v[106:109], v[142:145], v[174:177], v[106:109]
	v_mfma_f32_16x16x32_bf16 v[90:93], v[138:141], v[178:181], v[90:93]
	v_mfma_f32_16x16x32_bf16 v[90:93], v[142:145], v[182:185], v[90:93]
	v_mfma_f32_16x16x32_bf16 v[74:77], v[138:141], v[186:189], v[74:77]
	v_mfma_f32_16x16x32_bf16 v[74:77], v[142:145], v[190:193], v[74:77]
	v_mfma_f32_16x16x32_bf16 v[126:129], v[146:149], v[162:165], v[126:129]
	v_mfma_f32_16x16x32_bf16 v[126:129], v[150:153], v[166:169], v[126:129]
	v_mfma_f32_16x16x32_bf16 v[102:105], v[146:149], v[170:173], v[102:105]
	v_mfma_f32_16x16x32_bf16 v[102:105], v[150:153], v[174:177], v[102:105]
	v_mfma_f32_16x16x32_bf16 v[86:89], v[146:149], v[178:181], v[86:89]
	v_mfma_f32_16x16x32_bf16 v[86:89], v[150:153], v[182:185], v[86:89]
	v_mfma_f32_16x16x32_bf16 v[70:73], v[146:149], v[186:189], v[70:73]
	v_mfma_f32_16x16x32_bf16 v[70:73], v[150:153], v[190:193], v[70:73]
	v_mfma_f32_16x16x32_bf16 v[122:125], v[154:157], v[162:165], v[122:125]
	v_mfma_f32_16x16x32_bf16 v[122:125], v[158:161], v[166:169], v[122:125]
	v_mfma_f32_16x16x32_bf16 v[98:101], v[154:157], v[170:173], v[98:101]
	v_mfma_f32_16x16x32_bf16 v[98:101], v[158:161], v[174:177], v[98:101]
	v_mfma_f32_16x16x32_bf16 v[82:85], v[154:157], v[178:181], v[82:85]
	v_mfma_f32_16x16x32_bf16 v[82:85], v[158:161], v[182:185], v[82:85]
	v_mfma_f32_16x16x32_bf16 v[66:69], v[154:157], v[186:189], v[66:69]
	v_mfma_f32_16x16x32_bf16 v[66:69], v[158:161], v[190:193], v[66:69]
	s_branch .Lz274_0_join
.Lz274_0_first:
	v_mfma_f32_16x16x32_bf16 v[130:133], v[110:113], v[162:165], 0
	v_mfma_f32_16x16x32_bf16 v[130:133], v[118:121], v[166:169], v[130:133]
	v_mfma_f32_16x16x32_bf16 v[114:117], v[110:113], v[170:173], 0
	v_mfma_f32_16x16x32_bf16 v[114:117], v[118:121], v[174:177], v[114:117]
	v_mfma_f32_16x16x32_bf16 v[94:97], v[110:113], v[178:181], 0
	v_mfma_f32_16x16x32_bf16 v[94:97], v[118:121], v[182:185], v[94:97]
	v_mfma_f32_16x16x32_bf16 v[78:81], v[110:113], v[186:189], 0
	v_mfma_f32_16x16x32_bf16 v[78:81], v[118:121], v[190:193], v[78:81]
	v_mfma_f32_16x16x32_bf16 v[134:137], v[138:141], v[162:165], 0
	v_mfma_f32_16x16x32_bf16 v[134:137], v[142:145], v[166:169], v[134:137]
	v_mfma_f32_16x16x32_bf16 v[106:109], v[138:141], v[170:173], 0
	v_mfma_f32_16x16x32_bf16 v[106:109], v[142:145], v[174:177], v[106:109]
	v_mfma_f32_16x16x32_bf16 v[90:93], v[138:141], v[178:181], 0
	v_mfma_f32_16x16x32_bf16 v[90:93], v[142:145], v[182:185], v[90:93]
	v_mfma_f32_16x16x32_bf16 v[74:77], v[138:141], v[186:189], 0
	v_mfma_f32_16x16x32_bf16 v[74:77], v[142:145], v[190:193], v[74:77]
	v_mfma_f32_16x16x32_bf16 v[126:129], v[146:149], v[162:165], 0
	v_mfma_f32_16x16x32_bf16 v[126:129], v[150:153], v[166:169], v[126:129]
	v_mfma_f32_16x16x32_bf16 v[102:105], v[146:149], v[170:173], 0
	v_mfma_f32_16x16x32_bf16 v[102:105], v[150:153], v[174:177], v[102:105]
	v_mfma_f32_16x16x32_bf16 v[86:89], v[146:149], v[178:181], 0
	v_mfma_f32_16x16x32_bf16 v[86:89], v[150:153], v[182:185], v[86:89]
	v_mfma_f32_16x16x32_bf16 v[70:73], v[146:149], v[186:189], 0
	v_mfma_f32_16x16x32_bf16 v[70:73], v[150:153], v[190:193], v[70:73]
	v_mfma_f32_16x16x32_bf16 v[122:125], v[154:157], v[162:165], 0
	v_mfma_f32_16x16x32_bf16 v[122:125], v[158:161], v[166:169], v[122:125]
	v_mfma_f32_16x16x32_bf16 v[98:101], v[154:157], v[170:173], 0
	v_mfma_f32_16x16x32_bf16 v[98:101], v[158:161], v[174:177], v[98:101]
	v_mfma_f32_16x16x32_bf16 v[82:85], v[154:157], v[178:181], 0
	v_mfma_f32_16x16x32_bf16 v[82:85], v[158:161], v[182:185], v[82:85]
	v_mfma_f32_16x16x32_bf16 v[66:69], v[154:157], v[186:189], 0
	v_mfma_f32_16x16x32_bf16 v[66:69], v[158:161], v[190:193], v[66:69]
; #define PG8_STAGE(bufoff, gbase, voff) do { _Pragma("unroll") for (int _i = 0; _i < 2; ++_i) \
;         __builtin_amdgcn_global_load_lds((const unsigned*)((const char*)(gbase) + (voff)[_i]), (PG8_LAS unsigned*)(lds + (bufoff) + ldsw + _i * 8192), 16, 0, 0); } while (0)
; #define PG8_LDA(dst, b, h) do { _Pragma("unroll") for (int m = 0; m < 4; ++m) _Pragma("unroll") for (int k = 0; k < 2; ++k) dst[m][k] = *(const PG8_LAS bf16x8*)(lds + PG8_SA(b, h) + aoff + m * 2048 + k * 1024); } while (0)
; #define PG8_MMA(ai, bj, At, Bt) do { __builtin_amdgcn_s_setprio(1); _Pragma("unroll") for (int m = 0; m < 4; ++m) _Pragma("unroll") for (int n = 0; n < 2; ++n) _Pragma("unroll") for (int k = 0; k < 2; ++k) \
;         acc[ai][bj][m][n] = __builtin_amdgcn_mfma_f32_16x16x32_bf16(Bt[n][k], At[m][k], acc[ai][bj][m][n], 0, 0, 0); __builtin_amdgcn_s_setprio(0); } while (0)
; #define PG8_WAIT_V(n) asm volatile("s_waitcnt vmcnt(" #n ")" ::: "memory")
; #define PG8_WAIT_L(n) asm volatile("s_waitcnt lgkmcnt(" #n ")" ::: "memory")
; #define PG8_BAR __builtin_amdgcn_s_barrier()
; #define PG8_SCHED __builtin_amdgcn_sched_barrier(0)
; template <class Epi, class Sched, bool ALIGN_EPI = false, bool SP2 = false>
; __device__ __forceinline__ void gemm_phase(PG8_LAS unsigned char* lds, const Gemm g, const Sched& S, const Epi& E) {
;     ...
;             PG8_LDA(At, 0, 1); PG8_STAGE(PG8_SB(0, 0), b2, voffB); PG8_STAGE(PG8_SB(0, 1), b2 + hstep, voffB); PG8_STAGE(PG8_SA(0, 0), a2, voffA);
;             PG8_WAIT_V(8); PG8_WAIT_L(0); PG8_BAR; PG8_MMA(1, 0, At, B0); PG8_MMA(1, 1, At, B1); PG8_BAR; PG8_SCHED;
.Lz274_0_join:
	s_setprio 0
	s_barrier
	s_add_i32 vcc_hi, vcc_hi, s6
	v_lshl_add_u64 v[210:211], s[38:39], 0, v[0:1]
	s_mov_b32 m0, vcc_hi
	ds_read_b128 v[162:165], v247 offset:16384
	ds_read_b128 v[166:169], v247 offset:17408
	ds_read_b128 v[170:173], v247 offset:18432
	ds_read_b128 v[174:177], v247 offset:19456
	ds_read_b128 v[178:181], v247 offset:20480
	ds_read_b128 v[182:185], v247 offset:21504
	ds_read_b128 v[186:189], v247 offset:22528
	ds_read_b128 v[190:193], v247 offset:23552
	global_load_lds_dwordx4 v[210:211], off
	s_add_i32 m0, vcc_hi, 0x2000
	v_lshl_add_u64 v[212:213], s[38:39], 0, v[204:205]
	s_add_u32 s38, s38, s58
	s_addc_u32 s39, s39, 0
	s_add_i32 s18, s18, s6
	global_load_lds_dwordx4 v[212:213], off
	v_lshl_add_u64 v[214:215], s[38:39], 0, v[0:1]
	s_mov_b32 m0, s18
	v_lshl_add_u64 v[216:217], s[38:39], 0, v[204:205]
	global_load_lds_dwordx4 v[214:215], off
	s_add_i32 m0, s18, 0x2000
	v_lshl_add_u64 v[218:219], s[46:47], 0, v[194:195]
	global_load_lds_dwordx4 v[216:217], off
	s_mov_b32 m0, s92
	v_lshl_add_u64 v[220:221], s[46:47], 0, v[202:203]
	global_load_lds_dwordx4 v[218:219], off
	s_mov_b32 m0, s93
	s_nop 0
	global_load_lds_dwordx4 v[220:221], off
	s_waitcnt vmcnt(8)
	s_waitcnt lgkmcnt(0)
	s_barrier
	s_setprio 1
	s_cmp_eq_u32 vcc_lo, 2
	s_cbranch_scc1 .Lz274_1_first
	v_mfma_f32_16x16x32_bf16 v[62:65], v[110:113], v[162:165], v[62:65]
	v_mfma_f32_16x16x32_bf16 v[62:65], v[118:121], v[166:169], v[62:65]
	v_mfma_f32_16x16x32_bf16 v[46:49], v[110:113], v[170:173], v[46:49]
	v_mfma_f32_16x16x32_bf16 v[46:49], v[118:121], v[174:177], v[46:49]
	v_mfma_f32_16x16x32_bf16 v[30:33], v[110:113], v[178:181], v[30:33]
	v_mfma_f32_16x16x32_bf16 v[30:33], v[118:121], v[182:185], v[30:33]
	v_mfma_f32_16x16x32_bf16 v[14:17], v[110:113], v[186:189], v[14:17]
	v_mfma_f32_16x16x32_bf16 v[14:17], v[118:121], v[190:193], v[14:17]
	v_mfma_f32_16x16x32_bf16 v[58:61], v[138:141], v[162:165], v[58:61]
	v_mfma_f32_16x16x32_bf16 v[58:61], v[142:145], v[166:169], v[58:61]
	v_mfma_f32_16x16x32_bf16 v[42:45], v[138:141], v[170:173], v[42:45]
	v_mfma_f32_16x16x32_bf16 v[42:45], v[142:145], v[174:177], v[42:45]
	v_mfma_f32_16x16x32_bf16 v[26:29], v[138:141], v[178:181], v[26:29]
	v_mfma_f32_16x16x32_bf16 v[26:29], v[142:145], v[182:185], v[26:29]
	v_mfma_f32_16x16x32_bf16 v[10:13], v[138:141], v[186:189], v[10:13]
	v_mfma_f32_16x16x32_bf16 v[10:13], v[142:145], v[190:193], v[10:13]
	v_mfma_f32_16x16x32_bf16 v[54:57], v[146:149], v[162:165], v[54:57]
	v_mfma_f32_16x16x32_bf16 v[54:57], v[150:153], v[166:169], v[54:57]
	v_mfma_f32_16x16x32_bf16 v[38:41], v[146:149], v[170:173], v[38:41]
	v_mfma_f32_16x16x32_bf16 v[38:41], v[150:153], v[174:177], v[38:41]
	v_mfma_f32_16x16x32_bf16 v[22:25], v[146:149], v[178:181], v[22:25]
	v_mfma_f32_16x16x32_bf16 v[22:25], v[150:153], v[182:185], v[22:25]
	v_mfma_f32_16x16x32_bf16 v[6:9], v[146:149], v[186:189], v[6:9]
	v_mfma_f32_16x16x32_bf16 v[6:9], v[150:153], v[190:193], v[6:9]
	v_mfma_f32_16x16x32_bf16 v[50:53], v[154:157], v[162:165], v[50:53]
	v_mfma_f32_16x16x32_bf16 v[50:53], v[158:161], v[166:169], v[50:53]
	v_mfma_f32_16x16x32_bf16 v[34:37], v[154:157], v[170:173], v[34:37]
	v_mfma_f32_16x16x32_bf16 v[34:37], v[158:161], v[174:177], v[34:37]
	v_mfma_f32_16x16x32_bf16 v[18:21], v[154:157], v[178:181], v[18:21]
	v_mfma_f32_16x16x32_bf16 v[18:21], v[158:161], v[182:185], v[18:21]
	v_mfma_f32_16x16x32_bf16 v[2:5], v[154:157], v[186:189], v[2:5]
	v_mfma_f32_16x16x32_bf16 v[2:5], v[158:161], v[190:193], v[2:5]
	s_branch .Lz274_1_join
.Lz274_1_first:
	v_mfma_f32_16x16x32_bf16 v[62:65], v[110:113], v[162:165], 0
	v_mfma_f32_16x16x32_bf16 v[62:65], v[118:121], v[166:169], v[62:65]
	v_mfma_f32_16x16x32_bf16 v[46:49], v[110:113], v[170:173], 0
	v_mfma_f32_16x16x32_bf16 v[46:49], v[118:121], v[174:177], v[46:49]
	v_mfma_f32_16x16x32_bf16 v[30:33], v[110:113], v[178:181], 0
	v_mfma_f32_16x16x32_bf16 v[30:33], v[118:121], v[182:185], v[30:33]
	v_mfma_f32_16x16x32_bf16 v[14:17], v[110:113], v[186:189], 0
	v_mfma_f32_16x16x32_bf16 v[14:17], v[118:121], v[190:193], v[14:17]
	v_mfma_f32_16x16x32_bf16 v[58:61], v[138:141], v[162:165], 0
	v_mfma_f32_16x16x32_bf16 v[58:61], v[142:145], v[166:169], v[58:61]
	v_mfma_f32_16x16x32_bf16 v[42:45], v[138:141], v[170:173], 0
	v_mfma_f32_16x16x32_bf16 v[42:45], v[142:145], v[174:177], v[42:45]
	v_mfma_f32_16x16x32_bf16 v[26:29], v[138:141], v[178:181], 0
	v_mfma_f32_16x16x32_bf16 v[26:29], v[142:145], v[182:185], v[26:29]
	v_mfma_f32_16x16x32_bf16 v[10:13], v[138:141], v[186:189], 0
	v_mfma_f32_16x16x32_bf16 v[10:13], v[142:145], v[190:193], v[10:13]
	v_mfma_f32_16x16x32_bf16 v[54:57], v[146:149], v[162:165], 0
	v_mfma_f32_16x16x32_bf16 v[54:57], v[150:153], v[166:169], v[54:57]
	v_mfma_f32_16x16x32_bf16 v[38:41], v[146:149], v[170:173], 0
	v_mfma_f32_16x16x32_bf16 v[38:41], v[150:153], v[174:177], v[38:41]
	v_mfma_f32_16x16x32_bf16 v[22:25], v[146:149], v[178:181], 0
	v_mfma_f32_16x16x32_bf16 v[22:25], v[150:153], v[182:185], v[22:25]
	v_mfma_f32_16x16x32_bf16 v[6:9], v[146:149], v[186:189], 0
	v_mfma_f32_16x16x32_bf16 v[6:9], v[150:153], v[190:193], v[6:9]
	v_mfma_f32_16x16x32_bf16 v[50:53], v[154:157], v[162:165], 0
	v_mfma_f32_16x16x32_bf16 v[50:53], v[158:161], v[166:169], v[50:53]
	v_mfma_f32_16x16x32_bf16 v[34:37], v[154:157], v[170:173], 0
	v_mfma_f32_16x16x32_bf16 v[34:37], v[158:161], v[174:177], v[34:37]
	v_mfma_f32_16x16x32_bf16 v[18:21], v[154:157], v[178:181], 0
	v_mfma_f32_16x16x32_bf16 v[18:21], v[158:161], v[182:185], v[18:21]
	v_mfma_f32_16x16x32_bf16 v[2:5], v[154:157], v[186:189], 0
	v_mfma_f32_16x16x32_bf16 v[2:5], v[158:161], v[190:193], v[2:5]
; #define PG8_STAGE(bufoff, gbase, voff) do { _Pragma("unroll") for (int _i = 0; _i < 2; ++_i) \
;         __builtin_amdgcn_global_load_lds((const unsigned*)((const char*)(gbase) + (voff)[_i]), (PG8_LAS unsigned*)(lds + (bufoff) + ldsw + _i * 8192), 16, 0, 0); } while (0)
; #define PG8_LDA(dst, b, h) do { _Pragma("unroll") for (int m = 0; m < 4; ++m) _Pragma("unroll") for (int k = 0; k < 2; ++k) dst[m][k] = *(const PG8_LAS bf16x8*)(lds + PG8_SA(b, h) + aoff + m * 2048 + k * 1024); } while (0)
; #define PG8_LDB(dst, b, h) do { _Pragma("unroll") for (int n = 0; n < 2; ++n) _Pragma("unroll") for (int k = 0; k < 2; ++k) dst[n][k] = *(const PG8_LAS bf16x8*)(lds + PG8_SB(b, h) + boff + n * 2048 + k * 1024); } while (0)
; #define PG8_MMA(ai, bj, At, Bt) do { __builtin_amdgcn_s_setprio(1); _Pragma("unroll") for (int m = 0; m < 4; ++m) _Pragma("unroll") for (int n = 0; n < 2; ++n) _Pragma("unroll") for (int k = 0; k < 2; ++k) \
;         acc[ai][bj][m][n] = __builtin_amdgcn_mfma_f32_16x16x32_bf16(Bt[n][k], At[m][k], acc[ai][bj][m][n], 0, 0, 0); __builtin_amdgcn_s_setprio(0); } while (0)
; #define PG8_WAIT_V(n) asm volatile("s_waitcnt vmcnt(" #n ")" ::: "memory")
; #define PG8_WAIT_L(n) asm volatile("s_waitcnt lgkmcnt(" #n ")" ::: "memory")
; #define PG8_BAR __builtin_amdgcn_s_barrier()
; #define PG8_SCHED __builtin_amdgcn_sched_barrier(0)
; template <class Epi, class Sched, bool ALIGN_EPI = false, bool SP2 = false>
; __device__ __forceinline__ void gemm_phase(PG8_LAS unsigned char* lds, const Gemm g, const Sched& S, const Epi& E) {
;     ...
;             PG8_LDB(B0, 1, 0); PG8_LDB(B1, 1, 1); PG8_SCHED; PG8_LDA(At, 1, 0); PG8_STAGE(PG8_SA(0, 1), a2 + hstep, voffA);
;             PG8_WAIT_V(8); PG8_WAIT_L(0); PG8_BAR; PG8_MMA(0, 0, At, B0); PG8_MMA(0, 1, At, B1); PG8_BAR; PG8_SCHED;
.Lz274_1_join:
	s_setprio 0
	s_barrier
	s_add_i32 s18, 0, 0x18000
	s_add_i32 vcc_hi, 0, 0x1c000
	v_add_u32_e32 v142, s18, v245
	v_add_u32_e32 v158, vcc_hi, v245
	ds_read_b128 v[110:113], v142
	ds_read_b128 v[118:121], v142 offset:1024
	ds_read_b128 v[138:141], v142 offset:2048
	ds_read_b128 v[142:145], v142 offset:3072
	ds_read_b128 v[146:149], v158
	ds_read_b128 v[150:153], v158 offset:1024
	ds_read_b128 v[154:157], v158 offset:2048
	ds_read_b128 v[158:161], v158 offset:3072
	s_add_u32 s38, s46, s58
	s_addc_u32 s39, s47, 0
	s_mov_b32 m0, s94
	v_lshl_add_u64 v[222:223], s[38:39], 0, v[194:195]
	ds_read_b128 v[162:165], v247 offset:32768
	ds_read_b128 v[166:169], v247 offset:33792
	ds_read_b128 v[170:173], v247 offset:34816
	ds_read_b128 v[174:177], v247 offset:35840
	ds_read_b128 v[178:181], v247 offset:36864
	ds_read_b128 v[182:185], v247 offset:37888
	ds_read_b128 v[186:189], v247 offset:38912
	ds_read_b128 v[190:193], v247 offset:39936
	global_load_lds_dwordx4 v[222:223], off
	v_lshl_add_u64 v[222:223], s[38:39], 0, v[202:203]
	s_mov_b32 m0, s95
	s_nop 0
	global_load_lds_dwordx4 v[222:223], off
	s_waitcnt vmcnt(8)
	s_waitcnt lgkmcnt(0)
	s_barrier
	s_setprio 1
	v_mfma_f32_16x16x32_bf16 v[130:133], v[110:113], v[162:165], v[130:133]
	v_mfma_f32_16x16x32_bf16 v[130:133], v[118:121], v[166:169], v[130:133]
	v_mfma_f32_16x16x32_bf16 v[114:117], v[110:113], v[170:173], v[114:117]
	v_mfma_f32_16x16x32_bf16 v[114:117], v[118:121], v[174:177], v[114:117]
	v_mfma_f32_16x16x32_bf16 v[94:97], v[110:113], v[178:181], v[94:97]
	v_mfma_f32_16x16x32_bf16 v[94:97], v[118:121], v[182:185], v[94:97]
	v_mfma_f32_16x16x32_bf16 v[78:81], v[110:113], v[186:189], v[78:81]
	v_mfma_f32_16x16x32_bf16 v[78:81], v[118:121], v[190:193], v[78:81]
	v_mfma_f32_16x16x32_bf16 v[134:137], v[138:141], v[162:165], v[134:137]
	v_mfma_f32_16x16x32_bf16 v[134:137], v[142:145], v[166:169], v[134:137]
	v_mfma_f32_16x16x32_bf16 v[106:109], v[138:141], v[170:173], v[106:109]
	v_mfma_f32_16x16x32_bf16 v[106:109], v[142:145], v[174:177], v[106:109]
	v_mfma_f32_16x16x32_bf16 v[90:93], v[138:141], v[178:181], v[90:93]
	v_mfma_f32_16x16x32_bf16 v[90:93], v[142:145], v[182:185], v[90:93]
	v_mfma_f32_16x16x32_bf16 v[74:77], v[138:141], v[186:189], v[74:77]
	v_mfma_f32_16x16x32_bf16 v[74:77], v[142:145], v[190:193], v[74:77]
	v_mfma_f32_16x16x32_bf16 v[126:129], v[146:149], v[162:165], v[126:129]
	v_mfma_f32_16x16x32_bf16 v[126:129], v[150:153], v[166:169], v[126:129]
	v_mfma_f32_16x16x32_bf16 v[102:105], v[146:149], v[170:173], v[102:105]
	v_mfma_f32_16x16x32_bf16 v[102:105], v[150:153], v[174:177], v[102:105]
	v_mfma_f32_16x16x32_bf16 v[86:89], v[146:149], v[178:181], v[86:89]
	v_mfma_f32_16x16x32_bf16 v[86:89], v[150:153], v[182:185], v[86:89]
	v_mfma_f32_16x16x32_bf16 v[70:73], v[146:149], v[186:189], v[70:73]
	v_mfma_f32_16x16x32_bf16 v[70:73], v[150:153], v[190:193], v[70:73]
	v_mfma_f32_16x16x32_bf16 v[122:125], v[154:157], v[162:165], v[122:125]
	v_mfma_f32_16x16x32_bf16 v[122:125], v[158:161], v[166:169], v[122:125]
	v_mfma_f32_16x16x32_bf16 v[98:101], v[154:157], v[170:173], v[98:101]
	v_mfma_f32_16x16x32_bf16 v[98:101], v[158:161], v[174:177], v[98:101]
	v_mfma_f32_16x16x32_bf16 v[82:85], v[154:157], v[178:181], v[82:85]
	v_mfma_f32_16x16x32_bf16 v[82:85], v[158:161], v[182:185], v[82:85]
	v_mfma_f32_16x16x32_bf16 v[66:69], v[154:157], v[186:189], v[66:69]
	v_mfma_f32_16x16x32_bf16 v[66:69], v[158:161], v[190:193], v[66:69]
	s_setprio 0
	s_barrier
; #define PG8_STAGE(bufoff, gbase, voff) do { _Pragma("unroll") for (int _i = 0; _i < 2; ++_i) \
;         __builtin_amdgcn_global_load_lds((const unsigned*)((const char*)(gbase) + (voff)[_i]), (PG8_LAS unsigned*)(lds + (bufoff) + ldsw + _i * 8192), 16, 0, 0); } while (0)
; #define PG8_LDA(dst, b, h) do { _Pragma("unroll") for (int m = 0; m < 4; ++m) _Pragma("unroll") for (int k = 0; k < 2; ++k) dst[m][k] = *(const PG8_LAS bf16x8*)(lds + PG8_SA(b, h) + aoff + m * 2048 + k * 1024); } while (0)
; #define PG8_MMA(ai, bj, At, Bt) do { __builtin_amdgcn_s_setprio(1); _Pragma("unroll") for (int m = 0; m < 4; ++m) _Pragma("unroll") for (int n = 0; n < 2; ++n) _Pragma("unroll") for (int k = 0; k < 2; ++k) \
;         acc[ai][bj][m][n] = __builtin_amdgcn_mfma_f32_16x16x32_bf16(Bt[n][k], At[m][k], acc[ai][bj][m][n], 0, 0, 0); __builtin_amdgcn_s_setprio(0); } while (0)
; #define PG8_WAIT_V(n) asm volatile("s_waitcnt vmcnt(" #n ")" ::: "memory")
; #define PG8_WAIT_L(n) asm volatile("s_waitcnt lgkmcnt(" #n ")" ::: "memory")
; #define PG8_BAR __builtin_amdgcn_s_barrier()
; #define PG8_SCHED __builtin_amdgcn_sched_barrier(0)
; template <class Epi, class Sched, bool ALIGN_EPI = false, bool SP2 = false>
; __device__ __forceinline__ void gemm_phase(PG8_LAS unsigned char* lds, const Gemm g, const Sched& S, const Epi& E) {
;     ...
;         for (int t = 0; t < nt; t += 2) {
;             const bool last = (t == nt - 2);
;     ...
;             PG8_LDA(At, 1, 1); PG8_STAGE(PG8_SB(1, 0), b3, voffB); PG8_STAGE(PG8_SB(1, 1), b3 + hstep, voffB); PG8_STAGE(PG8_SA(1, 0), a3, voffA);
;             PG8_WAIT_V(8); PG8_WAIT_L(0); PG8_BAR; PG8_MMA(1, 0, At, B0); PG8_MMA(1, 1, At, B1); PG8_BAR; PG8_SCHED;
	s_add_i32 s18, s18, s6
	v_lshl_add_u64 v[210:211], v[210:211], 0, s[30:31]
	s_mov_b32 m0, s18
	ds_read_b128 v[162:165], v247 offset:49152
	ds_read_b128 v[166:169], v247 offset:50176
	ds_read_b128 v[170:173], v247 offset:51200
	ds_read_b128 v[174:177], v247 offset:52224
	ds_read_b128 v[178:181], v247 offset:53248
	ds_read_b128 v[182:185], v247 offset:54272
	ds_read_b128 v[186:189], v247 offset:55296
	ds_read_b128 v[190:193], v247 offset:56320
	global_load_lds_dwordx4 v[210:211], off
	v_lshl_add_u64 v[210:211], v[212:213], 0, s[30:31]
	s_add_i32 m0, s18, 0x2000
	s_add_i32 s18, vcc_hi, s6
	global_load_lds_dwordx4 v[210:211], off
	v_lshl_add_u64 v[210:211], v[214:215], 0, s[30:31]
	s_mov_b32 m0, s18
	s_nop 0
	global_load_lds_dwordx4 v[210:211], off
	v_lshl_add_u64 v[210:211], v[216:217], 0, s[30:31]
	s_add_i32 m0, s18, 0x2000
	s_nop 0
	global_load_lds_dwordx4 v[210:211], off
	v_lshl_add_u64 v[210:211], v[218:219], 0, s[30:31]
	s_mov_b32 m0, s97
	s_nop 0
	global_load_lds_dwordx4 v[210:211], off
	v_lshl_add_u64 v[210:211], v[220:221], 0, s[30:31]
	s_mov_b32 m0, s98
	s_nop 0
	global_load_lds_dwordx4 v[210:211], off
	s_waitcnt vmcnt(8)
	s_waitcnt lgkmcnt(0)
	s_barrier
	s_setprio 1
	v_mfma_f32_16x16x32_bf16 v[62:65], v[110:113], v[162:165], v[62:65]
	v_mfma_f32_16x16x32_bf16 v[62:65], v[118:121], v[166:169], v[62:65]
	v_mfma_f32_16x16x32_bf16 v[46:49], v[110:113], v[170:173], v[46:49]
	v_mfma_f32_16x16x32_bf16 v[46:49], v[118:121], v[174:177], v[46:49]
	v_mfma_f32_16x16x32_bf16 v[30:33], v[110:113], v[178:181], v[30:33]
	v_mfma_f32_16x16x32_bf16 v[30:33], v[118:121], v[182:185], v[30:33]
	v_mfma_f32_16x16x32_bf16 v[14:17], v[110:113], v[186:189], v[14:17]
	v_mfma_f32_16x16x32_bf16 v[14:17], v[118:121], v[190:193], v[14:17]
	v_mfma_f32_16x16x32_bf16 v[58:61], v[138:141], v[162:165], v[58:61]
	v_mfma_f32_16x16x32_bf16 v[58:61], v[142:145], v[166:169], v[58:61]
	v_mfma_f32_16x16x32_bf16 v[42:45], v[138:141], v[170:173], v[42:45]
	v_mfma_f32_16x16x32_bf16 v[42:45], v[142:145], v[174:177], v[42:45]
	v_mfma_f32_16x16x32_bf16 v[26:29], v[138:141], v[178:181], v[26:29]
	v_mfma_f32_16x16x32_bf16 v[26:29], v[142:145], v[182:185], v[26:29]
	v_mfma_f32_16x16x32_bf16 v[10:13], v[138:141], v[186:189], v[10:13]
	v_mfma_f32_16x16x32_bf16 v[10:13], v[142:145], v[190:193], v[10:13]
	v_mfma_f32_16x16x32_bf16 v[54:57], v[146:149], v[162:165], v[54:57]
	v_mfma_f32_16x16x32_bf16 v[54:57], v[150:153], v[166:169], v[54:57]
	v_mfma_f32_16x16x32_bf16 v[38:41], v[146:149], v[170:173], v[38:41]
	v_mfma_f32_16x16x32_bf16 v[38:41], v[150:153], v[174:177], v[38:41]
	v_mfma_f32_16x16x32_bf16 v[22:25], v[146:149], v[178:181], v[22:25]
	v_mfma_f32_16x16x32_bf16 v[22:25], v[150:153], v[182:185], v[22:25]
	v_mfma_f32_16x16x32_bf16 v[6:9], v[146:149], v[186:189], v[6:9]
	v_mfma_f32_16x16x32_bf16 v[6:9], v[150:153], v[190:193], v[6:9]
	v_mfma_f32_16x16x32_bf16 v[50:53], v[154:157], v[162:165], v[50:53]
	v_mfma_f32_16x16x32_bf16 v[50:53], v[158:161], v[166:169], v[50:53]
	v_mfma_f32_16x16x32_bf16 v[34:37], v[154:157], v[170:173], v[34:37]
	v_mfma_f32_16x16x32_bf16 v[34:37], v[158:161], v[174:177], v[34:37]
	v_mfma_f32_16x16x32_bf16 v[18:21], v[154:157], v[178:181], v[18:21]
	v_mfma_f32_16x16x32_bf16 v[18:21], v[158:161], v[182:185], v[18:21]
	v_mfma_f32_16x16x32_bf16 v[2:5], v[154:157], v[186:189], v[2:5]
	v_mfma_f32_16x16x32_bf16 v[2:5], v[158:161], v[190:193], v[2:5]
	s_setprio 0
	s_barrier
	s_add_u32 s48, s48, 0x100
	s_addc_u32 s49, s49, 0
	s_add_u32 s50, s50, 0x100
	s_addc_u32 s51, s51, 0
	s_cmp_ge_u32 vcc_lo, s96
	s_mov_b32 s46, vcc_lo
	s_cbranch_scc0 .LBB0_274
	s_and_b64 vcc, exec, s[72:73]
	s_cbranch_vccz .LBB0_277
	s_barrier

; #define PG8_BAR __builtin_amdgcn_s_barrier()
; template <class Epi, class Sched, bool ALIGN_EPI = false, bool SP2 = false>
; __device__ __forceinline__ void gemm_phase(PG8_LAS unsigned char* lds, const Gemm g, const Sched& S, const Epi& E) {
;     ...
;         if (!has_next) break;
; #pragma unroll
;         for (int a = 0; a < 2; ++a)
; #pragma unroll
;             for (int b = 0; b < 2; ++b)
; #pragma unroll
;                 for (int m = 0; m < 4; ++m)
; #pragma unroll
;                     for (int n = 0; n < 2; ++n) { unsigned long long lo_, hi_; asm volatile("v_mov_b64 %0, 0\n\tv_mov_b64 %1, 0" : "=v"(lo_), "=v"(hi_)); acc[a][b][m][n] = __builtin_bit_cast(f32x4, (u64x2_t){lo_, hi_}); }
;         cur = nxt; cA = nA; cB = nB; ++ui;
;         if constexpr (ALIGN_EPI) { if (wr == 1) PG8_BAR; }
.LBB0_381:
	s_and_b64 vcc, exec, s[44:45]
	s_mov_b64 s[44:45], -1
	s_cbranch_vccnz .LBB0_259
	s_andn2_b64 vcc, exec, s[60:61]
	s_waitcnt lgkmcnt(0)
	s_cbranch_vccnz .LBB0_258
	s_barrier
	s_branch .LBB0_258

; #define PG8_STAGE(bufoff, gbase, voff) do { _Pragma("unroll") for (int _i = 0; _i < 2; ++_i) \
;         __builtin_amdgcn_global_load_lds((const unsigned*)((const char*)(gbase) + (voff)[_i]), (PG8_LAS unsigned*)(lds + (bufoff) + ldsw + _i * 8192), 16, 0, 0); } while (0)
; #define PG8_WAIT_V(n) asm volatile("s_waitcnt vmcnt(" #n ")" ::: "memory")
; #define PG8_BAR __builtin_amdgcn_s_barrier()
; template <class Epi, class Sched, bool ALIGN_EPI = false, bool SP2 = false>
; __device__ __forceinline__ void gemm_phase(PG8_LAS unsigned char* lds, const Gemm g, const Sched& S, const Epi& E) {
;     ...
;     const int tid = tid_, wid = __builtin_amdgcn_readfirstlane(tid >> 6), lane = tid & 63, wr = wid >> 2, wc = wid & 3, fr = lane & 15, fq = lane >> 4;
;     const int K = g.K, nt = K / BK;
;     unsigned voffA[2], voffB[2];
; #pragma unroll
;     for (int i = 0; i < 2; ++i) { int R, C; stage_rc(tid * 16 + i * 8192, R, C); const int Rb = Epi::PERM ? ((R & ~31) + perm32(R & 31)) : R;
;         voffA[i] = (unsigned)(R * K + C) * 2u; voffB[i] = (unsigned)(Rb * K + C) * 2u; }
;     const size_t kstep = (size_t)(BK * 2);
;     const size_t hstep = (size_t)HALF * K * 2;
;     const size_t tstep = 2 * hstep;
;     const unsigned ldsw = (unsigned)wid * 1024u;
;     const int aoff = lds_byte(wr * 64 + fr, fq * 8), boff = lds_byte(wc * 32 + fr, fq * 8);
;     ...
;     const char* cA = (const char*)g.A + (size_t)cur.pm * tstep; const char* cB = (const char*)g.Bt + (size_t)cur.pn * tstep;
;     S.a_ready(cur);
;     if constexpr (SP2) {
;         PG8_STAGE(PG8_SB(0, 0), cB, voffB); PG8_STAGE(PG8_SB(0, 1), cB + hstep, voffB); PG8_STAGE(PG8_SA(0, 0), cA, voffA); PG8_STAGE(PG8_SA(0, 1), cA + hstep, voffA);
;         if (wr == 1) PG8_BAR;
;         PG8_WAIT_V(2); PG8_BAR;
;         PG8_STAGE(PG8_SB(1, 0), cB + kstep, voffB); PG8_STAGE(PG8_SA(1, 0), cA + kstep, voffA); PG8_STAGE(PG8_SB(1, 1), cB + hstep + kstep, voffB);
;         PG8_WAIT_V(6); PG8_BAR;
.LBB0_394:
	s_andn2_b64 vcc, exec, s[8:9]
	s_cbranch_vccnz .LBB0_491
	v_readlane_b32 s4, v253, 16
	v_mov_b32_e32 v146, v230
	v_readlane_b32 s5, v253, 17
	s_andn2_b64 vcc, exec, s[4:5]
	v_readfirstlane_b32 s6, v146
	s_cbranch_vccnz .LBB0_491
	v_lshlrev_b32_e32 v2, 4, v146
	v_add_u32_e32 v3, 0x2000, v2
	v_ashrrev_i32_e32 v0, 31, v3
	v_lshrrev_b32_e32 v0, 22, v0
	v_add_u32_e32 v0, v3, v0
	v_ashrrev_i32_e32 v0, 10, v0
	v_mul_i32_i24_e32 v4, 0x400, v0
	v_sub_u32_e32 v3, v3, v4
	v_lshrrev_b32_e32 v4, 4, v3
	v_bitop3_b32 v3, v4, v3, 32 bitop3:0x6c
	v_ashrrev_i32_e32 v4, 31, v3
	v_lshrrev_b32_e32 v4, 26, v4
	v_add_u32_e32 v4, v3, v4
	v_lshlrev_b32_e32 v5, 3, v0
	v_ashrrev_i32_e32 v147, 6, v4
	v_and_b32_e32 v5, -16, v5
	v_add_u32_e32 v5, v147, v5
	v_and_b32_e32 v6, 3, v147
	s_mov_b32 s8, 0x1fffe0
	v_lshrrev_b32_e32 v7, 2, v5
	v_lshlrev_b32_e32 v8, 1, v5
	v_and_b32_e32 v4, 0xc0, v4
	v_and_or_b32 v6, v5, s8, v6
	v_and_b32_e32 v7, 4, v7
	v_and_b32_e32 v8, 24, v8
	v_sub_u32_e32 v3, v3, v4
	v_or3_b32 v6, v6, v7, v8
	v_lshlrev_b32_e32 v7, 5, v0
	v_ashrrev_i16_sdwa v3, v244, sext(v3) dst_sel:DWORD dst_unused:UNUSED_PAD src0_sel:DWORD src1_sel:BYTE_0
	v_and_b32_e32 v7, 32, v7
	v_bfe_i32 v148, v3, 0, 16
	v_add_lshl_u32 v3, v7, v148, 1
	v_lshl_add_u32 v130, v6, 11, v3
	v_lshl_add_u32 v132, v5, 11, v3
	v_bfe_i32 v3, v146, 27, 1
	v_lshrrev_b32_e32 v3, 22, v3
	v_add_u32_e32 v3, v2, v3
	v_and_b32_e32 v3, 0xfffffc00, v3
	v_sub_u32_e32 v2, v2, v3
	v_lshrrev_b32_e32 v3, 4, v2
	v_ashrrev_i32_e32 v4, 31, v146
	v_bitop3_b32 v2, v3, v2, 32 bitop3:0x6c
	v_lshrrev_b32_e32 v4, 26, v4
	v_ashrrev_i32_e32 v3, 31, v2
	v_add_u32_e32 v4, v146, v4
	v_lshrrev_b32_e32 v3, 26, v3
	v_ashrrev_i32_e32 v150, 6, v4
	v_add_u32_e32 v3, v2, v3
	v_lshlrev_b32_e32 v4, 3, v150
	s_waitcnt lgkmcnt(0)
	s_add_u32 s4, s14, 0x4000000
	v_ashrrev_i32_e32 v149, 6, v3
	v_and_b32_e32 v4, -16, v4
	s_addc_u32 s5, s15, 0
	v_add_u32_e32 v4, v149, v4
	s_add_u32 s58, s14, 0x400000
	v_and_b32_e32 v5, 3, v149
	v_lshrrev_b32_e32 v6, 2, v4
	v_lshlrev_b32_e32 v7, 1, v4
	v_and_b32_e32 v3, 0xc0, v3
	s_addc_u32 s74, s15, 0
	s_ashr_i32 s10, s6, 6
	v_and_or_b32 v5, v4, s8, v5
	v_and_b32_e32 v6, 4, v6
	v_and_b32_e32 v7, 24, v7
	v_sub_u32_e32 v2, v2, v3
	s_ashr_i32 s7, s6, 8
	s_lshl_b32 s75, s10, 10
	v_or3_b32 v5, v5, v6, v7
	v_lshlrev_b32_e32 v6, 5, v150
	v_ashrrev_i16_sdwa v2, v244, sext(v2) dst_sel:DWORD dst_unused:UNUSED_PAD src0_sel:DWORD src1_sel:BYTE_0
	v_readlane_b32 s8, v254, 20
	v_and_b32_e32 v6, 32, v6
	v_bfe_i32 v151, v2, 0, 16
	v_readlane_b32 s9, v254, 21
	s_add_u32 s46, s58, s8
	v_add_lshl_u32 v2, v6, v151, 1
	s_addc_u32 s47, s74, s9
	s_add_i32 s76, s75, 0
	v_lshl_add_u32 v134, v5, 11, v2
	s_add_i32 m0, s76, 0x10000
	v_lshl_add_u32 v136, v4, 11, v2
	s_waitcnt vmcnt(0)
	global_load_lds_dwordx4 v134, s[46:47]
	s_add_i32 m0, s76, 0x12000
	s_add_u32 s8, s46, 0x40000
	global_load_lds_dwordx4 v130, s[46:47]
	s_addc_u32 s9, s47, 0
	s_add_i32 m0, s76, 0x14000
	v_mov_b32_e32 v135, v1
	global_load_lds_dwordx4 v134, s[8:9]
	s_add_i32 m0, s76, 0x16000
	v_mov_b32_e32 v131, v1
	global_load_lds_dwordx4 v130, s[8:9]
	v_readlane_b32 s8, v254, 50
	v_readlane_b32 s9, v254, 51
	s_add_u32 s48, s4, s8
	s_addc_u32 s49, s5, s9
	s_add_i32 s77, s76, 0x2000
	s_mov_b32 m0, s76
	s_add_u32 s8, s48, 0x40000
	global_load_lds_dwordx4 v136, s[48:49]
	s_mov_b32 m0, s77
	s_addc_u32 s9, s49, 0
	s_add_i32 s78, s76, 0x4000
	global_load_lds_dwordx4 v132, s[48:49]
	s_mov_b32 m0, s78
	s_add_i32 s79, s76, 0x6000
	global_load_lds_dwordx4 v136, s[8:9]
	s_mov_b32 m0, s79
	v_mov_b32_e32 v137, v1
	global_load_lds_dwordx4 v132, s[8:9]
	v_mov_b32_e32 v133, v1
	s_cmp_eq_u32 s7, 1
	s_cselect_b64 s[8:9], -1, 0
	s_cmp_lg_u32 s7, 1
	v_lshl_add_u64 v[144:145], s[46:47], 0, v[134:135]
	v_lshl_add_u64 v[142:143], s[46:47], 0, v[130:131]
	v_lshl_add_u64 v[140:141], s[48:49], 0, v[136:137]
	v_lshl_add_u64 v[138:139], s[48:49], 0, v[132:133]
	s_cbranch_scc1 .LBB0_398
	s_barrier

; #define PG8_STAGE(bufoff, gbase, voff) do { _Pragma("unroll") for (int _i = 0; _i < 2; ++_i) \
;         __builtin_amdgcn_global_load_lds((const unsigned*)((const char*)(gbase) + (voff)[_i]), (PG8_LAS unsigned*)(lds + (bufoff) + ldsw + _i * 8192), 16, 0, 0); } while (0)
; #define PG8_LDA(dst, b, h) do { _Pragma("unroll") for (int m = 0; m < 4; ++m) _Pragma("unroll") for (int k = 0; k < 2; ++k) dst[m][k] = *(const PG8_LAS bf16x8*)(lds + PG8_SA(b, h) + aoff + m * 2048 + k * 1024); } while (0)
; #define PG8_LDB(dst, b, h) do { _Pragma("unroll") for (int n = 0; n < 2; ++n) _Pragma("unroll") for (int k = 0; k < 2; ++k) dst[n][k] = *(const PG8_LAS bf16x8*)(lds + PG8_SB(b, h) + boff + n * 2048 + k * 1024); } while (0)
; #define PG8_MMA(ai, bj, At, Bt) do { __builtin_amdgcn_s_setprio(1); _Pragma("unroll") for (int m = 0; m < 4; ++m) _Pragma("unroll") for (int n = 0; n < 2; ++n) _Pragma("unroll") for (int k = 0; k < 2; ++k) \
;         acc[ai][bj][m][n] = __builtin_amdgcn_mfma_f32_16x16x32_bf16(Bt[n][k], At[m][k], acc[ai][bj][m][n], 0, 0, 0); __builtin_amdgcn_s_setprio(0); } while (0)
; #define PG8_WAIT_V(n) asm volatile("s_waitcnt vmcnt(" #n ")" ::: "memory")
; #define PG8_WAIT_L(n) asm volatile("s_waitcnt lgkmcnt(" #n ")" ::: "memory")
; #define PG8_BAR __builtin_amdgcn_s_barrier()
; #define PG8_SCHED __builtin_amdgcn_sched_barrier(0)
; template <class Epi, class Sched, bool ALIGN_EPI = false, bool SP2 = false>
; __device__ __forceinline__ void gemm_phase(PG8_LAS unsigned char* lds, const Gemm g, const Sched& S, const Epi& E) {
;     ...
;             PG8_LDB(B0, 0, 0); PG8_LDB(B1, 0, 1); PG8_SCHED; PG8_LDA(At, 0, 0); PG8_STAGE(PG8_SA(1, 1), a1 + hstep, voffA);
;             PG8_WAIT_V(8); PG8_WAIT_L(0); PG8_BAR; PG8_MMA(0, 0, At, B0); PG8_MMA(0, 1, At, B1); PG8_BAR; PG8_SCHED;
.LBB0_408:
	s_add_u32 s38, s48, 0xfffc0080
	s_addc_u32 s39, s49, -1
	s_add_i32 s85, 0, 0x10000
	s_cmp_eq_u32 s84, 12
	s_cselect_b32 s73, s21, s39
	s_cselect_b32 s72, s27, s38
	v_add_u32_e32 v0, s85, v167
	s_cselect_b32 s47, s29, s69
	s_cselect_b32 s46, s33, s53
	s_add_i32 s38, 0, 0x14000
	ds_read_b128 v[142:145], v0
	ds_read_b128 v[146:149], v0 offset:1024
	ds_read_b128 v[150:153], v0 offset:2048
	ds_read_b128 v[154:157], v0 offset:3072
	v_add_u32_e32 v0, s38, v167
	ds_read_b128 v[158:161], v0
	ds_read_b128 v[162:165], v0 offset:1024
	ds_read_b128 v[172:175], v0 offset:2048
	ds_read_b128 v[176:179], v0 offset:3072
	v_lshl_add_u64 v[218:219], s[48:49], 0, v[138:139]
	s_add_i32 m0, s76, 0xc000
	ds_read_b128 v[180:183], v170
	ds_read_b128 v[184:187], v170 offset:1024
	ds_read_b128 v[188:191], v170 offset:2048
	ds_read_b128 v[192:195], v170 offset:3072
	ds_read_b128 v[202:205], v170 offset:4096
	ds_read_b128 v[206:209], v170 offset:5120
	ds_read_b128 v[210:213], v170 offset:6144
	ds_read_b128 v[214:217], v170 offset:7168
	global_load_lds_dwordx4 v[218:219], off
	v_lshl_add_u64 v[218:219], s[48:49], 0, v[140:141]
	s_add_i32 m0, s76, 0xe000
	s_nop 0
	global_load_lds_dwordx4 v[218:219], off
	s_waitcnt vmcnt(8)
	s_waitcnt lgkmcnt(0)
	s_barrier
	s_setprio 1
	s_cmp_eq_u32 s84, -2
	s_cbranch_scc1 .Lz408_0_first
	v_mfma_f32_16x16x32_bf16 v[122:125], v[142:145], v[180:183], v[122:125]
	v_mfma_f32_16x16x32_bf16 v[122:125], v[146:149], v[184:187], v[122:125]
	v_mfma_f32_16x16x32_bf16 v[106:109], v[142:145], v[188:191], v[106:109]
	v_mfma_f32_16x16x32_bf16 v[106:109], v[146:149], v[192:195], v[106:109]
	v_mfma_f32_16x16x32_bf16 v[90:93], v[142:145], v[202:205], v[90:93]
	v_mfma_f32_16x16x32_bf16 v[90:93], v[146:149], v[206:209], v[90:93]
	v_mfma_f32_16x16x32_bf16 v[74:77], v[142:145], v[210:213], v[74:77]
	v_mfma_f32_16x16x32_bf16 v[74:77], v[146:149], v[214:217], v[74:77]
	v_mfma_f32_16x16x32_bf16 v[126:129], v[150:153], v[180:183], v[126:129]
	v_mfma_f32_16x16x32_bf16 v[126:129], v[154:157], v[184:187], v[126:129]
	v_mfma_f32_16x16x32_bf16 v[110:113], v[150:153], v[188:191], v[110:113]
	v_mfma_f32_16x16x32_bf16 v[110:113], v[154:157], v[192:195], v[110:113]
	v_mfma_f32_16x16x32_bf16 v[94:97], v[150:153], v[202:205], v[94:97]
	v_mfma_f32_16x16x32_bf16 v[94:97], v[154:157], v[206:209], v[94:97]
	v_mfma_f32_16x16x32_bf16 v[78:81], v[150:153], v[210:213], v[78:81]
	v_mfma_f32_16x16x32_bf16 v[78:81], v[154:157], v[214:217], v[78:81]
	v_mfma_f32_16x16x32_bf16 v[114:117], v[158:161], v[180:183], v[114:117]
	v_mfma_f32_16x16x32_bf16 v[114:117], v[162:165], v[184:187], v[114:117]
	v_mfma_f32_16x16x32_bf16 v[98:101], v[158:161], v[188:191], v[98:101]
	v_mfma_f32_16x16x32_bf16 v[98:101], v[162:165], v[192:195], v[98:101]
	v_mfma_f32_16x16x32_bf16 v[82:85], v[158:161], v[202:205], v[82:85]
	v_mfma_f32_16x16x32_bf16 v[82:85], v[162:165], v[206:209], v[82:85]
	v_mfma_f32_16x16x32_bf16 v[66:69], v[158:161], v[210:213], v[66:69]
	v_mfma_f32_16x16x32_bf16 v[66:69], v[162:165], v[214:217], v[66:69]
	v_mfma_f32_16x16x32_bf16 v[118:121], v[172:175], v[180:183], v[118:121]
	v_mfma_f32_16x16x32_bf16 v[118:121], v[176:179], v[184:187], v[118:121]
	v_mfma_f32_16x16x32_bf16 v[102:105], v[172:175], v[188:191], v[102:105]
	v_mfma_f32_16x16x32_bf16 v[102:105], v[176:179], v[192:195], v[102:105]
	v_mfma_f32_16x16x32_bf16 v[86:89], v[172:175], v[202:205], v[86:89]
	v_mfma_f32_16x16x32_bf16 v[86:89], v[176:179], v[206:209], v[86:89]
	v_mfma_f32_16x16x32_bf16 v[70:73], v[172:175], v[210:213], v[70:73]
	v_mfma_f32_16x16x32_bf16 v[70:73], v[176:179], v[214:217], v[70:73]
	s_branch .Lz408_0_join
.Lz408_0_first:
	v_mfma_f32_16x16x32_bf16 v[122:125], v[142:145], v[180:183], 0
	v_mfma_f32_16x16x32_bf16 v[122:125], v[146:149], v[184:187], v[122:125]
	v_mfma_f32_16x16x32_bf16 v[106:109], v[142:145], v[188:191], 0
	v_mfma_f32_16x16x32_bf16 v[106:109], v[146:149], v[192:195], v[106:109]
	v_mfma_f32_16x16x32_bf16 v[90:93], v[142:145], v[202:205], 0
	v_mfma_f32_16x16x32_bf16 v[90:93], v[146:149], v[206:209], v[90:93]
	v_mfma_f32_16x16x32_bf16 v[74:77], v[142:145], v[210:213], 0
	v_mfma_f32_16x16x32_bf16 v[74:77], v[146:149], v[214:217], v[74:77]
	v_mfma_f32_16x16x32_bf16 v[126:129], v[150:153], v[180:183], 0
	v_mfma_f32_16x16x32_bf16 v[126:129], v[154:157], v[184:187], v[126:129]
	v_mfma_f32_16x16x32_bf16 v[110:113], v[150:153], v[188:191], 0
	v_mfma_f32_16x16x32_bf16 v[110:113], v[154:157], v[192:195], v[110:113]
	v_mfma_f32_16x16x32_bf16 v[94:97], v[150:153], v[202:205], 0
	v_mfma_f32_16x16x32_bf16 v[94:97], v[154:157], v[206:209], v[94:97]
	v_mfma_f32_16x16x32_bf16 v[78:81], v[150:153], v[210:213], 0
	v_mfma_f32_16x16x32_bf16 v[78:81], v[154:157], v[214:217], v[78:81]
	v_mfma_f32_16x16x32_bf16 v[114:117], v[158:161], v[180:183], 0
	v_mfma_f32_16x16x32_bf16 v[114:117], v[162:165], v[184:187], v[114:117]
	v_mfma_f32_16x16x32_bf16 v[98:101], v[158:161], v[188:191], 0
	v_mfma_f32_16x16x32_bf16 v[98:101], v[162:165], v[192:195], v[98:101]
	v_mfma_f32_16x16x32_bf16 v[82:85], v[158:161], v[202:205], 0
	v_mfma_f32_16x16x32_bf16 v[82:85], v[162:165], v[206:209], v[82:85]
	v_mfma_f32_16x16x32_bf16 v[66:69], v[158:161], v[210:213], 0
	v_mfma_f32_16x16x32_bf16 v[66:69], v[162:165], v[214:217], v[66:69]
	v_mfma_f32_16x16x32_bf16 v[118:121], v[172:175], v[180:183], 0
	v_mfma_f32_16x16x32_bf16 v[118:121], v[176:179], v[184:187], v[118:121]
	v_mfma_f32_16x16x32_bf16 v[102:105], v[172:175], v[188:191], 0
	v_mfma_f32_16x16x32_bf16 v[102:105], v[176:179], v[192:195], v[102:105]
	v_mfma_f32_16x16x32_bf16 v[86:89], v[172:175], v[202:205], 0
	v_mfma_f32_16x16x32_bf16 v[86:89], v[176:179], v[206:209], v[86:89]
	v_mfma_f32_16x16x32_bf16 v[70:73], v[172:175], v[210:213], 0
	v_mfma_f32_16x16x32_bf16 v[70:73], v[176:179], v[214:217], v[70:73]
; #define PG8_STAGE(bufoff, gbase, voff) do { _Pragma("unroll") for (int _i = 0; _i < 2; ++_i) \
;         __builtin_amdgcn_global_load_lds((const unsigned*)((const char*)(gbase) + (voff)[_i]), (PG8_LAS unsigned*)(lds + (bufoff) + ldsw + _i * 8192), 16, 0, 0); } while (0)
; #define PG8_LDA(dst, b, h) do { _Pragma("unroll") for (int m = 0; m < 4; ++m) _Pragma("unroll") for (int k = 0; k < 2; ++k) dst[m][k] = *(const PG8_LAS bf16x8*)(lds + PG8_SA(b, h) + aoff + m * 2048 + k * 1024); } while (0)
; #define PG8_MMA(ai, bj, At, Bt) do { __builtin_amdgcn_s_setprio(1); _Pragma("unroll") for (int m = 0; m < 4; ++m) _Pragma("unroll") for (int n = 0; n < 2; ++n) _Pragma("unroll") for (int k = 0; k < 2; ++k) \
;         acc[ai][bj][m][n] = __builtin_amdgcn_mfma_f32_16x16x32_bf16(Bt[n][k], At[m][k], acc[ai][bj][m][n], 0, 0, 0); __builtin_amdgcn_s_setprio(0); } while (0)
; #define PG8_WAIT_V(n) asm volatile("s_waitcnt vmcnt(" #n ")" ::: "memory")
; #define PG8_WAIT_L(n) asm volatile("s_waitcnt lgkmcnt(" #n ")" ::: "memory")
; #define PG8_BAR __builtin_amdgcn_s_barrier()
; #define PG8_SCHED __builtin_amdgcn_sched_barrier(0)
; template <class Epi, class Sched, bool ALIGN_EPI = false, bool SP2 = false>
; __device__ __forceinline__ void gemm_phase(PG8_LAS unsigned char* lds, const Gemm g, const Sched& S, const Epi& E) {
;     ...
;             PG8_LDA(At, 0, 1); PG8_STAGE(PG8_SB(0, 0), b2, voffB); PG8_STAGE(PG8_SB(0, 1), b2 + hstep, voffB); PG8_STAGE(PG8_SA(0, 0), a2, voffA);
;             PG8_WAIT_V(8); PG8_WAIT_L(0); PG8_BAR; PG8_MMA(1, 0, At, B0); PG8_MMA(1, 1, At, B1); PG8_BAR; PG8_SCHED;
.Lz408_0_join:
	s_setprio 0
	s_barrier
	s_add_i32 s39, s85, s75
	v_lshl_add_u64 v[218:219], s[46:47], 0, v[134:135]
	s_mov_b32 m0, s39
	ds_read_b128 v[180:183], v170 offset:16384
	ds_read_b128 v[184:187], v170 offset:17408
	ds_read_b128 v[188:191], v170 offset:18432
	ds_read_b128 v[192:195], v170 offset:19456
	ds_read_b128 v[202:205], v170 offset:20480
	ds_read_b128 v[206:209], v170 offset:21504
	ds_read_b128 v[210:213], v170 offset:22528
	ds_read_b128 v[214:217], v170 offset:23552
	global_load_lds_dwordx4 v[218:219], off
	s_add_i32 m0, s39, 0x2000
	s_add_u32 s92, s46, 0x40000
	v_lshl_add_u64 v[220:221], s[46:47], 0, v[130:131]
	s_addc_u32 s93, s47, 0
	s_add_i32 s38, s38, s75
	global_load_lds_dwordx4 v[220:221], off
	v_lshl_add_u64 v[222:223], s[92:93], 0, v[134:135]
	s_mov_b32 m0, s38
	v_lshl_add_u64 v[224:225], s[72:73], 0, v[132:133]
	global_load_lds_dwordx4 v[222:223], off
	v_lshl_add_u64 v[222:223], s[92:93], 0, v[130:131]
	s_add_i32 m0, s38, 0x2000
	s_nop 0
	global_load_lds_dwordx4 v[222:223], off
	v_lshl_add_u64 v[222:223], s[72:73], 0, v[136:137]
	s_mov_b32 m0, s76
	s_nop 0
	global_load_lds_dwordx4 v[222:223], off
	s_mov_b32 m0, s77
	s_nop 0
	global_load_lds_dwordx4 v[224:225], off
	s_waitcnt vmcnt(8)
	s_waitcnt lgkmcnt(0)
	s_barrier
	s_setprio 1
	s_cmp_eq_u32 s84, -2
	s_cbranch_scc1 .Lz408_1_first
	v_mfma_f32_16x16x32_bf16 v[58:61], v[142:145], v[180:183], v[58:61]
	v_mfma_f32_16x16x32_bf16 v[58:61], v[146:149], v[184:187], v[58:61]
	v_mfma_f32_16x16x32_bf16 v[42:45], v[142:145], v[188:191], v[42:45]
	v_mfma_f32_16x16x32_bf16 v[42:45], v[146:149], v[192:195], v[42:45]
	v_mfma_f32_16x16x32_bf16 v[26:29], v[142:145], v[202:205], v[26:29]
	v_mfma_f32_16x16x32_bf16 v[26:29], v[146:149], v[206:209], v[26:29]
	v_mfma_f32_16x16x32_bf16 v[10:13], v[142:145], v[210:213], v[10:13]
	v_mfma_f32_16x16x32_bf16 v[10:13], v[146:149], v[214:217], v[10:13]
	v_mfma_f32_16x16x32_bf16 v[62:65], v[150:153], v[180:183], v[62:65]
	v_mfma_f32_16x16x32_bf16 v[62:65], v[154:157], v[184:187], v[62:65]
	v_mfma_f32_16x16x32_bf16 v[46:49], v[150:153], v[188:191], v[46:49]
	v_mfma_f32_16x16x32_bf16 v[46:49], v[154:157], v[192:195], v[46:49]
	v_mfma_f32_16x16x32_bf16 v[30:33], v[150:153], v[202:205], v[30:33]
	v_mfma_f32_16x16x32_bf16 v[30:33], v[154:157], v[206:209], v[30:33]
	v_mfma_f32_16x16x32_bf16 v[14:17], v[150:153], v[210:213], v[14:17]
	v_mfma_f32_16x16x32_bf16 v[14:17], v[154:157], v[214:217], v[14:17]
	v_mfma_f32_16x16x32_bf16 v[50:53], v[158:161], v[180:183], v[50:53]
	v_mfma_f32_16x16x32_bf16 v[50:53], v[162:165], v[184:187], v[50:53]
	v_mfma_f32_16x16x32_bf16 v[34:37], v[158:161], v[188:191], v[34:37]
	v_mfma_f32_16x16x32_bf16 v[34:37], v[162:165], v[192:195], v[34:37]
	v_mfma_f32_16x16x32_bf16 v[18:21], v[158:161], v[202:205], v[18:21]
	v_mfma_f32_16x16x32_bf16 v[18:21], v[162:165], v[206:209], v[18:21]
	v_mfma_f32_16x16x32_bf16 v[2:5], v[158:161], v[210:213], v[2:5]
	v_mfma_f32_16x16x32_bf16 v[2:5], v[162:165], v[214:217], v[2:5]
	v_mfma_f32_16x16x32_bf16 v[54:57], v[172:175], v[180:183], v[54:57]
	v_mfma_f32_16x16x32_bf16 v[54:57], v[176:179], v[184:187], v[54:57]
	v_mfma_f32_16x16x32_bf16 v[38:41], v[172:175], v[188:191], v[38:41]
	v_mfma_f32_16x16x32_bf16 v[38:41], v[176:179], v[192:195], v[38:41]
	v_mfma_f32_16x16x32_bf16 v[22:25], v[172:175], v[202:205], v[22:25]
	v_mfma_f32_16x16x32_bf16 v[22:25], v[176:179], v[206:209], v[22:25]
	v_mfma_f32_16x16x32_bf16 v[6:9], v[172:175], v[210:213], v[6:9]
	v_mfma_f32_16x16x32_bf16 v[6:9], v[176:179], v[214:217], v[6:9]
	s_branch .Lz408_1_join
.Lz408_1_first:
	v_mfma_f32_16x16x32_bf16 v[58:61], v[142:145], v[180:183], 0
	v_mfma_f32_16x16x32_bf16 v[58:61], v[146:149], v[184:187], v[58:61]
	v_mfma_f32_16x16x32_bf16 v[42:45], v[142:145], v[188:191], 0
	v_mfma_f32_16x16x32_bf16 v[42:45], v[146:149], v[192:195], v[42:45]
	v_mfma_f32_16x16x32_bf16 v[26:29], v[142:145], v[202:205], 0
	v_mfma_f32_16x16x32_bf16 v[26:29], v[146:149], v[206:209], v[26:29]
	v_mfma_f32_16x16x32_bf16 v[10:13], v[142:145], v[210:213], 0
	v_mfma_f32_16x16x32_bf16 v[10:13], v[146:149], v[214:217], v[10:13]
	v_mfma_f32_16x16x32_bf16 v[62:65], v[150:153], v[180:183], 0
	v_mfma_f32_16x16x32_bf16 v[62:65], v[154:157], v[184:187], v[62:65]
	v_mfma_f32_16x16x32_bf16 v[46:49], v[150:153], v[188:191], 0
	v_mfma_f32_16x16x32_bf16 v[46:49], v[154:157], v[192:195], v[46:49]
	v_mfma_f32_16x16x32_bf16 v[30:33], v[150:153], v[202:205], 0
	v_mfma_f32_16x16x32_bf16 v[30:33], v[154:157], v[206:209], v[30:33]
	v_mfma_f32_16x16x32_bf16 v[14:17], v[150:153], v[210:213], 0
	v_mfma_f32_16x16x32_bf16 v[14:17], v[154:157], v[214:217], v[14:17]
	v_mfma_f32_16x16x32_bf16 v[50:53], v[158:161], v[180:183], 0
	v_mfma_f32_16x16x32_bf16 v[50:53], v[162:165], v[184:187], v[50:53]
	v_mfma_f32_16x16x32_bf16 v[34:37], v[158:161], v[188:191], 0
	v_mfma_f32_16x16x32_bf16 v[34:37], v[162:165], v[192:195], v[34:37]
	v_mfma_f32_16x16x32_bf16 v[18:21], v[158:161], v[202:205], 0
	v_mfma_f32_16x16x32_bf16 v[18:21], v[162:165], v[206:209], v[18:21]
	v_mfma_f32_16x16x32_bf16 v[2:5], v[158:161], v[210:213], 0
	v_mfma_f32_16x16x32_bf16 v[2:5], v[162:165], v[214:217], v[2:5]
	v_mfma_f32_16x16x32_bf16 v[54:57], v[172:175], v[180:183], 0
	v_mfma_f32_16x16x32_bf16 v[54:57], v[176:179], v[184:187], v[54:57]
	v_mfma_f32_16x16x32_bf16 v[38:41], v[172:175], v[188:191], 0
	v_mfma_f32_16x16x32_bf16 v[38:41], v[176:179], v[192:195], v[38:41]
	v_mfma_f32_16x16x32_bf16 v[22:25], v[172:175], v[202:205], 0
	v_mfma_f32_16x16x32_bf16 v[22:25], v[176:179], v[206:209], v[22:25]
	v_mfma_f32_16x16x32_bf16 v[6:9], v[172:175], v[210:213], 0
	v_mfma_f32_16x16x32_bf16 v[6:9], v[176:179], v[214:217], v[6:9]
; #define PG8_STAGE(bufoff, gbase, voff) do { _Pragma("unroll") for (int _i = 0; _i < 2; ++_i) \
;         __builtin_amdgcn_global_load_lds((const unsigned*)((const char*)(gbase) + (voff)[_i]), (PG8_LAS unsigned*)(lds + (bufoff) + ldsw + _i * 8192), 16, 0, 0); } while (0)
; #define PG8_LDA(dst, b, h) do { _Pragma("unroll") for (int m = 0; m < 4; ++m) _Pragma("unroll") for (int k = 0; k < 2; ++k) dst[m][k] = *(const PG8_LAS bf16x8*)(lds + PG8_SA(b, h) + aoff + m * 2048 + k * 1024); } while (0)
; #define PG8_LDB(dst, b, h) do { _Pragma("unroll") for (int n = 0; n < 2; ++n) _Pragma("unroll") for (int k = 0; k < 2; ++k) dst[n][k] = *(const PG8_LAS bf16x8*)(lds + PG8_SB(b, h) + boff + n * 2048 + k * 1024); } while (0)
; #define PG8_MMA(ai, bj, At, Bt) do { __builtin_amdgcn_s_setprio(1); _Pragma("unroll") for (int m = 0; m < 4; ++m) _Pragma("unroll") for (int n = 0; n < 2; ++n) _Pragma("unroll") for (int k = 0; k < 2; ++k) \
;         acc[ai][bj][m][n] = __builtin_amdgcn_mfma_f32_16x16x32_bf16(Bt[n][k], At[m][k], acc[ai][bj][m][n], 0, 0, 0); __builtin_amdgcn_s_setprio(0); } while (0)
; #define PG8_WAIT_V(n) asm volatile("s_waitcnt vmcnt(" #n ")" ::: "memory")
; #define PG8_WAIT_L(n) asm volatile("s_waitcnt lgkmcnt(" #n ")" ::: "memory")
; #define PG8_BAR __builtin_amdgcn_s_barrier()
; #define PG8_SCHED __builtin_amdgcn_sched_barrier(0)
; template <class Epi, class Sched, bool ALIGN_EPI = false, bool SP2 = false>
; __device__ __forceinline__ void gemm_phase(PG8_LAS unsigned char* lds, const Gemm g, const Sched& S, const Epi& E) {
;     ...
;             PG8_LDB(B0, 1, 0); PG8_LDB(B1, 1, 1); PG8_SCHED; PG8_LDA(At, 1, 0); PG8_STAGE(PG8_SA(0, 1), a2 + hstep, voffA);
;             PG8_WAIT_V(8); PG8_WAIT_L(0); PG8_BAR; PG8_MMA(0, 0, At, B0); PG8_MMA(0, 1, At, B1); PG8_BAR; PG8_SCHED;
.Lz408_1_join:
	s_setprio 0
	s_barrier
	s_add_i32 s38, 0, 0x18000
	v_add_u32_e32 v0, s38, v167
	s_add_i32 s39, 0, 0x1c000
	ds_read_b128 v[142:145], v0
	ds_read_b128 v[146:149], v0 offset:1024
	ds_read_b128 v[150:153], v0 offset:2048
	ds_read_b128 v[154:157], v0 offset:3072
	v_add_u32_e32 v0, s39, v167
	ds_read_b128 v[158:161], v0
	ds_read_b128 v[162:165], v0 offset:1024
	ds_read_b128 v[172:175], v0 offset:2048
	ds_read_b128 v[176:179], v0 offset:3072
	s_add_u32 s72, s72, 0x40000
	s_addc_u32 s73, s73, 0
	s_mov_b32 m0, s78
	v_lshl_add_u64 v[226:227], s[72:73], 0, v[136:137]
	ds_read_b128 v[180:183], v170 offset:32768
	ds_read_b128 v[184:187], v170 offset:33792
	ds_read_b128 v[188:191], v170 offset:34816
	ds_read_b128 v[192:195], v170 offset:35840
	ds_read_b128 v[202:205], v170 offset:36864
	ds_read_b128 v[206:209], v170 offset:37888
	ds_read_b128 v[210:213], v170 offset:38912
	ds_read_b128 v[214:217], v170 offset:39936
	global_load_lds_dwordx4 v[226:227], off
	v_lshl_add_u64 v[226:227], s[72:73], 0, v[132:133]
	s_mov_b32 m0, s79
	s_nop 0
	global_load_lds_dwordx4 v[226:227], off
	s_waitcnt vmcnt(8)
	s_waitcnt lgkmcnt(0)
	s_barrier
	s_setprio 1
	v_mfma_f32_16x16x32_bf16 v[122:125], v[142:145], v[180:183], v[122:125]
	v_mfma_f32_16x16x32_bf16 v[122:125], v[146:149], v[184:187], v[122:125]
	v_mfma_f32_16x16x32_bf16 v[106:109], v[142:145], v[188:191], v[106:109]
	v_mfma_f32_16x16x32_bf16 v[106:109], v[146:149], v[192:195], v[106:109]
	v_mfma_f32_16x16x32_bf16 v[90:93], v[142:145], v[202:205], v[90:93]
	v_mfma_f32_16x16x32_bf16 v[90:93], v[146:149], v[206:209], v[90:93]
	v_mfma_f32_16x16x32_bf16 v[74:77], v[142:145], v[210:213], v[74:77]
	v_mfma_f32_16x16x32_bf16 v[74:77], v[146:149], v[214:217], v[74:77]
	v_mfma_f32_16x16x32_bf16 v[126:129], v[150:153], v[180:183], v[126:129]
	v_mfma_f32_16x16x32_bf16 v[126:129], v[154:157], v[184:187], v[126:129]
	v_mfma_f32_16x16x32_bf16 v[110:113], v[150:153], v[188:191], v[110:113]
	v_mfma_f32_16x16x32_bf16 v[110:113], v[154:157], v[192:195], v[110:113]
	v_mfma_f32_16x16x32_bf16 v[94:97], v[150:153], v[202:205], v[94:97]
	v_mfma_f32_16x16x32_bf16 v[94:97], v[154:157], v[206:209], v[94:97]
	v_mfma_f32_16x16x32_bf16 v[78:81], v[150:153], v[210:213], v[78:81]
	v_mfma_f32_16x16x32_bf16 v[78:81], v[154:157], v[214:217], v[78:81]
	v_mfma_f32_16x16x32_bf16 v[114:117], v[158:161], v[180:183], v[114:117]
	v_mfma_f32_16x16x32_bf16 v[114:117], v[162:165], v[184:187], v[114:117]
	v_mfma_f32_16x16x32_bf16 v[98:101], v[158:161], v[188:191], v[98:101]
	v_mfma_f32_16x16x32_bf16 v[98:101], v[162:165], v[192:195], v[98:101]
	v_mfma_f32_16x16x32_bf16 v[82:85], v[158:161], v[202:205], v[82:85]
	v_mfma_f32_16x16x32_bf16 v[82:85], v[162:165], v[206:209], v[82:85]
	v_mfma_f32_16x16x32_bf16 v[66:69], v[158:161], v[210:213], v[66:69]
	v_mfma_f32_16x16x32_bf16 v[66:69], v[162:165], v[214:217], v[66:69]
	v_mfma_f32_16x16x32_bf16 v[118:121], v[172:175], v[180:183], v[118:121]
	v_mfma_f32_16x16x32_bf16 v[118:121], v[176:179], v[184:187], v[118:121]
	v_mfma_f32_16x16x32_bf16 v[102:105], v[172:175], v[188:191], v[102:105]
	v_mfma_f32_16x16x32_bf16 v[102:105], v[176:179], v[192:195], v[102:105]
	v_mfma_f32_16x16x32_bf16 v[86:89], v[172:175], v[202:205], v[86:89]
	v_mfma_f32_16x16x32_bf16 v[86:89], v[176:179], v[206:209], v[86:89]
	v_mfma_f32_16x16x32_bf16 v[70:73], v[172:175], v[210:213], v[70:73]
	v_mfma_f32_16x16x32_bf16 v[70:73], v[176:179], v[214:217], v[70:73]
	s_setprio 0
	s_barrier
; #define PG8_STAGE(bufoff, gbase, voff) do { _Pragma("unroll") for (int _i = 0; _i < 2; ++_i) \
;         __builtin_amdgcn_global_load_lds((const unsigned*)((const char*)(gbase) + (voff)[_i]), (PG8_LAS unsigned*)(lds + (bufoff) + ldsw + _i * 8192), 16, 0, 0); } while (0)
; #define PG8_LDA(dst, b, h) do { _Pragma("unroll") for (int m = 0; m < 4; ++m) _Pragma("unroll") for (int k = 0; k < 2; ++k) dst[m][k] = *(const PG8_LAS bf16x8*)(lds + PG8_SA(b, h) + aoff + m * 2048 + k * 1024); } while (0)
; #define PG8_MMA(ai, bj, At, Bt) do { __builtin_amdgcn_s_setprio(1); _Pragma("unroll") for (int m = 0; m < 4; ++m) _Pragma("unroll") for (int n = 0; n < 2; ++n) _Pragma("unroll") for (int k = 0; k < 2; ++k) \
;         acc[ai][bj][m][n] = __builtin_amdgcn_mfma_f32_16x16x32_bf16(Bt[n][k], At[m][k], acc[ai][bj][m][n], 0, 0, 0); __builtin_amdgcn_s_setprio(0); } while (0)
; #define PG8_WAIT_V(n) asm volatile("s_waitcnt vmcnt(" #n ")" ::: "memory")
; #define PG8_WAIT_L(n) asm volatile("s_waitcnt lgkmcnt(" #n ")" ::: "memory")
; #define PG8_BAR __builtin_amdgcn_s_barrier()
; #define PG8_SCHED __builtin_amdgcn_sched_barrier(0)
; template <class Epi, class Sched, bool ALIGN_EPI = false, bool SP2 = false>
; __device__ __forceinline__ void gemm_phase(PG8_LAS unsigned char* lds, const Gemm g, const Sched& S, const Epi& E) {
;     ...
;         for (int t = 0; t < nt; t += 2) {
;             const bool last = (t == nt - 2);
;     ...
;             PG8_LDA(At, 1, 1); PG8_STAGE(PG8_SB(1, 0), b3, voffB); PG8_STAGE(PG8_SB(1, 1), b3 + hstep, voffB); PG8_STAGE(PG8_SA(1, 0), a3, voffA);
;             PG8_WAIT_V(8); PG8_WAIT_L(0); PG8_BAR; PG8_MMA(1, 0, At, B0); PG8_MMA(1, 1, At, B1); PG8_BAR; PG8_SCHED;
	s_add_i32 s38, s38, s75
	v_lshl_add_u64 v[218:219], v[218:219], 0, s[30:31]
	s_mov_b32 m0, s38
	ds_read_b128 v[180:183], v170 offset:49152
	ds_read_b128 v[184:187], v170 offset:50176
	ds_read_b128 v[188:191], v170 offset:51200
	ds_read_b128 v[192:195], v170 offset:52224
	ds_read_b128 v[202:205], v170 offset:53248
	ds_read_b128 v[206:209], v170 offset:54272
	ds_read_b128 v[210:213], v170 offset:55296
	ds_read_b128 v[214:217], v170 offset:56320
	global_load_lds_dwordx4 v[218:219], off
	s_add_i32 m0, s38, 0x2000
	s_add_u32 s46, s46, 0x40080
	v_lshl_add_u64 v[218:219], v[220:221], 0, s[30:31]
	s_addc_u32 s47, s47, 0
	s_add_i32 s38, s39, s75
	global_load_lds_dwordx4 v[218:219], off
	v_lshl_add_u64 v[218:219], s[46:47], 0, v[134:135]
	s_mov_b32 m0, s38
	s_nop 0
	global_load_lds_dwordx4 v[218:219], off
	v_lshl_add_u64 v[218:219], s[46:47], 0, v[130:131]
	s_add_i32 m0, s38, 0x2000
	s_nop 0
	global_load_lds_dwordx4 v[218:219], off
	v_lshl_add_u64 v[218:219], v[222:223], 0, s[30:31]
	s_mov_b32 m0, s80
	s_nop 0
	global_load_lds_dwordx4 v[218:219], off
	v_lshl_add_u64 v[218:219], v[224:225], 0, s[30:31]
	s_mov_b32 m0, s81
	s_nop 0
	global_load_lds_dwordx4 v[218:219], off
	s_waitcnt vmcnt(8)
	s_waitcnt lgkmcnt(0)
	s_barrier
	s_setprio 1
	v_mfma_f32_16x16x32_bf16 v[58:61], v[142:145], v[180:183], v[58:61]
	v_mfma_f32_16x16x32_bf16 v[58:61], v[146:149], v[184:187], v[58:61]
	v_mfma_f32_16x16x32_bf16 v[42:45], v[142:145], v[188:191], v[42:45]
	v_mfma_f32_16x16x32_bf16 v[42:45], v[146:149], v[192:195], v[42:45]
	v_mfma_f32_16x16x32_bf16 v[26:29], v[142:145], v[202:205], v[26:29]
	v_mfma_f32_16x16x32_bf16 v[26:29], v[146:149], v[206:209], v[26:29]
	v_mfma_f32_16x16x32_bf16 v[10:13], v[142:145], v[210:213], v[10:13]
	v_mfma_f32_16x16x32_bf16 v[10:13], v[146:149], v[214:217], v[10:13]
	v_mfma_f32_16x16x32_bf16 v[62:65], v[150:153], v[180:183], v[62:65]
	v_mfma_f32_16x16x32_bf16 v[62:65], v[154:157], v[184:187], v[62:65]
	v_mfma_f32_16x16x32_bf16 v[46:49], v[150:153], v[188:191], v[46:49]
	v_mfma_f32_16x16x32_bf16 v[46:49], v[154:157], v[192:195], v[46:49]
	v_mfma_f32_16x16x32_bf16 v[30:33], v[150:153], v[202:205], v[30:33]
	v_mfma_f32_16x16x32_bf16 v[30:33], v[154:157], v[206:209], v[30:33]
	v_mfma_f32_16x16x32_bf16 v[14:17], v[150:153], v[210:213], v[14:17]
	v_mfma_f32_16x16x32_bf16 v[14:17], v[154:157], v[214:217], v[14:17]
	v_mfma_f32_16x16x32_bf16 v[50:53], v[158:161], v[180:183], v[50:53]
	v_mfma_f32_16x16x32_bf16 v[50:53], v[162:165], v[184:187], v[50:53]
	v_mfma_f32_16x16x32_bf16 v[34:37], v[158:161], v[188:191], v[34:37]
	v_mfma_f32_16x16x32_bf16 v[34:37], v[162:165], v[192:195], v[34:37]
	v_mfma_f32_16x16x32_bf16 v[18:21], v[158:161], v[202:205], v[18:21]
	v_mfma_f32_16x16x32_bf16 v[18:21], v[162:165], v[206:209], v[18:21]
	v_mfma_f32_16x16x32_bf16 v[2:5], v[158:161], v[210:213], v[2:5]
	v_mfma_f32_16x16x32_bf16 v[2:5], v[162:165], v[214:217], v[2:5]
	v_mfma_f32_16x16x32_bf16 v[54:57], v[172:175], v[180:183], v[54:57]
	v_mfma_f32_16x16x32_bf16 v[54:57], v[176:179], v[184:187], v[54:57]
	v_mfma_f32_16x16x32_bf16 v[38:41], v[172:175], v[188:191], v[38:41]
	v_mfma_f32_16x16x32_bf16 v[38:41], v[176:179], v[192:195], v[38:41]
	v_mfma_f32_16x16x32_bf16 v[22:25], v[172:175], v[202:205], v[22:25]
	v_mfma_f32_16x16x32_bf16 v[22:25], v[176:179], v[206:209], v[22:25]
	v_mfma_f32_16x16x32_bf16 v[6:9], v[172:175], v[210:213], v[6:9]
	v_mfma_f32_16x16x32_bf16 v[6:9], v[176:179], v[214:217], v[6:9]
	s_setprio 0
	s_barrier
	s_add_i32 s84, s84, 2
	s_add_u32 s48, s48, 0x100
	s_addc_u32 s49, s49, 0
	s_add_u32 s53, s53, 0x100
	s_addc_u32 s69, s69, 0
	s_cmp_gt_u32 s84, 13
	s_cbranch_scc0 .LBB0_408
	s_and_b64 vcc, exec, s[64:65]
	s_cbranch_vccz .LBB0_411
	s_barrier

; #define PG8_BAR __builtin_amdgcn_s_barrier()
; template <class Epi, class Sched, bool ALIGN_EPI = false, bool SP2 = false>
; __device__ __forceinline__ void gemm_phase(PG8_LAS unsigned char* lds, const Gemm g, const Sched& S, const Epi& E) {
;     ...
;         if (!has_next) break;
; #pragma unroll
;         for (int a = 0; a < 2; ++a)
; #pragma unroll
;             for (int b = 0; b < 2; ++b)
; #pragma unroll
;                 for (int m = 0; m < 4; ++m)
; #pragma unroll
;                     for (int n = 0; n < 2; ++n) { unsigned long long lo_, hi_; asm volatile("v_mov_b64 %0, 0\n\tv_mov_b64 %1, 0" : "=v"(lo_), "=v"(hi_)); acc[a][b][m][n] = __builtin_bit_cast(f32x4, (u64x2_t){lo_, hi_}); }
;         cur = nxt; cA = nA; cB = nB; ++ui;
;         if constexpr (ALIGN_EPI) { if (wr == 1) PG8_BAR; }
.LBB0_487:
	s_andn2_b64 vcc, exec, s[44:45]
	s_mov_b64 s[44:45], -1
	s_cbranch_vccnz .LBB0_400
	s_andn2_b64 vcc, exec, s[8:9]
	s_waitcnt lgkmcnt(0)
	s_cbranch_vccnz .LBB0_399
	s_barrier
	s_branch .LBB0_399
